# conv phase: remap item->(segment,chunk) so each XCD handles vertically adjacent rows of one feature chunk concurrently (L2 sharing); plus in-place pk_mul->fma, gelu constant merge
# speedup vs baseline: 1.0256x; 1.0102x over previous
; __device__ __forceinline__ unsigned cvt_pk_bf16(float lo, float hi) { unsigned r; asm("v_cvt_pk_bf16_f32 %0, %1, %2" : "=v"(r) : "v"(lo), "v"(hi)); return r; }
; __device__ __forceinline__ void s5out_item(PRef p, int layer, int item, unsigned char* shm) {
;     ...
; #pragma unroll 4
;         for (int kk = 0; kk < 32; ++kk) {
;             const bf16x8 bfr = *(const bf16x8*)(ul + fr * S5_UP + kk * 64 + fq * 16);
;             const int sq = 2 * kk + (fq >> 1);
; #pragma unroll
;             for (int mi = 0; mi < 4; ++mi) { const bf16x8 af = *(const bf16x8*)(KT + (tb + mi - sq + 63) * 256 + fr * 16 + (fq & 1) * 8);
;                 acc[mi] = __builtin_amdgcn_mfma_f32_16x16x32_bf16(af, bfr, acc[mi], 0, 0, 0); } }
;         const int cidx = nt < 4 ? 4 + 16 * nt + fr : (fr & 3);
; #pragma unroll
;         for (int dir = 0; dir < 2; ++dir) {
;             const bf16_t* G = (const bf16_t*)(p.ws + O_S5G) + (size_t)(dir * 32 + g) * 1024 * 128;
;             const float* ST = (const float*)(p.ws + O_S5ST) + (size_t)((g * 2 + dir) * 4 + b) * 68 * 128 + (size_t)cidx * 128;
; #pragma unroll
;             for (int kk = 0; kk < 4; ++kk) {
;                 const f32x4 x0 = *(const f32x4*)(ST + kk * 32 + fq * 8), x1 = *(const f32x4*)(ST + kk * 32 + fq * 8 + 4);
;                 u32x4 w; w.x = cvt_pk_bf16(x0[0], x0[1]); w.y = cvt_pk_bf16(x0[2], x0[3]); w.z = cvt_pk_bf16(x1[0], x1[1]); w.w = cvt_pk_bf16(x1[2], x1[3]);
;                 const bf16x8 bfr = mk8(w);
; #pragma unroll
;                 for (int mi = 0; mi < 4; ++mi) { const bf16x8 af = *(const bf16x8*)(G + (size_t)((tb + mi) * 16 + fr) * 128 + kk * 32 + fq * 8);
;                     acc[mi] = __builtin_amdgcn_mfma_f32_16x16x32_bf16(af, bfr, acc[mi], 0, 0, 0); } } }
.LBB0_417:
	v_add_u32_e32 v43, s50, v81
	ds_read_b128 v[44:47], v42
	ds_read_b128 v[90:93], v42 offset:64
	ds_read_b128 v[94:97], v43 offset:32256
	ds_read_b128 v[98:101], v43 offset:32768
	ds_read_b128 v[102:105], v43 offset:31744
	ds_read_b128 v[106:109], v43 offset:33280
	s_waitcnt lgkmcnt(3)
	v_mfma_f32_16x16x32_bf16 v[16:19], v[94:97], v[44:47], v[16:19]
	s_addk_i32 s50, 0xf000
	s_cmpk_eq_i32 s50, 0x8000
	s_waitcnt lgkmcnt(2)
	v_mfma_f32_16x16x32_bf16 v[12:15], v[98:101], v[44:47], v[12:15]
	s_waitcnt lgkmcnt(0)
	v_mfma_f32_16x16x32_bf16 v[8:11], v[106:109], v[44:47], v[8:11]
	ds_read_b128 v[106:109], v43 offset:33792
	ds_read_b128 v[110:113], v43 offset:29184
	s_waitcnt lgkmcnt(1)
	v_mfma_f32_16x16x32_bf16 v[4:7], v[106:109], v[44:47], v[4:7]
	ds_read_b128 v[44:47], v43 offset:31232
	ds_read_b128 v[106:109], v43 offset:30720
	s_waitcnt lgkmcnt(1)
	v_mfma_f32_16x16x32_bf16 v[16:19], v[44:47], v[90:93], v[16:19]
	v_mfma_f32_16x16x32_bf16 v[12:15], v[102:105], v[90:93], v[12:15]
	v_mfma_f32_16x16x32_bf16 v[8:11], v[94:97], v[90:93], v[8:11]
	ds_read_b128 v[94:97], v42 offset:128
	ds_read_b128 v[114:117], v42 offset:192
	v_add_u32_e32 v42, 0x100, v42
	v_mfma_f32_16x16x32_bf16 v[4:7], v[98:101], v[90:93], v[4:7]
	ds_read_b128 v[90:93], v43 offset:30208
	ds_read_b128 v[98:101], v43 offset:29696
	s_waitcnt lgkmcnt(1)
	v_mfma_f32_16x16x32_bf16 v[16:19], v[90:93], v[94:97], v[16:19]
	v_mfma_f32_16x16x32_bf16 v[12:15], v[106:109], v[94:97], v[12:15]
	v_mfma_f32_16x16x32_bf16 v[8:11], v[44:47], v[94:97], v[8:11]
	v_mfma_f32_16x16x32_bf16 v[4:7], v[102:105], v[94:97], v[4:7]
	v_mfma_f32_16x16x32_bf16 v[16:19], v[110:113], v[114:117], v[16:19]
	s_waitcnt lgkmcnt(0)
	v_mfma_f32_16x16x32_bf16 v[12:15], v[98:101], v[114:117], v[12:15]
	v_mfma_f32_16x16x32_bf16 v[8:11], v[90:93], v[114:117], v[8:11]
	v_mfma_f32_16x16x32_bf16 v[4:7], v[106:109], v[114:117], v[4:7]
	s_cbranch_scc0 .LBB0_417
	v_lshl_add_u32 v42, s22, 4, v73
	v_cndmask_b32_e64 v42, v74, v42, s[4:5]
	v_mov_b32_e32 v43, v33
	v_lshlrev_b64 v[42:43], 9, v[42:43]
	v_lshl_add_u64 v[130:131], v[20:21], 0, v[42:43]
	v_lshl_add_u64 v[132:133], v[130:131], 0, s[46:47]
	global_load_dwordx4 v[42:45], v[24:25], off
	global_load_dwordx4 v[46:49], v[132:133], off
	global_load_dwordx4 v[90:93], v[132:133], off offset:16
	global_load_dwordx4 v[94:97], v[26:27], off
	global_load_dwordx4 v[98:101], v[28:29], off
	global_load_dwordx4 v[102:105], v[30:31], off
	global_load_dwordx4 v[106:109], v[132:133], off offset:128
	global_load_dwordx4 v[110:113], v[24:25], off offset:64
	global_load_dwordx4 v[114:117], v[132:133], off offset:144
	global_load_dwordx4 v[118:121], v[26:27], off offset:64
	s_or_b64 s[68:69], s[4:5], s[2:3]
	s_waitcnt vmcnt(8)
	v_cvt_pk_bf16_f32 v46, v46, v47
	v_cvt_pk_bf16_f32 v47, v48, v49
	s_waitcnt vmcnt(7)
	v_cvt_pk_bf16_f32 v48, v90, v91
	v_cvt_pk_bf16_f32 v49, v92, v93
	s_waitcnt vmcnt(3)
	v_cvt_pk_bf16_f32 v106, v106, v107
	v_mfma_f32_16x16x32_bf16 v[16:19], v[42:45], v[46:49], v[16:19]
	global_load_dwordx4 v[42:45], v[28:29], off offset:64
	v_cvt_pk_bf16_f32 v107, v108, v109
	s_waitcnt vmcnt(2)
	v_cvt_pk_bf16_f32 v108, v114, v115
	v_mfma_f32_16x16x32_bf16 v[12:15], v[94:97], v[46:49], v[12:15]
	global_load_dwordx4 v[90:93], v[30:31], off offset:64
	global_load_dwordx4 v[94:97], v[132:133], off offset:256
	global_load_dwordx4 v[122:125], v[24:25], off offset:128
	v_cvt_pk_bf16_f32 v109, v116, v117
	s_waitcnt vmcnt(1)
	v_cvt_pk_bf16_f32 v94, v94, v95
	v_mfma_f32_16x16x32_bf16 v[8:11], v[98:101], v[46:49], v[8:11]
	global_load_dwordx4 v[98:101], v[132:133], off offset:272
	global_load_dwordx4 v[126:129], v[26:27], off offset:128
	v_cvt_pk_bf16_f32 v95, v96, v97
	s_waitcnt vmcnt(1)
	v_cvt_pk_bf16_f32 v96, v98, v99
	v_mfma_f32_16x16x32_bf16 v[4:7], v[102:105], v[46:49], v[4:7]
	global_load_dwordx4 v[46:49], v[28:29], off offset:128
	v_cvt_pk_bf16_f32 v97, v100, v101
	v_mfma_f32_16x16x32_bf16 v[16:19], v[110:113], v[106:109], v[16:19]
	global_load_dwordx4 v[102:105], v[30:31], off offset:128
	global_load_dwordx4 v[110:113], v[132:133], off offset:400
	global_load_dwordx4 v[114:117], v[132:133], off offset:384
	s_waitcnt vmcnt(0)
	v_cvt_pk_bf16_f32 v114, v114, v115
	v_mfma_f32_16x16x32_bf16 v[12:15], v[118:121], v[106:109], v[12:15]
	v_cvt_pk_bf16_f32 v115, v116, v117
	v_cvt_pk_bf16_f32 v116, v110, v111
	v_cvt_pk_bf16_f32 v117, v112, v113
	v_mfma_f32_16x16x32_bf16 v[8:11], v[42:45], v[106:109], v[8:11]
	global_load_dwordx4 v[42:45], v[24:25], off offset:192
	global_load_dwordx4 v[118:121], v[26:27], off offset:192
	v_mfma_f32_16x16x32_bf16 v[4:7], v[90:93], v[106:109], v[4:7]
	global_load_dwordx4 v[90:93], v[28:29], off offset:192
	global_load_dwordx4 v[98:101], v[30:31], off offset:192
	v_mfma_f32_16x16x32_bf16 v[12:15], v[126:129], v[94:97], v[12:15]
	v_lshl_add_u64 v[126:127], v[130:131], 0, s[48:49]
	v_mfma_f32_16x16x32_bf16 v[16:19], v[122:125], v[94:97], v[16:19]
	global_load_dwordx4 v[106:109], v[126:127], off
	global_load_dwordx4 v[122:125], v[34:35], off
	s_waitcnt vmcnt(1)
	v_cvt_pk_bf16_f32 v106, v106, v107
	v_mfma_f32_16x16x32_bf16 v[8:11], v[46:49], v[94:97], v[8:11]
	global_load_dwordx4 v[46:49], v[126:127], off offset:16
	v_cvt_pk_bf16_f32 v107, v108, v109
	v_mfma_f32_16x16x32_bf16 v[16:19], v[42:45], v[114:117], v[16:19]
	global_load_dwordx4 v[42:45], v[36:37], off
	s_waitcnt vmcnt(1)
; __device__ __forceinline__ unsigned cvt_pk_bf16(float lo, float hi) { unsigned r; asm("v_cvt_pk_bf16_f32 %0, %1, %2" : "=v"(r) : "v"(lo), "v"(hi)); return r; }
; __device__ __forceinline__ void s5out_item(PRef p, int layer, int item, unsigned char* shm) {
;     ...
;         for (int dir = 0; dir < 2; ++dir) {
;             const bf16_t* G = (const bf16_t*)(p.ws + O_S5G) + (size_t)(dir * 32 + g) * 1024 * 128;
;             const float* ST = (const float*)(p.ws + O_S5ST) + (size_t)((g * 2 + dir) * 4 + b) * 68 * 128 + (size_t)cidx * 128;
; #pragma unroll
;             for (int kk = 0; kk < 4; ++kk) {
;                 const f32x4 x0 = *(const f32x4*)(ST + kk * 32 + fq * 8), x1 = *(const f32x4*)(ST + kk * 32 + fq * 8 + 4);
;                 u32x4 w; w.x = cvt_pk_bf16(x0[0], x0[1]); w.y = cvt_pk_bf16(x0[2], x0[3]); w.z = cvt_pk_bf16(x1[0], x1[1]); w.w = cvt_pk_bf16(x1[2], x1[3]);
;                 const bf16x8 bfr = mk8(w);
; #pragma unroll
;                 for (int mi = 0; mi < 4; ++mi) { const bf16x8 af = *(const bf16x8*)(G + (size_t)((tb + mi) * 16 + fr) * 128 + kk * 32 + fq * 8);
;                     acc[mi] = __builtin_amdgcn_mfma_f32_16x16x32_bf16(af, bfr, acc[mi], 0, 0, 0); } } }
;         if (nt < 4 || fr < 4) {
	v_cvt_pk_bf16_f32 v108, v46, v47
	v_cvt_pk_bf16_f32 v109, v48, v49
	v_mfma_f32_16x16x32_bf16 v[4:7], v[102:105], v[94:97], v[4:7]
	global_load_dwordx4 v[94:97], v[38:39], off
	global_load_dwordx4 v[102:105], v[40:41], off
	global_load_dwordx4 v[110:113], v[34:35], off offset:64
	v_mfma_f32_16x16x32_bf16 v[12:15], v[118:121], v[114:117], v[12:15]
	v_mfma_f32_16x16x32_bf16 v[8:11], v[90:93], v[114:117], v[8:11]
	global_load_dwordx4 v[90:93], v[126:127], off offset:144
	global_load_dwordx4 v[118:121], v[126:127], off offset:128
	global_load_dwordx4 v[46:49], v[36:37], off offset:64
	s_waitcnt vmcnt(1)
	v_cvt_pk_bf16_f32 v118, v118, v119
	v_mfma_f32_16x16x32_bf16 v[4:7], v[98:101], v[114:117], v[4:7]
	v_cvt_pk_bf16_f32 v119, v120, v121
	v_cvt_pk_bf16_f32 v120, v90, v91
	v_cvt_pk_bf16_f32 v121, v92, v93
	v_mfma_f32_16x16x32_bf16 v[16:19], v[122:125], v[106:109], v[16:19]
	v_mfma_f32_16x16x32_bf16 v[12:15], v[42:45], v[106:109], v[12:15]
	global_load_dwordx4 v[42:45], v[38:39], off offset:64
	global_load_dwordx4 v[98:101], v[40:41], off offset:64
	global_load_dwordx4 v[114:117], v[34:35], off offset:128
	v_mfma_f32_16x16x32_bf16 v[8:11], v[94:97], v[106:109], v[8:11]
	global_load_dwordx4 v[94:97], v[126:127], off offset:272
	global_load_dwordx4 v[122:125], v[126:127], off offset:256
	global_load_dwordx4 v[90:93], v[36:37], off offset:128
	s_waitcnt vmcnt(1)
	v_cvt_pk_bf16_f32 v122, v122, v123
	v_mfma_f32_16x16x32_bf16 v[4:7], v[102:105], v[106:109], v[4:7]
	v_cvt_pk_bf16_f32 v123, v124, v125
	v_cvt_pk_bf16_f32 v124, v94, v95
	v_cvt_pk_bf16_f32 v125, v96, v97
	v_mfma_f32_16x16x32_bf16 v[12:15], v[46:49], v[118:121], v[12:15]
	global_load_dwordx4 v[46:49], v[38:39], off offset:128
	global_load_dwordx4 v[102:105], v[40:41], off offset:128
	global_load_dwordx4 v[106:109], v[34:35], off offset:192
	v_mfma_f32_16x16x32_bf16 v[8:11], v[42:45], v[118:121], v[8:11]
	v_mfma_f32_16x16x32_bf16 v[16:19], v[110:113], v[118:121], v[16:19]
	global_load_dwordx4 v[42:45], v[126:127], off offset:400
	global_load_dwordx4 v[110:113], v[126:127], off offset:384
	global_load_dwordx4 v[94:97], v[36:37], off offset:192
	s_waitcnt vmcnt(6)
	v_mfma_f32_16x16x32_bf16 v[12:15], v[90:93], v[122:125], v[12:15]
	global_load_dwordx4 v[90:93], v[38:39], off offset:192
	s_waitcnt vmcnt(6)
	v_mfma_f32_16x16x32_bf16 v[8:11], v[46:49], v[122:125], v[8:11]
	global_load_dwordx4 v[46:49], v[40:41], off offset:192
	v_mfma_f32_16x16x32_bf16 v[4:7], v[98:101], v[118:121], v[4:7]
	s_waitcnt vmcnt(3)
	v_cvt_pk_bf16_f32 v98, v110, v111
	v_mfma_f32_16x16x32_bf16 v[16:19], v[114:117], v[122:125], v[16:19]
	v_cvt_pk_bf16_f32 v99, v112, v113
	v_cvt_pk_bf16_f32 v100, v42, v43
	v_cvt_pk_bf16_f32 v101, v44, v45
	v_mfma_f32_16x16x32_bf16 v[4:7], v[102:105], v[122:125], v[4:7]
	v_mfma_f32_16x16x32_bf16 v[16:19], v[106:109], v[98:101], v[16:19]
	s_waitcnt vmcnt(2)
	v_mfma_f32_16x16x32_bf16 v[12:15], v[94:97], v[98:101], v[12:15]
	s_waitcnt vmcnt(1)
	v_mfma_f32_16x16x32_bf16 v[8:11], v[90:93], v[98:101], v[8:11]
	s_waitcnt vmcnt(0)
	v_mfma_f32_16x16x32_bf16 v[4:7], v[46:49], v[98:101], v[4:7]
	s_and_saveexec_b64 s[50:51], s[68:69]
	s_cbranch_execz .LBB0_415
; __device__ __forceinline__ unsigned cvt_pk_bf16(float lo, float hi) { unsigned r; asm("v_cvt_pk_bf16_f32 %0, %1, %2" : "=v"(r) : "v"(lo), "v"(hi)); return r; }
; __device__ __forceinline__ float bflo(unsigned w) { return __uint_as_float(w << 16); }
; __device__ __forceinline__ float bfhi(unsigned w) { return __uint_as_float(w & 0xffff0000u); }
; __device__ __forceinline__ float gelu_tanh(float x) { const float u = 0.7978845608028654f * (x + 0.044715f * x * x * x); return x / (1.f + __expf(-2.f * u)); }
; __device__ __forceinline__ void s5out_item(PRef p, int layer, int item, unsigned char* shm) {
;     ...
;         if (nt < 4 || fr < 4) {
; #pragma unroll
;             for (int mi = 0; mi < 4; ++mi) { const int t = tb + mi; const size_t row = nt < 4 ? (size_t)(b * 4096 + (16 * nt + fr) * 64 + t) : (size_t)(RL + b * 256 + fr * 64 + t);
;                 const u32x2 uu = *(const u32x2*)(ul + fr * S5_UP + t * 32 + fq * 8);
;                 const f32x4 y = acc[mi];
;                 u32x2 w; w.x = cvt_pk_bf16(gelu_tanh(y[0] + dv[0] * bflo(uu.x)), gelu_tanh(y[1] + dv[1] * bfhi(uu.x)));
;                 w.y = cvt_pk_bf16(gelu_tanh(y[2] + dv[2] * bflo(uu.y)), gelu_tanh(y[3] + dv[3] * bfhi(uu.y)));
;                 *(u32x2*)(Z + row * 512 + g * 16 + fq * 4) = w; } }
	ds_read_b64 v[42:43], v86 offset:65024
	ds_read_b64 v[44:45], v87 offset:65024
	ds_read_b64 v[48:49], v88 offset:65024
	ds_read_b64 v[46:47], v89 offset:65024
	s_waitcnt lgkmcnt(3)
	v_lshlrev_b32_e32 v90, 16, v42
	v_fma_f32 v16, v0, v90, v16
	v_mul_f32_e32 v90, 0x3d372713, v16
	v_mul_f32_e32 v90, v16, v90
	v_fma_f32 v90, v16, v90, v16
	v_mul_f32_e32 v90, 0xc0135761, v90
	v_exp_f32_e32 v91, v90
	v_add_u32_e32 v90, s12, v76
	v_cndmask_b32_e64 v92, v75, v90, s[4:5]
	v_and_b32_e32 v42, 0xffff0000, v42
	v_add_f32_e32 v93, 1.0, v91
	v_rcp_f32_e32 v95, v93
	v_fma_f32 v17, v1, v42, v17
	v_mul_f32_e32 v42, 0x3d372713, v17
	v_mul_f32_e32 v42, v17, v42
	v_fma_f32 v42, v17, v42, v17
	v_mul_f32_e32 v42, 0xc0135761, v42
	v_exp_f32_e32 v42, v42
	v_mul_f32_e32 v94, v16, v95
	v_lshlrev_b32_e32 v95, 16, v43
	v_fma_f32 v18, v2, v95, v18
	v_add_f32_e32 v42, 1.0, v42
	v_mul_f32_e32 v95, 0x3d372713, v18
	v_mul_f32_e32 v95, v18, v95
	v_rcp_f32_e32 v98, v42
	v_fma_f32 v95, v18, v95, v18
	v_mul_f32_e32 v95, 0xc0135761, v95
	v_mov_b32_e32 v16, v94
	v_exp_f32_e32 v95, v95
	v_and_b32_e32 v43, 0xffff0000, v43
	v_fmac_f32_e32 v19, v3, v43
	v_mul_f32_e32 v43, 0x3d372713, v19
	v_add_f32_e32 v95, 1.0, v95
	v_mul_f32_e32 v43, v19, v43
	v_fma_f32 v43, v19, v43, v19
	v_rcp_f32_e32 v97, v95
	v_mul_f32_e32 v43, 0xc0135761, v43
	v_mul_f32_e32 v17, v17, v98
	v_exp_f32_e32 v43, v43
	v_cvt_pk_bf16_f32 v16, v16, v17
	v_add_f32_e32 v43, 1.0, v43
	v_rcp_f32_e32 v94, v43
	v_mul_f32_e32 v17, v18, v97
	v_mul_f32_e32 v18, v19, v94
	s_waitcnt lgkmcnt(2)
	v_lshlrev_b32_e32 v19, 16, v44
	v_fma_f32 v12, v0, v19, v12
	v_mul_f32_e32 v19, 0x3d372713, v12
	v_mul_f32_e32 v19, v12, v19
	v_fma_f32 v19, v12, v19, v12
	v_mul_f32_e32 v19, 0xc0135761, v19
	v_exp_f32_e32 v42, v19
	v_and_b32_e32 v44, 0xffff0000, v44
	v_add_u32_e32 v90, v92, v63
	v_fma_f32 v13, v1, v44, v13
	v_add_f32_e32 v42, 1.0, v42
	v_ashrrev_i32_e32 v91, 31, v90
	v_mul_f32_e32 v44, 0x3d372713, v13
	v_cvt_pk_bf16_f32 v17, v17, v18
	v_lshlrev_b64 v[18:19], 10, v[90:91]
	v_rcp_f32_e32 v90, v42
	v_mul_f32_e32 v44, v13, v44
	v_fma_f32 v44, v13, v44, v13
	v_mul_f32_e32 v44, 0xc0135761, v44
	v_lshl_add_u64 v[18:19], v[22:23], 0, v[18:19]
	global_store_dwordx2 v[18:19], v[16:17], off
	v_exp_f32_e32 v44, v44
	s_nop 0
	v_add_f32_e32 v43, 1.0, v44
	v_rcp_f32_e32 v91, v43
	v_mul_f32_e32 v12, v12, v90
	v_lshlrev_b32_e32 v42, 16, v45
	v_fma_f32 v14, v2, v42, v14
	v_mul_f32_e32 v42, 0x3d372713, v14
	v_mul_f32_e32 v42, v14, v42
	v_fma_f32 v42, v14, v42, v14
	v_mul_f32_e32 v42, 0xc0135761, v42
	v_exp_f32_e32 v42, v42
	v_and_b32_e32 v19, 0xffff0000, v45
	v_fmac_f32_e32 v15, v3, v19
	v_mul_f32_e32 v19, 0x3d372713, v15
	v_add_f32_e32 v42, 1.0, v42
	v_mul_f32_e32 v19, v15, v19
	v_fma_f32 v19, v15, v19, v15
	v_rcp_f32_e32 v90, v42
	v_mul_f32_e32 v19, 0xc0135761, v19
	v_mul_f32_e32 v13, v13, v91
	v_exp_f32_e32 v19, v19
	v_cvt_pk_bf16_f32 v12, v12, v13
	v_add_f32_e32 v19, 1.0, v19
	v_rcp_f32_e32 v44, v19
	v_mul_f32_e32 v13, v14, v90
	v_add_u32_e32 v16, v92, v77
	v_mul_f32_e32 v14, v15, v44
	s_waitcnt lgkmcnt(1)
	v_lshlrev_b32_e32 v15, 16, v48
	v_fma_f32 v8, v0, v15, v8
	v_mul_f32_e32 v15, 0x3d372713, v8
	v_mul_f32_e32 v15, v8, v15
	v_fma_f32 v15, v8, v15, v8
	v_mul_f32_e32 v15, 0xc0135761, v15
	v_exp_f32_e32 v18, v15
	v_ashrrev_i32_e32 v17, 31, v16
	v_and_b32_e32 v19, 0xffff0000, v48
	v_cvt_pk_bf16_f32 v13, v13, v14
	v_lshlrev_b64 v[14:15], 10, v[16:17]
	v_add_f32_e32 v16, 1.0, v18
	v_fma_f32 v9, v1, v19, v9
	v_mul_f32_e32 v19, 0x3d372713, v9
	v_rcp_f32_e32 v18, v16
	v_mul_f32_e32 v19, v9, v19
	v_fma_f32 v19, v9, v19, v9
	v_mul_f32_e32 v19, 0xc0135761, v19
	v_lshl_add_u64 v[14:15], v[22:23], 0, v[14:15]
	global_store_dwordx2 v[14:15], v[12:13], off
	v_exp_f32_e32 v19, v19
	s_nop 0
	v_add_f32_e32 v17, 1.0, v19
	v_rcp_f32_e32 v42, v17
	v_mul_f32_e32 v8, v8, v18
	v_lshlrev_b32_e32 v16, 16, v49
	v_fma_f32 v10, v2, v16, v10
	v_mul_f32_e32 v16, 0x3d372713, v10
	v_mul_f32_e32 v16, v10, v16
	v_fma_f32 v16, v10, v16, v10
	v_mul_f32_e32 v16, 0xc0135761, v16
	v_exp_f32_e32 v16, v16
	v_and_b32_e32 v15, 0xffff0000, v49
	v_fmac_f32_e32 v11, v3, v15
	v_mul_f32_e32 v15, 0x3d372713, v11
	v_add_f32_e32 v16, 1.0, v16
	v_mul_f32_e32 v15, v11, v15
	v_fma_f32 v15, v11, v15, v11
	v_rcp_f32_e32 v19, v16
	v_mul_f32_e32 v15, 0xc0135761, v15
	v_mul_f32_e32 v9, v9, v42
	v_exp_f32_e32 v15, v15
	v_cvt_pk_bf16_f32 v8, v8, v9
	v_add_f32_e32 v15, 1.0, v15
	v_rcp_f32_e32 v18, v15
	v_mul_f32_e32 v9, v10, v19
	v_add_u32_e32 v12, v92, v78
	v_mul_f32_e32 v10, v11, v18
	s_waitcnt lgkmcnt(0)
	v_lshlrev_b32_e32 v11, 16, v46
	v_fma_f32 v4, v0, v11, v4
	v_mul_f32_e32 v11, 0x3d372713, v4
	v_mul_f32_e32 v11, v4, v11
	v_fma_f32 v11, v4, v11, v4
	v_mul_f32_e32 v11, 0xc0135761, v11
	v_exp_f32_e32 v14, v11
	v_ashrrev_i32_e32 v13, 31, v12
	v_and_b32_e32 v15, 0xffff0000, v46
	v_cvt_pk_bf16_f32 v9, v9, v10
	v_lshlrev_b64 v[10:11], 10, v[12:13]
	v_add_f32_e32 v12, 1.0, v14
	v_fma_f32 v5, v1, v15, v5
	v_mul_f32_e32 v15, 0x3d372713, v5
	v_rcp_f32_e32 v14, v12
	v_mul_f32_e32 v15, v5, v15
	v_fma_f32 v15, v5, v15, v5
	v_mul_f32_e32 v15, 0xc0135761, v15
	v_lshl_add_u64 v[10:11], v[22:23], 0, v[10:11]
	global_store_dwordx2 v[10:11], v[8:9], off
	v_exp_f32_e32 v15, v15
	s_nop 0
	v_add_f32_e32 v13, 1.0, v15
	v_rcp_f32_e32 v16, v13
	v_mul_f32_e32 v4, v4, v14
	v_lshlrev_b32_e32 v12, 16, v47
	v_fma_f32 v6, v2, v12, v6
	v_mul_f32_e32 v12, 0x3d372713, v6
	v_mul_f32_e32 v12, v6, v12
	v_fma_f32 v12, v6, v12, v6
	v_mul_f32_e32 v12, 0xc0135761, v12
	v_exp_f32_e32 v12, v12
	v_and_b32_e32 v11, 0xffff0000, v47
	v_fmac_f32_e32 v7, v3, v11
	v_mul_f32_e32 v11, 0x3d372713, v7
	v_add_f32_e32 v12, 1.0, v12
	v_mul_f32_e32 v11, v7, v11
	v_fma_f32 v11, v7, v11, v7
	v_rcp_f32_e32 v15, v12
	v_mul_f32_e32 v11, 0xc0135761, v11
	v_mul_f32_e32 v5, v5, v16
	v_exp_f32_e32 v11, v11
	v_cvt_pk_bf16_f32 v4, v4, v5
	v_add_f32_e32 v11, 1.0, v11
	v_rcp_f32_e32 v14, v11
	v_mul_f32_e32 v5, v6, v15
	v_add_u32_e32 v8, v92, v79
	v_ashrrev_i32_e32 v9, 31, v8
	v_mul_f32_e32 v6, v7, v14
	v_cvt_pk_bf16_f32 v5, v5, v6
	v_lshlrev_b64 v[6:7], 10, v[8:9]
	v_lshl_add_u64 v[6:7], v[22:23], 0, v[6:7]
	global_store_dwordx2 v[6:7], v[4:5], off
	s_branch .LBB0_415

; __device__ __forceinline__ void phase_conv(PRef p, int layer, int nseg) {
;     ...
;     for (int it = blockIdx.x; it < nseg * 11; it += gridDim.x) {
;         const int seg = it / 11, f = (it % 11) * 512 + fg * 8;
;         const bool isc = seg >= 256;
;         float w[9][8], bias[8];
; #pragma unroll
;         for (int k = 0; k < 9; ++k) { const float4 a = *(const float4*)(CW + (size_t)k * NFF + f), bq = *(const float4*)(CW + (size_t)k * NFF + f + 4);
;             w[k][0] = a.x; w[k][1] = a.y; w[k][2] = a.z; w[k][3] = a.w; w[k][4] = bq.x; w[k][5] = bq.y; w[k][6] = bq.z; w[k][7] = bq.w; }
;         { const float4 a = *(const float4*)(CB + f), bq = *(const float4*)(CB + f + 4); bias[0] = a.x; bias[1] = a.y; bias[2] = a.z; bias[3] = a.w; bias[4] = bq.x; bias[5] = bq.y; bias[6] = bq.z; bias[7] = bq.w; }
;         int W, x0; const bf16_t* lp[3]; bool lv[3];
;         if (!isc) { const int b = seg >> 6, r = seg & 63; W = 64; x0 = 8 * xs;
; #pragma unroll
;             for (int ky = 0; ky < 3; ++ky) { const int yy = r + ky - 1; lv[ky] = (yy >= 0) && (yy < 64); lp[ky] = GV + ((size_t)b * 4096 + (size_t)(lv[ky] ? yy : r) * 64) * NUP + f; } }
.LBB0_546:
	s_lshr_b32 s2, s29, 8
	s_lshl_b32 s2, s2, 5
	s_lshr_b32 s3, s84, 3
	s_add_i32 s3, s2, s3
	s_mul_i32 s2, s3, 0x788
	s_lshr_b32 s2, s2, 16
	s_mul_i32 s4, s2, 34
	s_sub_i32 s3, s3, s4
	s_and_b32 s4, s84, 7
	s_mul_i32 s4, s4, 34
	s_add_i32 s4, s4, s3
	v_lshl_or_b32 v80, s2, 9, v218
	v_ashrrev_i32_e32 v81, 31, v80
	v_lshlrev_b64 v[72:73], 2, v[80:81]
	v_lshl_add_u64 v[64:65], s[16:17], 0, v[72:73]
	v_add_co_u32_e32 v8, vcc, 0x5000, v64
	global_load_dwordx4 v[0:3], v[64:65], off offset:16
	global_load_dwordx4 v[4:7], v[64:65], off
	v_addc_co_u32_e32 v9, vcc, 0, v65, vcc
	v_add_co_u32_e32 v16, vcc, 0xb000, v64
	v_lshl_add_u64 v[12:13], v[64:65], 0, s[20:21]
	s_nop 0
	v_addc_co_u32_e32 v17, vcc, 0, v65, vcc
	v_add_co_u32_e32 v24, vcc, 0x10000, v64
	v_lshl_add_u64 v[20:21], v[64:65], 0, s[22:23]
	s_nop 0
	v_addc_co_u32_e32 v25, vcc, 0, v65, vcc
	v_add_co_u32_e32 v32, vcc, 0x16000, v64
	v_lshl_add_u64 v[28:29], v[64:65], 0, s[24:25]
	s_nop 0
	v_addc_co_u32_e32 v33, vcc, 0, v65, vcc
	v_add_co_u32_e32 v40, vcc, 0x1b000, v64
	v_lshl_add_u64 v[36:37], v[64:65], 0, s[26:27]
	s_nop 0
	v_addc_co_u32_e32 v41, vcc, 0, v65, vcc
	v_add_co_u32_e32 v48, vcc, 0x21000, v64
	v_lshl_add_u64 v[44:45], v[64:65], 0, s[42:43]
	s_nop 0
	v_addc_co_u32_e32 v49, vcc, 0, v65, vcc
	v_add_co_u32_e32 v56, vcc, 0x26000, v64
	v_lshl_add_u64 v[52:53], v[64:65], 0, s[44:45]
	s_nop 0
	v_addc_co_u32_e32 v57, vcc, 0, v65, vcc
	v_lshl_add_u64 v[60:61], v[64:65], 0, s[46:47]
	v_lshl_add_u64 v[68:69], v[64:65], 0, s[48:49]
	v_add_co_u32_e32 v64, vcc, 0x2c000, v64
	v_lshl_add_u64 v[76:77], s[18:19], 0, v[72:73]
	s_nop 0
	v_addc_co_u32_e32 v65, vcc, 0, v65, vcc
	global_load_dwordx4 v[8:11], v[8:9], off offset:2048
	s_nop 0
	global_load_dwordx4 v[12:15], v[12:13], off offset:16
	s_nop 0
	global_load_dwordx4 v[16:19], v[16:17], off
	s_nop 0
	global_load_dwordx4 v[20:23], v[20:21], off offset:16
	s_nop 0
	global_load_dwordx4 v[24:27], v[24:25], off offset:2048
	s_nop 0
	global_load_dwordx4 v[28:31], v[28:29], off offset:16
	s_nop 0
	global_load_dwordx4 v[32:35], v[32:33], off
	s_nop 0
	global_load_dwordx4 v[36:39], v[36:37], off offset:16
	s_nop 0
	global_load_dwordx4 v[40:43], v[40:41], off offset:2048
	s_nop 0
	global_load_dwordx4 v[44:47], v[44:45], off offset:16
	s_nop 0
	global_load_dwordx4 v[48:51], v[48:49], off
	s_nop 0
	global_load_dwordx4 v[52:55], v[52:53], off offset:16
	s_nop 0
	global_load_dwordx4 v[56:59], v[56:57], off offset:2048
	s_nop 0
	global_load_dwordx4 v[60:63], v[60:61], off offset:16
	s_nop 0
	global_load_dwordx4 v[64:67], v[64:65], off
	s_nop 0
	global_load_dwordx4 v[68:71], v[68:69], off offset:16
	s_nop 0
	global_load_dwordx4 v[72:75], v[76:77], off offset:16
	s_nop 0
	global_load_dwordx4 v[76:79], v[76:77], off
	s_cmpk_gt_i32 s4, 0xff
	s_mov_b64 s[2:3], -1
	s_cbranch_scc1 .LBB0_548
	s_ashr_i32 s2, s4, 6
	s_and_b32 s5, s4, 63
	s_ashr_i32 s3, s2, 31
	s_add_i32 s8, s5, -1
	s_lshl_b64 s[2:3], s[2:3], 12
	s_cmp_lt_u32 s8, 64
	s_cselect_b64 s[52:53], -1, 0
	s_and_b64 s[6:7], s[52:53], exec
	s_cselect_b32 s6, s8, s5
	s_ashr_i32 s7, s6, 31
	s_lshl_b64 s[6:7], s[6:7], 6
	s_add_u32 s6, s6, s2
	s_addc_u32 s7, s7, s3
	s_mulk_i32 s7, 0x5800
	s_mul_hi_u32 s8, s6, 0x5800
	s_add_i32 s8, s8, s7
	s_mulk_i32 s6, 0x5800
	s_add_u32 s6, s13, s6
	s_addc_u32 s7, s14, s8
	v_lshlrev_b64 v[82:83], 1, v[80:81]
	s_lshl_b32 s8, s5, 6
	v_lshl_add_u64 v[168:169], s[6:7], 0, v[82:83]
	s_or_b32 s6, s2, s8
	s_mul_i32 s7, s3, 0x5800
	s_mul_hi_u32 s9, s6, 0x5800
	s_add_i32 s9, s9, s7
	s_mulk_i32 s6, 0x5800
	s_add_u32 s6, s13, s6
	s_addc_u32 s7, s14, s9
	s_add_i32 s8, s8, 64
	s_cmp_lg_u32 s5, 63
	s_cselect_b64 s[54:55], -1, 0
	v_lshl_add_u64 v[170:171], s[6:7], 0, v[82:83]
	s_and_b64 s[6:7], s[54:55], exec
	s_cselect_b32 s5, s8, 0xfc0
	s_add_u32 s2, s2, s5
	s_addc_u32 s3, s3, 0
	s_mulk_i32 s3, 0x5800
	s_mul_hi_u32 s5, s2, 0x5800
	s_add_i32 s5, s5, s3
	s_mulk_i32 s2, 0x5800
	s_add_u32 s2, s13, s2
	s_addc_u32 s3, s14, s5
	v_lshl_add_u64 v[172:173], s[2:3], 0, v[82:83]
	s_mov_b64 s[2:3], 0

; __device__ __forceinline__ float bflo(unsigned w) { return __uint_as_float(w << 16); }
; __device__ __forceinline__ float bfhi(unsigned w) { return __uint_as_float(w & 0xffff0000u); }
; __device__ __forceinline__ void phase_conv(PRef p, int layer, int nseg) {
;     ...
;         for (int hx = 0; hx < 2; ++hx) { const int xb = x0 + 4 * hx;
;             u32x4 gc[3][6], vv[4];
; #pragma unroll
;             for (int ky = 0; ky < 3; ++ky)
; #pragma unroll
;                 for (int cx = 0; cx < 6; ++cx) { const int xx = xb - 1 + cx;
;                     gc[ky][cx] = (lv[ky] && xx >= 0 && xx < W) ? *(const u32x4*)(lp[ky] + (size_t)xx * NUP) : (u32x4){0u, 0u, 0u, 0u}; }
; #pragma unroll
;             for (int xi = 0; xi < 4; ++xi) vv[xi] = *(const u32x4*)(lp[1] + (size_t)(xb + xi) * NUP + NFF);
; #pragma unroll
;             for (int xi = 0; xi < 4; ++xi) {
;                 float acc[8];
; #pragma unroll
;                 for (int j = 0; j < 8; ++j) acc[j] = bias[j];
; #pragma unroll
;                 for (int ky = 0; ky < 3; ++ky)
; #pragma unroll
;                     for (int kx = 0; kx < 3; ++kx) { const u32x4 gq = gc[ky][xi + kx]; const int k = ky * 3 + kx;
;                         acc[0] += w[k][0] * bflo(gq.x); acc[1] += w[k][1] * bfhi(gq.x); acc[2] += w[k][2] * bflo(gq.y); acc[3] += w[k][3] * bfhi(gq.y);
;                         acc[4] += w[k][4] * bflo(gq.z); acc[5] += w[k][5] * bfhi(gq.z); acc[6] += w[k][6] * bflo(gq.w); acc[7] += w[k][7] * bfhi(gq.w); }
.LBB0_551:
	s_or_b64 exec, exec, s[2:3]
	s_waitcnt vmcnt(0)
	v_lshlrev_b32_e32 v180, 16, v132
	v_and_b32_e32 v132, 0xffff0000, v132
	v_fma_f32 v181, v5, v132, v77
	v_lshlrev_b32_e32 v132, 16, v133
	v_fma_f32 v182, v6, v132, v78
	v_and_b32_e32 v132, 0xffff0000, v133
	v_fma_f32 v183, v7, v132, v79
	v_lshlrev_b32_e32 v132, 16, v134
	v_fma_f32 v184, v0, v132, v72
	v_and_b32_e32 v132, 0xffff0000, v134
	v_fma_f32 v134, v1, v132, v73
	v_lshlrev_b32_e32 v132, 16, v135
	v_fma_f32 v185, v2, v132, v74
	v_and_b32_e32 v132, 0xffff0000, v135
	v_lshlrev_b32_e32 v199, 16, v136
	v_lshlrev_b32_e32 v198, 16, v124
	v_fma_f32 v180, v4, v180, v76
	v_fma_f32 v135, v3, v132, v75
	v_and_b32_e32 v197, 0xffff0000, v136
	v_fma_f32 v132, v8, v198, v180
	v_and_b32_e32 v196, 0xffff0000, v124
	v_fma_f32 v180, v9, v199, v132
	v_lshlrev_b32_e32 v194, 16, v125
	v_fma_f32 v124, v16, v196, v181
	v_lshlrev_b32_e32 v195, 16, v137
	v_fma_f32 v136, v17, v197, v124
	v_mad_i64_i32 v[120:121], s[4:5], v80, s28, v[170:171]
	v_fma_f32 v124, v10, v194, v182
	v_and_b32_e32 v193, 0xffff0000, v137
	v_and_b32_e32 v192, 0xffff0000, v125
	v_add_co_u32_e32 v200, vcc, 0x2000, v120
	v_fma_f32 v132, v11, v195, v124
	s_nop 0
	v_addc_co_u32_e32 v201, vcc, 0, v121, vcc
	v_mad_i64_i32 v[80:81], s[4:5], v81, s28, v[170:171]
	v_fma_f32 v124, v18, v192, v183
	v_lshlrev_b32_e32 v191, 16, v138
	v_lshlrev_b32_e32 v190, 16, v126
	v_add_co_u32_e32 v178, vcc, 0x2000, v80
	v_fma_f32 v133, v19, v193, v124
	s_nop 0
	v_addc_co_u32_e32 v179, vcc, 0, v81, vcc
	global_load_dwordx4 v[140:143], v[200:201], off offset:3072
	global_load_dwordx4 v[128:131], v[178:179], off offset:3072
	v_fma_f32 v124, v12, v190, v184
	v_and_b32_e32 v189, 0xffff0000, v138
	v_and_b32_e32 v188, 0xffff0000, v126
	v_fma_f32 v137, v13, v191, v124
	v_lshlrev_b32_e32 v186, 16, v127
	v_fma_f32 v124, v20, v188, v134
	v_lshlrev_b32_e32 v187, 16, v139
	v_fma_f32 v126, v21, v189, v124
	v_and_b32_e32 v184, 0xffff0000, v127
	v_fma_f32 v124, v14, v186, v185
	v_and_b32_e32 v185, 0xffff0000, v139
	v_fma_f32 v134, v15, v187, v124
	v_lshlrev_b32_e32 v203, 16, v152
	v_fma_f32 v124, v22, v184, v135
	v_lshlrev_b32_e32 v202, 16, v148
	v_fma_f32 v127, v23, v185, v124
	v_and_b32_e32 v205, 0xffff0000, v152
	v_fma_f32 v124, v24, v202, v180
	v_and_b32_e32 v204, 0xffff0000, v148
	v_fma_f32 v135, v25, v203, v124
	v_lshlrev_b32_e32 v206, 16, v149
	v_fma_f32 v124, v32, v204, v136
	v_lshlrev_b32_e32 v207, 16, v153
	v_fma_f32 v136, v33, v205, v124
	v_and_b32_e32 v209, 0xffff0000, v153
	v_fma_f32 v124, v26, v206, v132
	v_and_b32_e32 v208, 0xffff0000, v149
	v_fma_f32 v132, v27, v207, v124
	v_lshlrev_b32_e32 v211, 16, v154
	v_fma_f32 v124, v34, v208, v133
	v_lshlrev_b32_e32 v210, 16, v150
	v_fma_f32 v133, v35, v209, v124
	v_and_b32_e32 v213, 0xffff0000, v154
	v_fma_f32 v124, v28, v210, v137
	v_and_b32_e32 v212, 0xffff0000, v150
	v_fma_f32 v137, v29, v211, v124
	v_lshlrev_b32_e32 v214, 16, v151
	v_fma_f32 v124, v36, v212, v126
	v_lshlrev_b32_e32 v215, 16, v155
	v_fma_f32 v126, v37, v213, v124
	v_and_b32_e32 v217, 0xffff0000, v155
	v_fma_f32 v124, v30, v214, v134
	v_and_b32_e32 v216, 0xffff0000, v151
	v_fma_f32 v134, v31, v215, v124
	v_lshlrev_b32_e32 v183, 16, v164
	v_fma_f32 v124, v38, v216, v127
	v_lshlrev_b32_e32 v182, 16, v144
	v_fma_f32 v138, v39, v217, v124
	v_and_b32_e32 v181, 0xffff0000, v164
	v_fma_f32 v124, v40, v182, v135
	v_and_b32_e32 v180, 0xffff0000, v144
	v_fma_f32 v135, v41, v183, v124
	v_lshlrev_b32_e32 v152, 16, v145
	v_fma_f32 v124, v48, v180, v136
	v_lshlrev_b32_e32 v153, 16, v165
	v_fma_f32 v139, v49, v181, v124
	v_and_b32_e32 v149, 0xffff0000, v165
	v_fma_f32 v124, v42, v152, v132
	v_and_b32_e32 v148, 0xffff0000, v145
	v_fma_f32 v150, v43, v153, v124
	v_lshlrev_b32_e32 v145, 16, v166
	v_fma_f32 v124, v50, v148, v133
	v_lshlrev_b32_e32 v144, 16, v146
	v_fma_f32 v202, v51, v149, v124
	v_and_b32_e32 v136, 0xffff0000, v146
	v_fma_f32 v124, v44, v144, v137
	v_and_b32_e32 v137, 0xffff0000, v166
	v_fma_f32 v206, v45, v145, v124
	v_lshlrev_b32_e32 v132, 16, v147
	v_fma_f32 v124, v52, v136, v126
	v_lshlrev_b32_e32 v133, 16, v167
	v_fma_f32 v210, v53, v137, v124
	v_lshlrev_b32_e32 v166, 16, v156
	v_fma_f32 v124, v46, v132, v134
	v_fma_f32 v214, v47, v133, v124
	v_and_b32_e32 v125, 0xffff0000, v167
	v_and_b32_e32 v124, 0xffff0000, v147
	v_lshlrev_b32_e32 v167, 16, v160
	v_fma_f32 v126, v54, v124, v138
	v_fma_f32 v221, v55, v125, v126
	v_and_b32_e32 v165, 0xffff0000, v160
	v_fma_f32 v126, v56, v166, v135
	v_and_b32_e32 v164, 0xffff0000, v156
	v_fma_f32 v224, v57, v167, v126
	v_lshlrev_b32_e32 v154, 16, v157
	v_fma_f32 v126, v64, v164, v139
	v_lshlrev_b32_e32 v155, 16, v161
	v_fma_f32 v160, v65, v165, v126
	v_mul_f32_e32 v156, 0x3d372713, v224
	v_fma_f32 v126, v58, v154, v150
	v_and_b32_e32 v151, 0xffff0000, v161
	v_and_b32_e32 v150, 0xffff0000, v157
	v_mul_f32_e32 v156, v224, v156
	v_fma_f32 v225, v59, v155, v126
	v_fma_f32 v156, v224, v156, v224
	v_fma_f32 v126, v66, v150, v202
	v_lshlrev_b32_e32 v147, 16, v162
	v_lshlrev_b32_e32 v146, 16, v158
	v_mul_f32_e32 v156, 0xc0135761, v156
	v_fma_f32 v161, v67, v151, v126
	v_fma_f32 v126, v60, v146, v206
	v_and_b32_e32 v139, 0xffff0000, v162
	v_and_b32_e32 v138, 0xffff0000, v158
	v_fma_f32 v202, v61, v147, v126
	v_exp_f32_e32 v156, v156
	v_fma_f32 v126, v68, v138, v210
	v_lshlrev_b32_e32 v134, 16, v159
	v_lshlrev_b32_e32 v135, 16, v163
	v_fma_f32 v158, v69, v139, v126
	v_mad_i64_i32 v[80:81], s[4:5], v82, s28, v[170:171]
	v_fma_f32 v126, v62, v134, v214
	v_fma_f32 v162, v63, v135, v126
	v_and_b32_e32 v126, 0xffff0000, v159
	v_add_f32_e32 v159, 1.0, v156
	v_and_b32_e32 v127, 0xffff0000, v163
	v_rcp_f32_e32 v206, v159
	v_add_co_u32_e32 v176, vcc, 0x2000, v80
	s_nop 0
	s_nop 0
	v_addc_co_u32_e32 v177, vcc, 0, v81, vcc
	v_mad_i64_i32 v[80:81], s[4:5], v83, s28, v[170:171]
	v_add_co_u32_e32 v174, vcc, 0x2000, v80
	v_fma_f32 v156, v70, v126, v221
	s_nop 0
	v_addc_co_u32_e32 v175, vcc, 0, v81, vcc
	v_fma_f32 v156, v71, v127, v156
	v_mul_f32_e32 v214, 0x3d372713, v160
	v_mul_f32_e32 v214, v160, v214
	v_fma_f32 v214, v160, v214, v160
	v_mul_f32_e32 v214, 0xc0135761, v214
	v_exp_f32_e32 v214, v214
	v_mul_f32_e32 v157, v224, v206
	v_add_f32_e32 v163, 1.0, v214
	v_rcp_f32_e32 v210, v163
	s_waitcnt vmcnt(1)
; __device__ __forceinline__ unsigned cvt_pk_bf16(float lo, float hi) { unsigned r; asm("v_cvt_pk_bf16_f32 %0, %1, %2" : "=v"(r) : "v"(lo), "v"(hi)); return r; }
; __device__ __forceinline__ float bflo(unsigned w) { return __uint_as_float(w << 16); }
; __device__ __forceinline__ float bfhi(unsigned w) { return __uint_as_float(w & 0xffff0000u); }
; __device__ __forceinline__ float gelu_tanh(float x) { const float u = 0.7978845608028654f * (x + 0.044715f * x * x * x); return x / (1.f + __expf(-2.f * u)); }
; __device__ __forceinline__ void phase_conv(PRef p, int layer, int nseg) {
;     ...
;                 for (int ky = 0; ky < 3; ++ky)
; #pragma unroll
;                     for (int kx = 0; kx < 3; ++kx) { const u32x4 gq = gc[ky][xi + kx]; const int k = ky * 3 + kx;
;                         acc[0] += w[k][0] * bflo(gq.x); acc[1] += w[k][1] * bfhi(gq.x); acc[2] += w[k][2] * bflo(gq.y); acc[3] += w[k][3] * bfhi(gq.y);
;                         acc[4] += w[k][4] * bflo(gq.z); acc[5] += w[k][5] * bfhi(gq.z); acc[6] += w[k][6] * bflo(gq.w); acc[7] += w[k][7] * bfhi(gq.w); }
;                 u32x4 o;
;                 o.x = cvt_pk_bf16(gelu_tanh(acc[0]) * bflo(vv[xi].x), gelu_tanh(acc[1]) * bfhi(vv[xi].x));
;                 o.y = cvt_pk_bf16(gelu_tanh(acc[2]) * bflo(vv[xi].y), gelu_tanh(acc[3]) * bfhi(vv[xi].y));
;                 o.z = cvt_pk_bf16(gelu_tanh(acc[4]) * bflo(vv[xi].z), gelu_tanh(acc[5]) * bfhi(vv[xi].z));
;                 o.w = cvt_pk_bf16(gelu_tanh(acc[6]) * bflo(vv[xi].w), gelu_tanh(acc[7]) * bfhi(vv[xi].w));
;                 *(u32x4*)((bf16_t*)lp[1] + (size_t)(xb + xi) * NUP + NFF) = o; } }
	v_lshlrev_b32_e32 v159, 16, v140
	v_mul_f32_e32 v157, v157, v159
	v_and_b32_e32 v140, 0xffff0000, v140
	v_mul_f32_e32 v206, 0x3d372713, v225
	v_mul_f32_e32 v206, v225, v206
	v_fma_f32 v206, v225, v206, v225
	v_mul_f32_e32 v206, 0xc0135761, v206
	v_exp_f32_e32 v206, v206
	v_mul_f32_e32 v159, v160, v210
	v_mul_f32_e32 v140, v159, v140
	v_add_f32_e32 v160, 1.0, v206
	v_rcp_f32_e32 v206, v160
	v_cvt_pk_bf16_f32 v140, v157, v140
	global_load_dwordx4 v[120:123], v[176:177], off offset:3072
	global_load_dwordx4 v[80:83], v[174:175], off offset:3072
	v_fma_f32 v198, v4, v198, v76
	v_mul_f32_e32 v210, 0x3d372713, v161
	v_mul_f32_e32 v210, v161, v210
	v_fma_f32 v210, v161, v210, v161
	v_mul_f32_e32 v210, 0xc0135761, v210
	v_exp_f32_e32 v210, v210
	v_mul_f32_e32 v157, v225, v206
	v_add_f32_e32 v159, 1.0, v210
	v_rcp_f32_e32 v206, v159
	v_lshlrev_b32_e32 v160, 16, v141
	v_mul_f32_e32 v157, v157, v160
	v_and_b32_e32 v141, 0xffff0000, v141
	v_mul_f32_e32 v163, 0x3d372713, v202
	v_mul_f32_e32 v163, v202, v163
	v_fma_f32 v163, v202, v163, v202
	v_mul_f32_e32 v163, 0xc0135761, v163
	v_exp_f32_e32 v163, v163
	v_mul_f32_e32 v159, v161, v206
	v_mul_f32_e32 v141, v159, v141
	v_add_f32_e32 v160, 1.0, v163
	v_rcp_f32_e32 v163, v160
	v_cvt_pk_bf16_f32 v141, v157, v141
	v_fma_f32 v210, v5, v196, v77
	s_waitcnt vmcnt(2)
	v_lshlrev_b32_e32 v232, 16, v129
	v_mul_f32_e32 v206, 0x3d372713, v158
	v_mul_f32_e32 v206, v158, v206
	v_fma_f32 v206, v158, v206, v158
	v_mul_f32_e32 v206, 0xc0135761, v206
	v_exp_f32_e32 v206, v206
	v_mul_f32_e32 v157, v202, v163
	v_add_f32_e32 v159, 1.0, v206
	v_rcp_f32_e32 v163, v159
	v_lshlrev_b32_e32 v160, 16, v142
	v_mul_f32_e32 v157, v157, v160
	v_and_b32_e32 v142, 0xffff0000, v142
	v_mul_f32_e32 v161, 0x3d372713, v162
	v_mul_f32_e32 v161, v162, v161
	v_fma_f32 v161, v162, v161, v162
	v_mul_f32_e32 v161, 0xc0135761, v161
	v_exp_f32_e32 v161, v161
	v_mul_f32_e32 v158, v158, v163
	v_mul_f32_e32 v142, v158, v142
	v_add_f32_e32 v159, 1.0, v161
	v_rcp_f32_e32 v161, v159
	v_cvt_pk_bf16_f32 v142, v157, v142
	v_fma_f32 v214, v6, v194, v78
	v_and_b32_e32 v194, 0xffff0000, v131
	v_mul_f32_e32 v163, 0x3d372713, v156
	v_mul_f32_e32 v163, v156, v163
	v_fma_f32 v163, v156, v163, v156
	v_mul_f32_e32 v163, 0xc0135761, v163
	v_exp_f32_e32 v163, v163
	v_mul_f32_e32 v157, v162, v161
	v_add_f32_e32 v158, 1.0, v163
	v_rcp_f32_e32 v161, v158
	v_lshlrev_b32_e32 v159, 16, v143
	v_mul_f32_e32 v157, v157, v159
	v_and_b32_e32 v143, 0xffff0000, v143
	v_mul_f32_e32 v156, v156, v161
	v_mul_f32_e32 v143, v156, v143
	v_cvt_pk_bf16_f32 v143, v157, v143
	v_pk_mov_b32 v[156:157], v[206:207], v[152:153] op_sel:[1,0]
	v_lshlrev_b32_e32 v207, 16, v108
	v_lshlrev_b32_e32 v206, 16, v104
	v_pk_mov_b32 v[158:159], v[208:209], v[148:149] op_sel:[1,0]
	v_pk_mov_b32 v[160:161], v[210:211], v[144:145] op_sel:[1,0]
	v_lshlrev_b32_e32 v149, 16, v128
	v_and_b32_e32 v153, 0xffff0000, v128
	v_and_b32_e32 v145, 0xffff0000, v129
	v_pk_mov_b32 v[128:129], v[198:199], v[206:207] op_sel:[1,0]
	global_store_dwordx4 v[200:201], v[140:143], off offset:3072
	v_pk_mov_b32 v[162:163], v[212:213], v[136:137] op_sel:[1,0]
	s_nop 0
	v_pk_mov_b32 v[140:141], v[202:203], v[182:183] op_sel:[1,0]
	v_fma_f32 v128, v8, v128, v198
	v_fma_f32 v128, v9, v129, v128
	v_fma_f32 v128, v24, v140, v128
	v_pk_mov_b32 v[200:201], v[214:215], v[132:133] op_sel:[1,0]
	v_lshlrev_b32_e32 v137, 16, v130
	v_and_b32_e32 v133, 0xffff0000, v130
	v_fma_f32 v130, v4, v199, v76
	v_fma_f32 v233, v25, v141, v128
	v_and_b32_e32 v209, 0xffff0000, v108
	v_fma_f32 v128, v8, v206, v130
	v_and_b32_e32 v208, 0xffff0000, v104
	v_fma_f32 v234, v9, v207, v128
	v_pk_mov_b32 v[128:129], v[196:197], v[208:209] op_sel:[1,0]
	v_pk_mov_b32 v[142:143], v[204:205], v[180:181] op_sel:[1,0]
	v_fma_f32 v104, v16, v128, v210
	v_fma_f32 v104, v17, v129, v104
	v_pk_mul_f32 v[202:203], v[30:31], v[200:201]
	v_pk_mov_b32 v[200:201], v[216:217], v[124:125] op_sel:[1,0]
	v_lshlrev_b32_e32 v125, 16, v131
	v_fma_f32 v131, v5, v197, v77
	v_fma_f32 v104, v32, v142, v104
	v_fma_f32 v235, v33, v143, v104
	v_fma_f32 v104, v16, v208, v131
	v_lshlrev_b32_e32 v210, 16, v105
	v_lshlrev_b32_e32 v211, 16, v109
	v_fma_f32 v236, v17, v209, v104
	v_pk_mov_b32 v[128:129], v[194:195], v[210:211] op_sel:[1,0]
	v_fma_f32 v181, v6, v195, v78
	v_fma_f32 v104, v10, v128, v214
	v_fma_f32 v104, v11, v129, v104
	v_fma_f32 v104, v26, v156, v104
	v_fma_f32 v237, v27, v157, v104
	v_fma_f32 v104, v10, v210, v181
	v_and_b32_e32 v213, 0xffff0000, v109
	v_and_b32_e32 v212, 0xffff0000, v105
	v_fma_f32 v238, v11, v211, v104
	v_pk_mov_b32 v[104:105], v[192:193], v[212:213] op_sel:[1,0]
	v_fma_f32 v221, v7, v192, v79
	v_fma_f32 v104, v18, v104, v221
	v_fma_f32 v104, v19, v105, v104
	v_fma_f32 v104, v34, v158, v104
	v_fma_f32 v183, v7, v193, v79
	v_fma_f32 v221, v35, v159, v104
	v_fma_f32 v190, v0, v190, v72
	v_fma_f32 v104, v18, v212, v183
	v_lshlrev_b32_e32 v215, 16, v110
	v_lshlrev_b32_e32 v214, 16, v106
	v_fma_f32 v239, v19, v213, v104
	v_pk_mov_b32 v[104:105], v[190:191], v[214:215] op_sel:[1,0]
	s_waitcnt vmcnt(2)
; __device__ __forceinline__ unsigned cvt_pk_bf16(float lo, float hi) { unsigned r; asm("v_cvt_pk_bf16_f32 %0, %1, %2" : "=v"(r) : "v"(lo), "v"(hi)); return r; }
; __device__ __forceinline__ float bflo(unsigned w) { return __uint_as_float(w << 16); }
; __device__ __forceinline__ float bfhi(unsigned w) { return __uint_as_float(w & 0xffff0000u); }
; __device__ __forceinline__ float gelu_tanh(float x) { const float u = 0.7978845608028654f * (x + 0.044715f * x * x * x); return x / (1.f + __expf(-2.f * u)); }
; __device__ __forceinline__ void phase_conv(PRef p, int layer, int nseg) {
;     ...
;                 for (int ky = 0; ky < 3; ++ky)
; #pragma unroll
;                     for (int kx = 0; kx < 3; ++kx) { const u32x4 gq = gc[ky][xi + kx]; const int k = ky * 3 + kx;
;                         acc[0] += w[k][0] * bflo(gq.x); acc[1] += w[k][1] * bfhi(gq.x); acc[2] += w[k][2] * bflo(gq.y); acc[3] += w[k][3] * bfhi(gq.y);
;                         acc[4] += w[k][4] * bflo(gq.z); acc[5] += w[k][5] * bfhi(gq.z); acc[6] += w[k][6] * bflo(gq.w); acc[7] += w[k][7] * bfhi(gq.w); }
;                 u32x4 o;
;                 o.x = cvt_pk_bf16(gelu_tanh(acc[0]) * bflo(vv[xi].x), gelu_tanh(acc[1]) * bfhi(vv[xi].x));
;                 o.y = cvt_pk_bf16(gelu_tanh(acc[2]) * bflo(vv[xi].y), gelu_tanh(acc[3]) * bfhi(vv[xi].y));
;                 o.z = cvt_pk_bf16(gelu_tanh(acc[4]) * bflo(vv[xi].z), gelu_tanh(acc[5]) * bfhi(vv[xi].z));
;                 o.w = cvt_pk_bf16(gelu_tanh(acc[6]) * bflo(vv[xi].w), gelu_tanh(acc[7]) * bfhi(vv[xi].w));
;                 *(u32x4*)((bf16_t*)lp[1] + (size_t)(xb + xi) * NUP + NFF) = o; } }
	v_lshlrev_b32_e32 v181, 16, v120
	v_fma_f32 v104, v12, v104, v190
	v_fma_f32 v104, v13, v105, v104
	v_fma_f32 v104, v28, v160, v104
	v_and_b32_e32 v240, 0xffff0000, v120
	v_lshlrev_b32_e32 v241, 16, v121
	v_and_b32_e32 v242, 0xffff0000, v121
	v_lshlrev_b32_e32 v243, 16, v122
	v_and_b32_e32 v199, 0xffff0000, v122
	v_lshlrev_b32_e32 v121, 16, v123
	v_and_b32_e32 v120, 0xffff0000, v123
	v_lshlrev_b32_e32 v123, 16, v100
	v_mov_b32_e32 v122, v207
	v_pk_mul_f32 v[204:205], v[38:39], v[200:201]
	v_fma_f32 v200, v0, v191, v72
	v_fma_f32 v201, v29, v161, v104
	v_fma_f32 v183, v4, v206, v76
	v_fma_f32 v104, v12, v214, v200
	v_and_b32_e32 v217, 0xffff0000, v110
	v_and_b32_e32 v216, 0xffff0000, v106
	v_fma_f32 v122, v8, v122, v183
	v_fma_f32 v200, v13, v215, v104
	v_pk_mov_b32 v[104:105], v[188:189], v[216:217] op_sel:[1,0]
	v_fma_f32 v207, v9, v123, v122
	v_and_b32_e32 v123, 0xffff0000, v100
	v_mov_b32_e32 v122, v209
	v_fma_f32 v224, v1, v188, v73
	v_fma_f32 v206, v5, v208, v77
	v_fma_f32 v104, v20, v104, v224
	v_fma_f32 v100, v16, v122, v206
	v_fma_f32 v104, v21, v105, v104
	v_fma_f32 v206, v17, v123, v100
	v_lshlrev_b32_e32 v123, 16, v101
	v_mov_b32_e32 v122, v211
	v_fma_f32 v104, v36, v162, v104
	v_fma_f32 v208, v6, v210, v78
	v_fma_f32 v225, v1, v189, v73
	v_fma_f32 v198, v37, v163, v104
	v_fma_f32 v100, v10, v122, v208
	v_fma_f32 v186, v2, v186, v74
	v_fma_f32 v104, v20, v216, v225
	v_lshlrev_b32_e32 v224, 16, v107
	v_lshlrev_b32_e32 v225, 16, v111
	v_fma_f32 v208, v11, v123, v100
	v_and_b32_e32 v101, 0xffff0000, v101
	v_mov_b32_e32 v100, v213
	v_fma_f32 v197, v21, v217, v104
	v_pk_mov_b32 v[104:105], v[186:187], v[224:225] op_sel:[1,0]
	v_fma_f32 v210, v7, v212, v79
	v_fma_f32 v100, v18, v100, v210
	v_fma_f32 v104, v14, v104, v186
	v_fma_f32 v209, v19, v101, v100
	v_lshlrev_b32_e32 v101, 16, v102
	v_mov_b32_e32 v100, v215
	v_fma_f32 v104, v15, v105, v104
	v_fma_f32 v212, v0, v214, v72
	v_add_f32_e32 v104, v104, v202
	v_fma_f32 v100, v12, v100, v212
	v_fma_f32 v227, v2, v187, v74
	v_add_f32_e32 v196, v104, v203
	v_fma_f32 v210, v13, v101, v100
	v_and_b32_e32 v101, 0xffff0000, v102
	v_mov_b32_e32 v100, v217
	v_fma_f32 v104, v14, v224, v227
	v_and_b32_e32 v203, 0xffff0000, v111
	v_and_b32_e32 v202, 0xffff0000, v107
	v_fma_f32 v214, v1, v216, v73
	v_fma_f32 v195, v15, v225, v104
	v_pk_mov_b32 v[104:105], v[184:185], v[202:203] op_sel:[1,0]
	v_fma_f32 v100, v20, v100, v214
	v_fma_f32 v226, v3, v184, v75
	v_fma_f32 v123, v21, v101, v100
	v_lshlrev_b32_e32 v101, 16, v103
	v_mov_b32_e32 v100, v225
	v_fma_f32 v104, v22, v104, v226
	v_fma_f32 v216, v2, v224, v74
	v_fma_f32 v104, v23, v105, v104
	v_fma_f32 v100, v14, v100, v216
	v_add_f32_e32 v104, v104, v204
	v_fma_f32 v122, v15, v101, v100
	v_and_b32_e32 v101, 0xffff0000, v103
	v_mov_b32_e32 v100, v203
	v_add_f32_e32 v193, v104, v205
	v_pk_mul_f32 v[104:105], v[22:23], v[202:203]
	v_fma_f32 v202, v3, v202, v75
	v_fma_f32 v228, v3, v185, v75
	v_fma_f32 v100, v22, v100, v202
	v_lshlrev_b32_e32 v202, 16, v88
	v_add_f32_e32 v104, v228, v104
	v_mov_b32_e32 v102, v202
	v_mov_b32_e32 v103, v166
	v_add_f32_e32 v192, v104, v105
	v_lshlrev_b32_e32 v105, 16, v116
	v_lshlrev_b32_e32 v104, 16, v112
	v_pk_mov_b32 v[106:107], v[166:167], v[104:105] op_sel:[1,0]
	v_fma_f32 v100, v23, v101, v100
	v_fma_f32 v101, v40, v102, v233
	v_fma_f32 v101, v41, v103, v101
	v_fma_f32 v101, v56, v106, v101
	v_fma_f32 v101, v57, v107, v101
	v_mul_f32_e32 v166, 0x3d372713, v101
	v_mul_f32_e32 v166, v101, v166
	v_fma_f32 v166, v101, v166, v101
	v_mul_f32_e32 v166, 0xc0135761, v166
	v_mov_b32_e32 v183, v202
	v_lshlrev_b32_e32 v203, 16, v96
	v_pk_mul_f32 v[102:103], v[24:25], v[182:183]
	v_exp_f32_e32 v182, v166
	v_add_f32_e32 v102, v234, v102
	v_mov_b32_e32 v166, v203
	v_add_f32_e32 v183, v102, v103
	v_pk_mul_f32 v[226:227], v[56:57], v[104:105]
	v_fma_f32 v102, v40, v166, v183
	v_fma_f32 v102, v41, v167, v102
	v_fma_f32 v102, v56, v104, v102
	v_fma_f32 v102, v57, v105, v102
	v_mul_f32_e32 v167, 0x3d372713, v102
	v_add_f32_e32 v182, 1.0, v182
	v_mul_f32_e32 v167, v102, v167
	v_fma_f32 v167, v102, v167, v102
	v_rcp_f32_e32 v205, v182
	v_mul_f32_e32 v167, 0xc0135761, v167
	v_exp_f32_e32 v167, v167
	s_nop 0
	v_add_f32_e32 v167, 1.0, v167
	v_rcp_f32_e32 v204, v167
	v_mul_f32_e32 v101, v101, v205
	v_mul_f32_e32 v149, v101, v149
	v_mul_f32_e32 v101, v102, v204
	v_mul_f32_e32 v102, v101, v181
	v_fma_f32 v101, v24, v202, v207
	v_and_b32_e32 v166, 0xffff0000, v88
	v_mov_b32_e32 v182, v166
	v_mov_b32_e32 v183, v164
	v_and_b32_e32 v107, 0xffff0000, v116
	v_and_b32_e32 v106, 0xffff0000, v112
	v_pk_mov_b32 v[108:109], v[164:165], v[106:107] op_sel:[1,0]
	v_fma_f32 v88, v48, v182, v235
	v_pk_mul_f32 v[228:229], v[64:65], v[108:109]
	v_fma_f32 v88, v49, v183, v88
	v_fma_f32 v88, v64, v108, v88
	v_fma_f32 v88, v65, v109, v88
	v_fma_f32 v101, v25, v203, v101
	v_and_b32_e32 v167, 0xffff0000, v96
	v_mul_f32_e32 v96, 0x3d372713, v88
	v_mul_f32_e32 v96, v88, v96
	v_fma_f32 v96, v88, v96, v88
	v_mov_b32_e32 v181, v166
	v_mul_f32_e32 v96, 0xc0135761, v96
	v_fma_f32 v103, v32, v180, v236
	v_mov_b32_e32 v164, v167
	v_exp_f32_e32 v96, v96
	v_fma_f32 v103, v33, v181, v103
	v_pk_mul_f32 v[230:231], v[64:65], v[106:107]
	v_fma_f32 v103, v48, v164, v103
	v_fma_f32 v103, v49, v165, v103
	v_fma_f32 v103, v64, v106, v103
	v_add_f32_e32 v96, 1.0, v96
	v_fma_f32 v103, v65, v107, v103
	v_mul_f32_e32 v182, 0x3d372713, v103
	v_rcp_f32_e32 v181, v96
	v_mul_f32_e32 v182, v103, v182
	v_fma_f32 v182, v103, v182, v103
	v_mul_f32_e32 v182, 0xc0135761, v182
	v_exp_f32_e32 v182, v182
	s_nop 0
	v_add_f32_e32 v180, 1.0, v182
	v_rcp_f32_e32 v183, v180
	v_mul_f32_e32 v88, v88, v181
; __device__ __forceinline__ unsigned cvt_pk_bf16(float lo, float hi) { unsigned r; asm("v_cvt_pk_bf16_f32 %0, %1, %2" : "=v"(r) : "v"(lo), "v"(hi)); return r; }
; __device__ __forceinline__ float bflo(unsigned w) { return __uint_as_float(w << 16); }
; __device__ __forceinline__ float bfhi(unsigned w) { return __uint_as_float(w & 0xffff0000u); }
; __device__ __forceinline__ float gelu_tanh(float x) { const float u = 0.7978845608028654f * (x + 0.044715f * x * x * x); return x / (1.f + __expf(-2.f * u)); }
; __device__ __forceinline__ void phase_conv(PRef p, int layer, int nseg) {
;     ...
;                 for (int ky = 0; ky < 3; ++ky)
; #pragma unroll
;                     for (int kx = 0; kx < 3; ++kx) { const u32x4 gq = gc[ky][xi + kx]; const int k = ky * 3 + kx;
;                         acc[0] += w[k][0] * bflo(gq.x); acc[1] += w[k][1] * bfhi(gq.x); acc[2] += w[k][2] * bflo(gq.y); acc[3] += w[k][3] * bfhi(gq.y);
;                         acc[4] += w[k][4] * bflo(gq.z); acc[5] += w[k][5] * bfhi(gq.z); acc[6] += w[k][6] * bflo(gq.w); acc[7] += w[k][7] * bfhi(gq.w); }
;                 u32x4 o;
;                 o.x = cvt_pk_bf16(gelu_tanh(acc[0]) * bflo(vv[xi].x), gelu_tanh(acc[1]) * bfhi(vv[xi].x));
;                 o.y = cvt_pk_bf16(gelu_tanh(acc[2]) * bflo(vv[xi].y), gelu_tanh(acc[3]) * bfhi(vv[xi].y));
;                 o.z = cvt_pk_bf16(gelu_tanh(acc[4]) * bflo(vv[xi].z), gelu_tanh(acc[5]) * bfhi(vv[xi].z));
;                 o.w = cvt_pk_bf16(gelu_tanh(acc[6]) * bflo(vv[xi].w), gelu_tanh(acc[7]) * bfhi(vv[xi].w));
;                 *(u32x4*)((bf16_t*)lp[1] + (size_t)(xb + xi) * NUP + NFF) = o; } }
	v_mul_f32_e32 v88, v88, v153
	v_mul_f32_e32 v96, v103, v183
	v_pk_mul_f32 v[164:165], v[32:33], v[166:167]
	v_mul_f32_e32 v103, v96, v240
	v_add_f32_e32 v96, v206, v164
	v_lshlrev_b32_e32 v164, 16, v89
	v_mov_b32_e32 v166, v164
	v_mov_b32_e32 v167, v154
	v_lshlrev_b32_e32 v108, 16, v113
	v_lshlrev_b32_e32 v109, 16, v117
	v_pk_mov_b32 v[110:111], v[154:155], v[108:109] op_sel:[1,0]
	v_cvt_pk_bf16_f32 v88, v149, v88
	v_fma_f32 v149, v42, v166, v237
	v_pk_mul_f32 v[190:191], v[58:59], v[110:111]
	v_fma_f32 v149, v43, v167, v149
	v_fma_f32 v149, v58, v110, v149
	v_fma_f32 v149, v59, v111, v149
	v_mul_f32_e32 v154, 0x3d372713, v149
	v_mul_f32_e32 v154, v149, v154
	v_fma_f32 v154, v149, v154, v149
	v_mul_f32_e32 v154, 0xc0135761, v154
	v_mov_b32_e32 v153, v164
	v_add_f32_e32 v96, v96, v165
	v_lshlrev_b32_e32 v165, 16, v97
	v_exp_f32_e32 v166, v154
	v_fma_f32 v152, v26, v152, v238
	v_mov_b32_e32 v154, v165
	v_fma_f32 v167, v27, v153, v152
	v_pk_mul_f32 v[188:189], v[58:59], v[108:109]
	v_fma_f32 v152, v42, v154, v167
	v_fma_f32 v152, v43, v155, v152
	v_fma_f32 v152, v58, v108, v152
	v_fma_f32 v152, v59, v109, v152
	v_mul_f32_e32 v155, 0x3d372713, v152
	v_add_f32_e32 v166, 1.0, v166
	v_mul_f32_e32 v155, v152, v155
	v_fma_f32 v155, v152, v155, v152
	v_rcp_f32_e32 v181, v166
	v_mul_f32_e32 v155, 0xc0135761, v155
	v_exp_f32_e32 v155, v155
	s_nop 0
	v_add_f32_e32 v155, 1.0, v155
	v_rcp_f32_e32 v180, v155
	v_mul_f32_e32 v149, v149, v181
	v_mul_f32_e32 v166, v149, v232
	v_mul_f32_e32 v149, v152, v180
	v_mul_f32_e32 v167, v149, v241
	v_fma_f32 v149, v26, v164, v208
	v_and_b32_e32 v152, 0xffff0000, v89
	v_mov_b32_e32 v154, v152
	v_mov_b32_e32 v155, v150
	v_and_b32_e32 v111, 0xffff0000, v117
	v_and_b32_e32 v110, 0xffff0000, v113
	v_pk_mov_b32 v[112:113], v[150:151], v[110:111] op_sel:[1,0]
	v_fma_f32 v89, v50, v154, v221
	v_pk_mul_f32 v[186:187], v[66:67], v[112:113]
	v_fma_f32 v89, v51, v155, v89
	v_fma_f32 v89, v66, v112, v89
	v_fma_f32 v89, v67, v113, v89
	v_fma_f32 v164, v27, v165, v149
	v_and_b32_e32 v153, 0xffff0000, v97
	v_mul_f32_e32 v97, 0x3d372713, v89
	v_mov_b32_e32 v149, v152
	v_mul_f32_e32 v97, v89, v97
	v_fma_f32 v97, v89, v97, v89
	v_mul_f32_e32 v97, 0xc0135761, v97
	v_fma_f32 v148, v34, v148, v239
	v_mov_b32_e32 v150, v153
	v_fma_f32 v154, v35, v149, v148
	v_fma_f32 v148, v50, v150, v154
	v_pk_mul_f32 v[184:185], v[66:67], v[110:111]
	v_exp_f32_e32 v97, v97
	v_fma_f32 v148, v51, v151, v148
	v_fma_f32 v148, v66, v110, v148
	v_fma_f32 v148, v67, v111, v148
	v_mul_f32_e32 v151, 0x3d372713, v148
	v_add_f32_e32 v97, 1.0, v97
	v_mul_f32_e32 v151, v148, v151
	v_fma_f32 v151, v148, v151, v148
	v_rcp_f32_e32 v165, v97
	v_mul_f32_e32 v151, 0xc0135761, v151
	v_exp_f32_e32 v151, v151
	s_nop 0
	v_add_f32_e32 v151, 1.0, v151
	v_rcp_f32_e32 v155, v151
	v_mul_f32_e32 v89, v89, v165
	v_mul_f32_e32 v89, v89, v145
	v_mul_f32_e32 v97, v148, v155
	v_mov_b32_e32 v151, v146
	v_fma_f32 v145, v34, v152, v209
	v_lshlrev_b32_e32 v148, 16, v90
	v_mov_b32_e32 v150, v148
	v_lshlrev_b32_e32 v113, 16, v118
	v_lshlrev_b32_e32 v112, 16, v114
	v_pk_mov_b32 v[116:117], v[146:147], v[112:113] op_sel:[1,0]
	v_fma_f32 v152, v35, v153, v145
	v_fma_f32 v145, v44, v150, v201
	v_pk_mul_f32 v[162:163], v[60:61], v[116:117]
	v_fma_f32 v146, v45, v151, v145
	v_fma_f32 v146, v60, v116, v146
	v_fma_f32 v150, v61, v117, v146
	v_mul_f32_e32 v146, 0x3d372713, v150
	v_mul_f32_e32 v146, v150, v146
	v_fma_f32 v146, v150, v146, v150
	v_mul_f32_e32 v146, 0xc0135761, v146
	v_mov_b32_e32 v145, v148
	v_lshlrev_b32_e32 v149, 16, v98
	v_exp_f32_e32 v151, v146
	v_fma_f32 v144, v28, v144, v200
	v_mov_b32_e32 v146, v149
	v_fma_f32 v153, v29, v145, v144
	v_pk_mul_f32 v[160:161], v[60:61], v[112:113]
	v_fma_f32 v144, v44, v146, v153
	v_fma_f32 v144, v45, v147, v144
	v_fma_f32 v144, v60, v112, v144
	v_fma_f32 v144, v61, v113, v144
	v_mul_f32_e32 v147, 0x3d372713, v144
	v_add_f32_e32 v151, 1.0, v151
	v_mul_f32_e32 v147, v144, v147
	v_fma_f32 v147, v144, v147, v144
	v_rcp_f32_e32 v155, v151
	v_mul_f32_e32 v147, 0xc0135761, v147
	v_exp_f32_e32 v147, v147
	s_nop 0
	v_add_f32_e32 v147, 1.0, v147
	v_rcp_f32_e32 v154, v147
	v_mul_f32_e32 v145, v150, v155
	v_mul_f32_e32 v150, v145, v137
	v_mul_f32_e32 v137, v144, v154
	v_mul_f32_e32 v151, v137, v243
	v_fma_f32 v137, v28, v148, v210
	v_and_b32_e32 v144, 0xffff0000, v90
	v_mov_b32_e32 v146, v144
	v_mov_b32_e32 v147, v138
	v_and_b32_e32 v117, 0xffff0000, v118
	v_and_b32_e32 v116, 0xffff0000, v114
	v_pk_mov_b32 v[128:129], v[138:139], v[116:117] op_sel:[1,0]
	v_fma_f32 v90, v52, v146, v198
	v_pk_mul_f32 v[158:159], v[68:69], v[128:129]
	v_fma_f32 v90, v53, v147, v90
	v_fma_f32 v90, v68, v128, v90
	v_fma_f32 v90, v69, v129, v90
	v_fma_f32 v148, v29, v149, v137
	v_and_b32_e32 v145, 0xffff0000, v98
	v_mul_f32_e32 v98, 0x3d372713, v90
	v_mov_b32_e32 v137, v144
	v_mul_f32_e32 v98, v90, v98
	v_fma_f32 v98, v90, v98, v90
	v_mul_f32_e32 v98, 0xc0135761, v98
	v_fma_f32 v136, v36, v136, v197
	v_mov_b32_e32 v138, v145
	v_fma_f32 v146, v37, v137, v136
	v_fma_f32 v136, v52, v138, v146
	v_pk_mul_f32 v[156:157], v[68:69], v[116:117]
	v_exp_f32_e32 v98, v98
	v_fma_f32 v136, v53, v139, v136
	v_fma_f32 v136, v68, v116, v136
	v_fma_f32 v136, v69, v117, v136
	v_mul_f32_e32 v139, 0x3d372713, v136
	v_add_f32_e32 v98, 1.0, v98
	v_mul_f32_e32 v139, v136, v139
	v_fma_f32 v139, v136, v139, v136
	v_rcp_f32_e32 v149, v98
	v_mul_f32_e32 v139, 0xc0135761, v139
	v_exp_f32_e32 v139, v139
	s_nop 0
	v_add_f32_e32 v139, 1.0, v139
	v_rcp_f32_e32 v147, v139
	v_mul_f32_e32 v90, v90, v149
	v_mul_f32_e32 v90, v90, v133
	v_mul_f32_e32 v98, v136, v147
	v_mul_f32_e32 v146, v98, v199
	v_fma_f32 v98, v36, v144, v123
; __device__ __forceinline__ unsigned cvt_pk_bf16(float lo, float hi) { unsigned r; asm("v_cvt_pk_bf16_f32 %0, %1, %2" : "=v"(r) : "v"(lo), "v"(hi)); return r; }
; __device__ __forceinline__ float bflo(unsigned w) { return __uint_as_float(w << 16); }
; __device__ __forceinline__ float bfhi(unsigned w) { return __uint_as_float(w & 0xffff0000u); }
; __device__ __forceinline__ float gelu_tanh(float x) { const float u = 0.7978845608028654f * (x + 0.044715f * x * x * x); return x / (1.f + __expf(-2.f * u)); }
; __device__ __forceinline__ void phase_conv(PRef p, int layer, int nseg) {
;     ...
;                 for (int ky = 0; ky < 3; ++ky)
; #pragma unroll
;                     for (int kx = 0; kx < 3; ++kx) { const u32x4 gq = gc[ky][xi + kx]; const int k = ky * 3 + kx;
;                         acc[0] += w[k][0] * bflo(gq.x); acc[1] += w[k][1] * bfhi(gq.x); acc[2] += w[k][2] * bflo(gq.y); acc[3] += w[k][3] * bfhi(gq.y);
;                         acc[4] += w[k][4] * bflo(gq.z); acc[5] += w[k][5] * bfhi(gq.z); acc[6] += w[k][6] * bflo(gq.w); acc[7] += w[k][7] * bfhi(gq.w); }
;                 u32x4 o;
;                 o.x = cvt_pk_bf16(gelu_tanh(acc[0]) * bflo(vv[xi].x), gelu_tanh(acc[1]) * bfhi(vv[xi].x));
;                 o.y = cvt_pk_bf16(gelu_tanh(acc[2]) * bflo(vv[xi].y), gelu_tanh(acc[3]) * bfhi(vv[xi].y));
;                 o.z = cvt_pk_bf16(gelu_tanh(acc[4]) * bflo(vv[xi].z), gelu_tanh(acc[5]) * bfhi(vv[xi].z));
;                 o.w = cvt_pk_bf16(gelu_tanh(acc[6]) * bflo(vv[xi].w), gelu_tanh(acc[7]) * bfhi(vv[xi].w));
;                 *(u32x4*)((bf16_t*)lp[1] + (size_t)(xb + xi) * NUP + NFF) = o; } }
	v_lshlrev_b32_e32 v136, 16, v91
	v_mov_b32_e32 v138, v136
	v_mov_b32_e32 v139, v134
	v_lshlrev_b32_e32 v128, 16, v115
	v_lshlrev_b32_e32 v129, 16, v119
	v_pk_mov_b32 v[130:131], v[134:135], v[128:129] op_sel:[1,0]
	v_fma_f32 v144, v37, v145, v98
	v_fma_f32 v98, v46, v138, v196
	v_pk_mul_f32 v[142:143], v[62:63], v[130:131]
	v_fma_f32 v98, v47, v139, v98
	v_fma_f32 v98, v62, v130, v98
	v_fma_f32 v98, v63, v131, v98
	v_mul_f32_e32 v123, 0x3d372713, v98
	v_mov_b32_e32 v133, v136
	v_mul_f32_e32 v123, v98, v123
	v_lshlrev_b32_e32 v137, 16, v99
	v_fma_f32 v123, v98, v123, v98
	v_mul_f32_e32 v123, 0xc0135761, v123
	v_fma_f32 v132, v30, v132, v195
	v_mov_b32_e32 v134, v137
	v_fma_f32 v138, v31, v133, v132
	v_fma_f32 v132, v46, v134, v138
	v_pk_mul_f32 v[140:141], v[62:63], v[128:129]
	v_exp_f32_e32 v123, v123
	v_fma_f32 v132, v47, v135, v132
	v_fma_f32 v132, v62, v128, v132
	v_fma_f32 v132, v63, v129, v132
	v_mul_f32_e32 v135, 0x3d372713, v132
	v_add_f32_e32 v123, 1.0, v123
	v_mul_f32_e32 v135, v132, v135
	v_fma_f32 v135, v132, v135, v132
	v_rcp_f32_e32 v142, v123
	v_mul_f32_e32 v135, 0xc0135761, v135
	v_exp_f32_e32 v135, v135
	s_nop 0
	v_add_f32_e32 v135, 1.0, v135
	v_rcp_f32_e32 v139, v135
	v_mul_f32_e32 v98, v98, v142
	v_mul_f32_e32 v134, v98, v125
	v_mul_f32_e32 v98, v132, v139
	v_pk_mul_f32 v[132:133], v[30:31], v[136:137]
	v_mul_f32_e32 v121, v98, v121
	v_fma_f32 v98, v30, v136, v122
	v_fma_f32 v132, v31, v137, v98
	v_and_b32_e32 v98, 0xffff0000, v91
	v_mov_b32_e32 v122, v98
	v_mov_b32_e32 v123, v126
	v_and_b32_e32 v119, 0xffff0000, v119
	v_and_b32_e32 v118, 0xffff0000, v115
	v_pk_mov_b32 v[114:115], v[126:127], v[118:119] op_sel:[1,0]
	v_fma_f32 v91, v54, v122, v193
	v_pk_mul_f32 v[130:131], v[70:71], v[114:115]
	v_fma_f32 v91, v55, v123, v91
	v_fma_f32 v91, v70, v114, v91
	v_mov_b32_e32 v125, v98
	v_fma_f32 v91, v71, v115, v91
	v_pk_mul_f32 v[122:123], v[38:39], v[124:125]
	v_mul_f32_e32 v124, 0x3d372713, v91
	v_mul_f32_e32 v124, v91, v124
	v_fma_f32 v124, v91, v124, v91
	v_and_b32_e32 v99, 0xffff0000, v99
	v_mul_f32_e32 v124, 0xc0135761, v124
	v_add_f32_e32 v122, v192, v122
	v_mov_b32_e32 v126, v99
	v_add_f32_e32 v125, v122, v123
	v_pk_mul_f32 v[122:123], v[54:55], v[126:127]
	v_exp_f32_e32 v124, v124
	v_fma_f32 v122, v54, v126, v125
	v_fma_f32 v122, v55, v127, v122
	v_fma_f32 v114, v70, v118, v122
	v_fma_f32 v114, v71, v119, v114
	v_add_f32_e32 v124, 1.0, v124
	v_mul_f32_e32 v115, 0x3d372713, v114
	v_mul_f32_e32 v115, v114, v115
	v_rcp_f32_e32 v131, v124
	v_fma_f32 v115, v114, v115, v114
	v_mul_f32_e32 v115, 0xc0135761, v115
	v_exp_f32_e32 v115, v115
	s_nop 0
	v_add_f32_e32 v115, 1.0, v115
	v_rcp_f32_e32 v126, v115
	v_mul_f32_e32 v91, v91, v131
	v_cvt_pk_bf16_f32 v89, v166, v89
	v_mul_f32_e32 v91, v91, v194
	v_mul_f32_e32 v97, v97, v242
	v_cvt_pk_bf16_f32 v90, v150, v90
	v_mul_f32_e32 v114, v114, v126
	v_cvt_pk_bf16_f32 v91, v134, v91
	global_store_dwordx4 v[178:179], v[88:91], off offset:3072
	v_pk_mov_b32 v[104:105], v[104:105], v[104:105] op_sel:[1,0]
	v_mul_f32_e32 v114, v114, v120
	v_cvt_pk_bf16_f32 v88, v102, v103
	v_cvt_pk_bf16_f32 v89, v167, v97
	v_cvt_pk_bf16_f32 v90, v151, v146
	v_cvt_pk_bf16_f32 v91, v121, v114
	global_store_dwordx4 v[176:177], v[88:91], off offset:3072
	v_fma_f32 v98, v38, v98, v100
	v_fma_f32 v120, v39, v99, v98
	v_lshlrev_b32_e32 v88, 16, v84
	v_mov_b32_e32 v89, v105
	v_lshlrev_b32_e32 v90, 16, v85
	v_and_b32_e32 v98, 0xffff0000, v85
	v_fma_f32 v85, v40, v88, v101
	v_fma_f32 v121, v41, v89, v85
	v_pk_mov_b32 v[88:89], v[106:107], v[106:107] op_sel:[1,0]
	v_and_b32_e32 v84, 0xffff0000, v84
	v_mov_b32_e32 v85, v89
	v_lshlrev_b32_e32 v100, 16, v86
	v_fma_f32 v84, v48, v84, v96
	v_fma_f32 v106, v49, v85, v84
	v_pk_mov_b32 v[84:85], v[108:109], v[108:109] op_sel:[1,0]
	v_and_b32_e32 v86, 0xffff0000, v86
	v_mov_b32_e32 v91, v85
	v_lshlrev_b32_e32 v102, 16, v87
	v_fma_f32 v85, v42, v90, v164
	v_fma_f32 v107, v43, v91, v85
	v_pk_mov_b32 v[90:91], v[110:111], v[110:111] op_sel:[1,0]
	v_and_b32_e32 v114, 0xffff0000, v87
	v_mov_b32_e32 v99, v91
	v_lshlrev_b32_e32 v105, 16, v92
	v_fma_f32 v85, v50, v98, v152
	v_fma_f32 v108, v51, v99, v85
	v_pk_mov_b32 v[96:97], v[112:113], v[112:113] op_sel:[1,0]
	v_and_b32_e32 v89, 0xffff0000, v92
	v_mov_b32_e32 v101, v97
	v_fma_f32 v85, v44, v100, v148
	v_fma_f32 v109, v45, v101, v85
	v_pk_mov_b32 v[98:99], v[116:117], v[116:117] op_sel:[1,0]
	v_and_b32_e32 v91, 0xffff0000, v93
	v_mov_b32_e32 v87, v99
	v_lshlrev_b32_e32 v97, 16, v94
	v_fma_f32 v85, v52, v86, v144
	v_fma_f32 v110, v53, v87, v85
	v_pk_mov_b32 v[86:87], v[128:129], v[128:129] op_sel:[1,0]
	v_and_b32_e32 v99, 0xffff0000, v94
	v_mov_b32_e32 v103, v87
	v_lshlrev_b32_e32 v87, 16, v95
	v_fma_f32 v85, v46, v102, v132
	v_fma_f32 v111, v47, v103, v85
	v_pk_mov_b32 v[100:101], v[118:119], v[118:119] op_sel:[1,0]
	s_xor_b64 s[2:3], s[56:57], -1
	v_mov_b32_e32 v115, v101
	v_and_b32_e32 v101, 0xffff0000, v95
	v_fma_f32 v85, v54, v114, v120
	v_fma_f32 v112, v55, v115, v85
	v_pk_mul_f32 v[102:103], v[56:57], v[104:105]
	s_mov_b64 s[56:57], 0
	v_fma_f32 v85, v56, v104, v121
	v_fma_f32 v102, v57, v105, v85
	v_fma_f32 v85, v64, v88, v106
	v_fma_f32 v88, v65, v89, v85
	v_lshlrev_b32_e32 v85, 16, v93
	s_nop 0
	v_fma_f32 v84, v58, v84, v107
	v_fma_f32 v89, v59, v85, v84
	s_nop 0
	v_fma_f32 v84, v66, v90, v108
	v_fma_f32 v90, v67, v91, v84
	s_nop 0
	v_fma_f32 v84, v60, v96, v109
	v_fma_f32 v91, v61, v97, v84
	s_nop 0
	v_fma_f32 v84, v68, v98, v110
	v_fma_f32 v92, v69, v99, v84
	v_pk_mul_f32 v[84:85], v[62:63], v[86:87]
	v_mul_f32_e32 v86, 0x3d372713, v102
	v_mul_f32_e32 v86, v102, v86
	v_fma_f32 v86, v102, v86, v102
	v_mul_f32_e32 v86, 0xc0135761, v86
	v_exp_f32_e32 v86, v86
	v_add_f32_e32 v84, v111, v84
	v_add_f32_e32 v87, v84, v85
	v_add_f32_e32 v86, 1.0, v86
	v_rcp_f32_e32 v94, v86
	v_fma_f32 v84, v70, v100, v112
	v_fma_f32 v84, v71, v101, v84
	v_mul_f32_e32 v96, 0x3d372713, v88
	v_mul_f32_e32 v96, v88, v96
	v_fma_f32 v96, v88, v96, v88
	v_mul_f32_e32 v96, 0xc0135761, v96
	v_exp_f32_e32 v96, v96
	v_mul_f32_e32 v85, v102, v94
	v_add_f32_e32 v93, 1.0, v96
	v_rcp_f32_e32 v95, v93
	s_waitcnt vmcnt(3)
; __device__ __forceinline__ unsigned cvt_pk_bf16(float lo, float hi) { unsigned r; asm("v_cvt_pk_bf16_f32 %0, %1, %2" : "=v"(r) : "v"(lo), "v"(hi)); return r; }
; __device__ __forceinline__ float bflo(unsigned w) { return __uint_as_float(w << 16); }
; __device__ __forceinline__ float bfhi(unsigned w) { return __uint_as_float(w & 0xffff0000u); }
; __device__ __forceinline__ float gelu_tanh(float x) { const float u = 0.7978845608028654f * (x + 0.044715f * x * x * x); return x / (1.f + __expf(-2.f * u)); }
; __device__ __forceinline__ void phase_conv(PRef p, int layer, int nseg) {
;     ...
;                 u32x4 o;
;                 o.x = cvt_pk_bf16(gelu_tanh(acc[0]) * bflo(vv[xi].x), gelu_tanh(acc[1]) * bfhi(vv[xi].x));
;                 o.y = cvt_pk_bf16(gelu_tanh(acc[2]) * bflo(vv[xi].y), gelu_tanh(acc[3]) * bfhi(vv[xi].y));
;                 o.z = cvt_pk_bf16(gelu_tanh(acc[4]) * bflo(vv[xi].z), gelu_tanh(acc[5]) * bfhi(vv[xi].z));
;                 o.w = cvt_pk_bf16(gelu_tanh(acc[6]) * bflo(vv[xi].w), gelu_tanh(acc[7]) * bfhi(vv[xi].w));
;                 *(u32x4*)((bf16_t*)lp[1] + (size_t)(xb + xi) * NUP + NFF) = o; } }
	v_lshlrev_b32_e32 v86, 16, v80
	v_mul_f32_e32 v85, v85, v86
	v_and_b32_e32 v80, 0xffff0000, v80
	v_mul_f32_e32 v94, 0x3d372713, v89
	v_mul_f32_e32 v94, v89, v94
	v_fma_f32 v94, v89, v94, v89
	v_mul_f32_e32 v94, 0xc0135761, v94
	v_exp_f32_e32 v94, v94
	v_mul_f32_e32 v86, v88, v95
	v_mul_f32_e32 v80, v86, v80
	v_add_f32_e32 v88, 1.0, v94
	v_rcp_f32_e32 v94, v88
	v_cvt_pk_bf16_f32 v80, v85, v80
	s_nop 0
	v_mul_f32_e32 v95, 0x3d372713, v90
	v_mul_f32_e32 v95, v90, v95
	v_fma_f32 v95, v90, v95, v90
	v_mul_f32_e32 v95, 0xc0135761, v95
	v_exp_f32_e32 v95, v95
	v_mul_f32_e32 v85, v89, v94
	v_add_f32_e32 v86, 1.0, v95
	v_rcp_f32_e32 v94, v86
	v_lshlrev_b32_e32 v88, 16, v81
	v_mul_f32_e32 v85, v85, v88
	v_and_b32_e32 v81, 0xffff0000, v81
	v_mul_f32_e32 v93, 0x3d372713, v91
	v_mul_f32_e32 v93, v91, v93
	v_fma_f32 v93, v91, v93, v91
	v_mul_f32_e32 v93, 0xc0135761, v93
	v_exp_f32_e32 v93, v93
	v_mul_f32_e32 v86, v90, v94
	v_mul_f32_e32 v81, v86, v81
	v_add_f32_e32 v88, 1.0, v93
	v_rcp_f32_e32 v90, v88
	v_cvt_pk_bf16_f32 v81, v85, v81
	s_nop 0
	v_mul_f32_e32 v93, 0x3d372713, v92
	v_mul_f32_e32 v93, v92, v93
	v_fma_f32 v93, v92, v93, v92
	v_mul_f32_e32 v93, 0xc0135761, v93
	v_exp_f32_e32 v93, v93
	v_mul_f32_e32 v85, v91, v90
	v_add_f32_e32 v86, 1.0, v93
	v_rcp_f32_e32 v90, v86
	v_lshlrev_b32_e32 v88, 16, v82
	v_mul_f32_e32 v85, v85, v88
	v_and_b32_e32 v82, 0xffff0000, v82
	v_mul_f32_e32 v89, 0x3d372713, v87
	v_mul_f32_e32 v89, v87, v89
	v_fma_f32 v89, v87, v89, v87
	v_mul_f32_e32 v89, 0xc0135761, v89
	v_exp_f32_e32 v89, v89
	v_mul_f32_e32 v86, v92, v90
	v_mul_f32_e32 v82, v86, v82
	v_add_f32_e32 v88, 1.0, v89
	v_rcp_f32_e32 v90, v88
	v_cvt_pk_bf16_f32 v82, v85, v82
	s_nop 0
	v_mul_f32_e32 v91, 0x3d372713, v84
	v_mul_f32_e32 v91, v84, v91
	v_fma_f32 v91, v84, v91, v84
	v_mul_f32_e32 v91, 0xc0135761, v91
	v_exp_f32_e32 v91, v91
	v_mul_f32_e32 v85, v87, v90
	v_add_f32_e32 v86, 1.0, v91
	v_rcp_f32_e32 v90, v86
	v_lshlrev_b32_e32 v87, 16, v83
	v_mul_f32_e32 v85, v85, v87
	v_and_b32_e32 v83, 0xffff0000, v83
	v_mul_f32_e32 v84, v84, v90
	v_mul_f32_e32 v83, v84, v83
	s_mov_b32 s4, 4
	s_and_b64 vcc, exec, s[2:3]
	v_cvt_pk_bf16_f32 v83, v85, v83
	global_store_dwordx4 v[174:175], v[80:83], off offset:3072
	s_cbranch_vccnz .LBB0_545

; __device__ __forceinline__ unsigned cvt_pk_bf16(float lo, float hi) { unsigned r; asm("v_cvt_pk_bf16_f32 %0, %1, %2" : "=v"(r) : "v"(lo), "v"(hi)); return r; }
; __device__ __forceinline__ void s5out_item(PRef p, int layer, int item, unsigned char* shm) {
;     ...
;     for (int nt = 0; nt < (layer == 1 ? 4 : 5); ++nt) {
;         __syncthreads();
;         s5_stage_u(A, ul, b, g, nt, tid);
;         __syncthreads();
;         f32x4 acc[4];
; #pragma unroll
;         for (int mi = 0; mi < 4; ++mi) acc[mi] = (f32x4){0.f, 0.f, 0.f, 0.f};
; #pragma unroll 4
;         for (int kk = 0; kk < 32; ++kk) {
;             const bf16x8 bfr = *(const bf16x8*)(ul + fr * S5_UP + kk * 64 + fq * 16);
;             const int sq = 2 * kk + (fq >> 1);
; #pragma unroll
;             for (int mi = 0; mi < 4; ++mi) { const bf16x8 af = *(const bf16x8*)(KT + (tb + mi - sq + 63) * 256 + fr * 16 + (fq & 1) * 8);
;                 acc[mi] = __builtin_amdgcn_mfma_f32_16x16x32_bf16(af, bfr, acc[mi], 0, 0, 0); } }
;         const int cidx = nt < 4 ? 4 + 16 * nt + fr : (fr & 3);
; #pragma unroll
;         for (int dir = 0; dir < 2; ++dir) {
;             const bf16_t* G = (const bf16_t*)(p.ws + O_S5G) + (size_t)(dir * 32 + g) * 1024 * 128;
;             const float* ST = (const float*)(p.ws + O_S5ST) + (size_t)((g * 2 + dir) * 4 + b) * 68 * 128 + (size_t)cidx * 128;
; #pragma unroll
;             for (int kk = 0; kk < 4; ++kk) {
;                 const f32x4 x0 = *(const f32x4*)(ST + kk * 32 + fq * 8), x1 = *(const f32x4*)(ST + kk * 32 + fq * 8 + 4);
;                 u32x4 w; w.x = cvt_pk_bf16(x0[0], x0[1]); w.y = cvt_pk_bf16(x0[2], x0[3]); w.z = cvt_pk_bf16(x1[0], x1[1]); w.w = cvt_pk_bf16(x1[2], x1[3]);
;                 const bf16x8 bfr = mk8(w);
; #pragma unroll
;                 for (int mi = 0; mi < 4; ++mi) { const bf16x8 af = *(const bf16x8*)(G + (size_t)((tb + mi) * 16 + fr) * 128 + kk * 32 + fq * 8);
;                     acc[mi] = __builtin_amdgcn_mfma_f32_16x16x32_bf16(af, bfr, acc[mi], 0, 0, 0); } } }
.LBB0_929:
	v_add_u32_e32 v21, s62, v87
	ds_read_b128 v[22:25], v20
	ds_read_b128 v[26:29], v20 offset:64
	ds_read_b128 v[54:57], v21 offset:32256
	ds_read_b128 v[58:61], v21 offset:32768
	ds_read_b128 v[96:99], v21 offset:31744
	ds_read_b128 v[100:103], v21 offset:33280
	s_waitcnt lgkmcnt(3)
	v_mfma_f32_16x16x32_bf16 v[16:19], v[54:57], v[22:25], v[16:19]
	s_addk_i32 s62, 0xf000
	s_cmpk_lg_i32 s62, 0x8000
	s_waitcnt lgkmcnt(2)
	v_mfma_f32_16x16x32_bf16 v[12:15], v[58:61], v[22:25], v[12:15]
	s_waitcnt lgkmcnt(0)
	v_mfma_f32_16x16x32_bf16 v[8:11], v[100:103], v[22:25], v[8:11]
	ds_read_b128 v[100:103], v21 offset:33792
	ds_read_b128 v[104:107], v21 offset:29184
	s_waitcnt lgkmcnt(1)
	v_mfma_f32_16x16x32_bf16 v[4:7], v[100:103], v[22:25], v[4:7]
	ds_read_b128 v[22:25], v21 offset:31232
	ds_read_b128 v[100:103], v21 offset:30720
	s_waitcnt lgkmcnt(1)
	v_mfma_f32_16x16x32_bf16 v[16:19], v[22:25], v[26:29], v[16:19]
	v_mfma_f32_16x16x32_bf16 v[12:15], v[96:99], v[26:29], v[12:15]
	v_mfma_f32_16x16x32_bf16 v[8:11], v[54:57], v[26:29], v[8:11]
	ds_read_b128 v[54:57], v20 offset:128
	ds_read_b128 v[108:111], v20 offset:192
	v_add_u32_e32 v20, 0x100, v20
	v_mfma_f32_16x16x32_bf16 v[4:7], v[58:61], v[26:29], v[4:7]
	ds_read_b128 v[26:29], v21 offset:30208
	ds_read_b128 v[58:61], v21 offset:29696
	s_waitcnt lgkmcnt(1)
	v_mfma_f32_16x16x32_bf16 v[16:19], v[26:29], v[54:57], v[16:19]
	v_mfma_f32_16x16x32_bf16 v[12:15], v[100:103], v[54:57], v[12:15]
	v_mfma_f32_16x16x32_bf16 v[8:11], v[22:25], v[54:57], v[8:11]
	v_mfma_f32_16x16x32_bf16 v[4:7], v[96:99], v[54:57], v[4:7]
	v_mfma_f32_16x16x32_bf16 v[16:19], v[104:107], v[108:111], v[16:19]
	s_waitcnt lgkmcnt(0)
	v_mfma_f32_16x16x32_bf16 v[12:15], v[58:61], v[108:111], v[12:15]
	v_mfma_f32_16x16x32_bf16 v[8:11], v[26:29], v[108:111], v[8:11]
	v_mfma_f32_16x16x32_bf16 v[4:7], v[100:103], v[108:111], v[4:7]
	s_cbranch_scc1 .LBB0_929
	v_lshl_add_u32 v20, s20, 4, v81
	v_mov_b32_e32 v21, v33
	v_lshlrev_b64 v[20:21], 9, v[20:21]
	v_lshl_add_u64 v[124:125], v[34:35], 0, v[20:21]
	v_lshl_add_u64 v[126:127], v[124:125], 0, s[36:37]
	global_load_dwordx4 v[20:23], v[38:39], off
	global_load_dwordx4 v[24:27], v[126:127], off
	global_load_dwordx4 v[28:31], v[126:127], off offset:16
	global_load_dwordx4 v[54:57], v[40:41], off
	global_load_dwordx4 v[58:61], v[42:43], off
	global_load_dwordx4 v[96:99], v[44:45], off
	global_load_dwordx4 v[100:103], v[126:127], off offset:128
	global_load_dwordx4 v[104:107], v[38:39], off offset:64
	global_load_dwordx4 v[108:111], v[126:127], off offset:144
	global_load_dwordx4 v[112:115], v[40:41], off offset:64
	v_lshl_add_u64 v[124:125], v[124:125], 0, s[38:39]
	s_add_i32 s20, s20, 1
	s_cmp_lg_u32 s20, 4
	s_waitcnt vmcnt(8)
	v_cvt_pk_bf16_f32 v24, v24, v25
	v_cvt_pk_bf16_f32 v25, v26, v27
	s_waitcnt vmcnt(7)
	v_cvt_pk_bf16_f32 v26, v28, v29
	v_cvt_pk_bf16_f32 v27, v30, v31
	s_waitcnt vmcnt(3)
	v_cvt_pk_bf16_f32 v100, v100, v101
	v_mfma_f32_16x16x32_bf16 v[16:19], v[20:23], v[24:27], v[16:19]
	global_load_dwordx4 v[20:23], v[42:43], off offset:64
	v_cvt_pk_bf16_f32 v101, v102, v103
	s_waitcnt vmcnt(2)
	v_cvt_pk_bf16_f32 v102, v108, v109
	v_mfma_f32_16x16x32_bf16 v[12:15], v[54:57], v[24:27], v[12:15]
	global_load_dwordx4 v[28:31], v[44:45], off offset:64
	global_load_dwordx4 v[54:57], v[126:127], off offset:256
	global_load_dwordx4 v[116:119], v[38:39], off offset:128
	v_cvt_pk_bf16_f32 v103, v110, v111
	s_waitcnt vmcnt(1)
	v_cvt_pk_bf16_f32 v54, v54, v55
	v_mfma_f32_16x16x32_bf16 v[8:11], v[58:61], v[24:27], v[8:11]
	global_load_dwordx4 v[58:61], v[126:127], off offset:272
	global_load_dwordx4 v[120:123], v[40:41], off offset:128
	v_cvt_pk_bf16_f32 v55, v56, v57
	s_waitcnt vmcnt(1)
	v_cvt_pk_bf16_f32 v56, v58, v59
	v_mfma_f32_16x16x32_bf16 v[4:7], v[96:99], v[24:27], v[4:7]
	global_load_dwordx4 v[24:27], v[42:43], off offset:128
	v_cvt_pk_bf16_f32 v57, v60, v61
	v_mfma_f32_16x16x32_bf16 v[16:19], v[104:107], v[100:103], v[16:19]
	global_load_dwordx4 v[96:99], v[44:45], off offset:128
	global_load_dwordx4 v[104:107], v[126:127], off offset:384
	global_load_dwordx4 v[108:111], v[38:39], off offset:192
	s_waitcnt vmcnt(1)
	v_cvt_pk_bf16_f32 v104, v104, v105
	v_mfma_f32_16x16x32_bf16 v[12:15], v[112:115], v[100:103], v[12:15]
	v_cvt_pk_bf16_f32 v105, v106, v107
	v_mfma_f32_16x16x32_bf16 v[8:11], v[20:23], v[100:103], v[8:11]
	global_load_dwordx4 v[20:23], v[126:127], off offset:400
	global_load_dwordx4 v[112:115], v[40:41], off offset:192
	s_waitcnt vmcnt(1)
	v_cvt_pk_bf16_f32 v106, v20, v21
	v_mfma_f32_16x16x32_bf16 v[4:7], v[28:31], v[100:103], v[4:7]
	global_load_dwordx4 v[28:31], v[42:43], off offset:192
	global_load_dwordx4 v[58:61], v[44:45], off offset:192
	v_cvt_pk_bf16_f32 v107, v22, v23
	v_mfma_f32_16x16x32_bf16 v[16:19], v[116:119], v[54:57], v[16:19]
	global_load_dwordx4 v[100:103], v[124:125], off
	global_load_dwordx4 v[116:119], v[46:47], off
	s_waitcnt vmcnt(1)
	v_cvt_pk_bf16_f32 v100, v100, v101
	v_mfma_f32_16x16x32_bf16 v[12:15], v[120:123], v[54:57], v[12:15]
	v_cvt_pk_bf16_f32 v101, v102, v103
	v_mfma_f32_16x16x32_bf16 v[8:11], v[24:27], v[54:57], v[8:11]
	global_load_dwordx4 v[24:27], v[124:125], off offset:16
	global_load_dwordx4 v[120:123], v[48:49], off
	global_load_dwordx4 v[20:23], v[50:51], off
	s_waitcnt vmcnt(2)
	v_cvt_pk_bf16_f32 v102, v24, v25
	v_mfma_f32_16x16x32_bf16 v[4:7], v[96:99], v[54:57], v[4:7]
	v_cvt_pk_bf16_f32 v103, v26, v27
	v_mfma_f32_16x16x32_bf16 v[16:19], v[108:111], v[104:107], v[16:19]
	global_load_dwordx4 v[54:57], v[52:53], off
	global_load_dwordx4 v[96:99], v[124:125], off offset:128
	global_load_dwordx4 v[108:111], v[46:47], off offset:64
	global_load_dwordx4 v[24:27], v[48:49], off offset:64
	s_waitcnt vmcnt(2)
; __device__ __forceinline__ unsigned cvt_pk_bf16(float lo, float hi) { unsigned r; asm("v_cvt_pk_bf16_f32 %0, %1, %2" : "=v"(r) : "v"(lo), "v"(hi)); return r; }
; __device__ __forceinline__ float bflo(unsigned w) { return __uint_as_float(w << 16); }
; __device__ __forceinline__ float bfhi(unsigned w) { return __uint_as_float(w & 0xffff0000u); }
; __device__ __forceinline__ float gelu_tanh(float x) { const float u = 0.7978845608028654f * (x + 0.044715f * x * x * x); return x / (1.f + __expf(-2.f * u)); }
; __device__ __forceinline__ void s5out_item(PRef p, int layer, int item, unsigned char* shm) {
;     ...
;         for (int dir = 0; dir < 2; ++dir) {
;             const bf16_t* G = (const bf16_t*)(p.ws + O_S5G) + (size_t)(dir * 32 + g) * 1024 * 128;
;             const float* ST = (const float*)(p.ws + O_S5ST) + (size_t)((g * 2 + dir) * 4 + b) * 68 * 128 + (size_t)cidx * 128;
; #pragma unroll
;             for (int kk = 0; kk < 4; ++kk) {
;                 const f32x4 x0 = *(const f32x4*)(ST + kk * 32 + fq * 8), x1 = *(const f32x4*)(ST + kk * 32 + fq * 8 + 4);
;                 u32x4 w; w.x = cvt_pk_bf16(x0[0], x0[1]); w.y = cvt_pk_bf16(x0[2], x0[3]); w.z = cvt_pk_bf16(x1[0], x1[1]); w.w = cvt_pk_bf16(x1[2], x1[3]);
;                 const bf16x8 bfr = mk8(w);
; #pragma unroll
;                 for (int mi = 0; mi < 4; ++mi) { const bf16x8 af = *(const bf16x8*)(G + (size_t)((tb + mi) * 16 + fr) * 128 + kk * 32 + fq * 8);
;                     acc[mi] = __builtin_amdgcn_mfma_f32_16x16x32_bf16(af, bfr, acc[mi], 0, 0, 0); } } }
;         if (nt < 4 || fr < 4) {
; #pragma unroll
;             for (int mi = 0; mi < 4; ++mi) { const int t = tb + mi; const size_t row = nt < 4 ? (size_t)(b * 4096 + (16 * nt + fr) * 64 + t) : (size_t)(RL + b * 256 + fr * 64 + t);
;                 const u32x2 uu = *(const u32x2*)(ul + fr * S5_UP + t * 32 + fq * 8);
;                 const f32x4 y = acc[mi];
;                 u32x2 w; w.x = cvt_pk_bf16(gelu_tanh(y[0] + dv[0] * bflo(uu.x)), gelu_tanh(y[1] + dv[1] * bfhi(uu.x)));
;                 w.y = cvt_pk_bf16(gelu_tanh(y[2] + dv[2] * bflo(uu.y)), gelu_tanh(y[3] + dv[3] * bfhi(uu.y)));
;                 *(u32x2*)(Z + row * 512 + g * 16 + fq * 4) = w; } }
	v_cvt_pk_bf16_f32 v96, v96, v97
	v_mfma_f32_16x16x32_bf16 v[8:11], v[28:31], v[104:107], v[8:11]
	global_load_dwordx4 v[28:31], v[124:125], off offset:144
	v_cvt_pk_bf16_f32 v97, v98, v99
	s_waitcnt vmcnt(0)
	v_cvt_pk_bf16_f32 v98, v28, v29
	v_mfma_f32_16x16x32_bf16 v[12:15], v[112:115], v[104:107], v[12:15]
	v_cvt_pk_bf16_f32 v99, v30, v31
	v_mfma_f32_16x16x32_bf16 v[4:7], v[58:61], v[104:107], v[4:7]
	global_load_dwordx4 v[58:61], v[50:51], off offset:64
	global_load_dwordx4 v[104:107], v[52:53], off offset:64
	global_load_dwordx4 v[112:115], v[46:47], off offset:128
	v_mfma_f32_16x16x32_bf16 v[16:19], v[116:119], v[100:103], v[16:19]
	v_mfma_f32_16x16x32_bf16 v[8:11], v[20:23], v[100:103], v[8:11]
	global_load_dwordx4 v[20:23], v[124:125], off offset:272
	global_load_dwordx4 v[116:119], v[124:125], off offset:256
	global_load_dwordx4 v[28:31], v[48:49], off offset:128
	s_waitcnt vmcnt(1)
	v_cvt_pk_bf16_f32 v116, v116, v117
	v_mfma_f32_16x16x32_bf16 v[12:15], v[120:123], v[100:103], v[12:15]
	v_cvt_pk_bf16_f32 v117, v118, v119
	v_cvt_pk_bf16_f32 v118, v20, v21
	v_cvt_pk_bf16_f32 v119, v22, v23
	v_mfma_f32_16x16x32_bf16 v[4:7], v[54:57], v[100:103], v[4:7]
	v_mfma_f32_16x16x32_bf16 v[16:19], v[108:111], v[96:99], v[16:19]
	global_load_dwordx4 v[54:57], v[50:51], off offset:128
	global_load_dwordx4 v[100:103], v[52:53], off offset:128
	global_load_dwordx4 v[108:111], v[46:47], off offset:192
	v_mfma_f32_16x16x32_bf16 v[8:11], v[58:61], v[96:99], v[8:11]
	global_load_dwordx4 v[58:61], v[124:125], off offset:400
	global_load_dwordx4 v[120:123], v[124:125], off offset:384
	v_mfma_f32_16x16x32_bf16 v[12:15], v[24:27], v[96:99], v[12:15]
	global_load_dwordx4 v[24:27], v[50:51], off offset:192
	v_mfma_f32_16x16x32_bf16 v[4:7], v[104:107], v[96:99], v[4:7]
	global_load_dwordx4 v[104:107], v[48:49], off offset:192
	v_mfma_f32_16x16x32_bf16 v[96:99], v[112:115], v[116:119], v[16:19]
	s_waitcnt vmcnt(2)
	v_cvt_pk_bf16_f32 v16, v120, v121
	v_mfma_f32_16x16x32_bf16 v[112:115], v[28:31], v[116:119], v[12:15]
	v_cvt_pk_bf16_f32 v17, v122, v123
	v_cvt_pk_bf16_f32 v18, v58, v59
	v_cvt_pk_bf16_f32 v19, v60, v61
	v_mfma_f32_16x16x32_bf16 v[28:31], v[54:57], v[116:119], v[8:11]
	ds_read_b64 v[54:55], v92 offset:65024
	s_nop 0
	global_load_dwordx4 v[12:15], v[52:53], off offset:192
	ds_read_b64 v[56:57], v93 offset:65024
	ds_read_b64 v[60:61], v94 offset:65024
	ds_read_b64 v[58:59], v95 offset:65024
	v_mfma_f32_16x16x32_bf16 v[8:11], v[108:111], v[16:19], v[96:99]
	s_waitcnt lgkmcnt(3)
	s_nop 1
	v_lshlrev_b32_e32 v96, 16, v54
	s_waitcnt vmcnt(2)
	v_mfma_f32_16x16x32_bf16 v[24:27], v[24:27], v[16:19], v[28:31]
	s_nop 1
	v_fma_f32 v8, v0, v96, v8
	v_mul_f32_e32 v28, 0x3d372713, v8
	v_mul_f32_e32 v28, v8, v28
	v_fma_f32 v28, v8, v28, v8
	v_mul_f32_e32 v28, 0xc0135761, v28
	v_mfma_f32_16x16x32_bf16 v[20:23], v[100:103], v[116:119], v[4:7]
	v_exp_f32_e32 v28, v28
	s_waitcnt vmcnt(1)
	v_mfma_f32_16x16x32_bf16 v[4:7], v[104:107], v[16:19], v[112:115]
	s_waitcnt vmcnt(0)
	v_mfma_f32_16x16x32_bf16 v[12:15], v[12:15], v[16:19], v[20:23]
	v_add_f32_e32 v18, 1.0, v28
	v_and_b32_e32 v28, 0xffff0000, v54
	v_fma_f32 v9, v1, v28, v9
	v_mul_f32_e32 v28, 0x3d372713, v9
	v_rcp_f32_e32 v20, v18
	v_mul_f32_e32 v28, v9, v28
	v_fma_f32 v28, v9, v28, v9
	v_mul_f32_e32 v28, 0xc0135761, v28
	v_exp_f32_e32 v28, v28
	s_nop 0
	v_add_f32_e32 v22, 1.0, v28
	v_rcp_f32_e32 v29, v22
	v_mul_f32_e32 v19, v8, v20
	v_lshlrev_b32_e32 v20, 16, v55
	v_fma_f32 v10, v2, v20, v10
	v_mul_f32_e32 v20, 0x3d372713, v10
	v_mov_b32_e32 v8, v19
	v_mul_f32_e32 v20, v10, v20
	v_fma_f32 v20, v10, v20, v10
	v_mul_f32_e32 v20, 0xc0135761, v20
	v_exp_f32_e32 v20, v20
	v_and_b32_e32 v19, 0xffff0000, v55
	v_fmac_f32_e32 v11, v3, v19
	v_mul_f32_e32 v19, 0x3d372713, v11
	v_add_f32_e32 v20, 1.0, v20
	v_mul_f32_e32 v19, v11, v19
	v_fma_f32 v19, v11, v19, v11
	v_rcp_f32_e32 v28, v20
	v_mul_f32_e32 v19, 0xc0135761, v19
	v_mul_f32_e32 v9, v9, v29
	v_exp_f32_e32 v19, v19
	v_cvt_pk_bf16_f32 v8, v8, v9
	v_add_f32_e32 v19, 1.0, v19
	v_rcp_f32_e32 v23, v19
	v_mul_f32_e32 v9, v10, v28
	v_add_u32_e32 v21, s12, v82
	v_mul_f32_e32 v10, v11, v23
	s_waitcnt lgkmcnt(2)
; __device__ __forceinline__ unsigned cvt_pk_bf16(float lo, float hi) { unsigned r; asm("v_cvt_pk_bf16_f32 %0, %1, %2" : "=v"(r) : "v"(lo), "v"(hi)); return r; }
; __device__ __forceinline__ float bflo(unsigned w) { return __uint_as_float(w << 16); }
; __device__ __forceinline__ float bfhi(unsigned w) { return __uint_as_float(w & 0xffff0000u); }
; __device__ __forceinline__ float gelu_tanh(float x) { const float u = 0.7978845608028654f * (x + 0.044715f * x * x * x); return x / (1.f + __expf(-2.f * u)); }
; __device__ __forceinline__ void s5out_item(PRef p, int layer, int item, unsigned char* shm) {
;     ...
;         if (nt < 4 || fr < 4) {
; #pragma unroll
;             for (int mi = 0; mi < 4; ++mi) { const int t = tb + mi; const size_t row = nt < 4 ? (size_t)(b * 4096 + (16 * nt + fr) * 64 + t) : (size_t)(RL + b * 256 + fr * 64 + t);
;                 const u32x2 uu = *(const u32x2*)(ul + fr * S5_UP + t * 32 + fq * 8);
;                 const f32x4 y = acc[mi];
;                 u32x2 w; w.x = cvt_pk_bf16(gelu_tanh(y[0] + dv[0] * bflo(uu.x)), gelu_tanh(y[1] + dv[1] * bfhi(uu.x)));
;                 w.y = cvt_pk_bf16(gelu_tanh(y[2] + dv[2] * bflo(uu.y)), gelu_tanh(y[3] + dv[3] * bfhi(uu.y)));
;                 *(u32x2*)(Z + row * 512 + g * 16 + fq * 4) = w; } }
	v_lshlrev_b32_e32 v11, 16, v56
	v_fma_f32 v4, v0, v11, v4
	v_mul_f32_e32 v11, 0x3d372713, v4
	v_mul_f32_e32 v11, v4, v11
	v_fma_f32 v11, v4, v11, v4
	v_mul_f32_e32 v11, 0xc0135761, v11
	v_exp_f32_e32 v18, v11
	v_add_u32_e32 v16, v21, v75
	v_ashrrev_i32_e32 v17, 31, v16
	v_and_b32_e32 v19, 0xffff0000, v56
	v_cvt_pk_bf16_f32 v9, v9, v10
	v_lshlrev_b64 v[10:11], 10, v[16:17]
	v_add_f32_e32 v16, 1.0, v18
	v_fma_f32 v5, v1, v19, v5
	v_mul_f32_e32 v19, 0x3d372713, v5
	v_rcp_f32_e32 v18, v16
	v_mul_f32_e32 v19, v5, v19
	v_fma_f32 v19, v5, v19, v5
	v_mul_f32_e32 v19, 0xc0135761, v19
	v_lshl_add_u64 v[10:11], v[36:37], 0, v[10:11]
	global_store_dwordx2 v[10:11], v[8:9], off
	v_exp_f32_e32 v19, v19
	s_nop 0
	v_add_f32_e32 v17, 1.0, v19
	v_rcp_f32_e32 v20, v17
	v_mul_f32_e32 v4, v4, v18
	v_lshlrev_b32_e32 v16, 16, v57
	v_fma_f32 v6, v2, v16, v6
	v_mul_f32_e32 v16, 0x3d372713, v6
	v_mul_f32_e32 v16, v6, v16
	v_fma_f32 v16, v6, v16, v6
	v_mul_f32_e32 v16, 0xc0135761, v16
	v_exp_f32_e32 v16, v16
	v_and_b32_e32 v11, 0xffff0000, v57
	v_fmac_f32_e32 v7, v3, v11
	v_mul_f32_e32 v11, 0x3d372713, v7
	v_add_f32_e32 v16, 1.0, v16
	v_mul_f32_e32 v11, v7, v11
	v_fma_f32 v11, v7, v11, v7
	v_rcp_f32_e32 v19, v16
	v_mul_f32_e32 v11, 0xc0135761, v11
	v_mul_f32_e32 v5, v5, v20
	v_exp_f32_e32 v11, v11
	v_cvt_pk_bf16_f32 v4, v4, v5
	v_add_f32_e32 v11, 1.0, v11
	v_rcp_f32_e32 v18, v11
	v_mul_f32_e32 v5, v6, v19
	v_add_u32_e32 v8, v21, v83
	v_mul_f32_e32 v6, v7, v18
	s_waitcnt lgkmcnt(1)
	v_lshlrev_b32_e32 v7, 16, v60
	v_fma_f32 v10, v0, v7, v24
	v_mul_f32_e32 v7, 0x3d372713, v10
	v_mul_f32_e32 v7, v10, v7
	v_fma_f32 v7, v10, v7, v10
	v_mul_f32_e32 v7, 0xc0135761, v7
	v_exp_f32_e32 v11, v7
	v_ashrrev_i32_e32 v9, 31, v8
	v_and_b32_e32 v16, 0xffff0000, v60
	v_cvt_pk_bf16_f32 v5, v5, v6
	v_lshlrev_b64 v[6:7], 10, v[8:9]
	v_add_f32_e32 v8, 1.0, v11
	v_fma_f32 v16, v1, v16, v25
	v_mul_f32_e32 v17, 0x3d372713, v16
	v_rcp_f32_e32 v11, v8
	v_mul_f32_e32 v17, v16, v17
	v_fma_f32 v17, v16, v17, v16
	v_mul_f32_e32 v17, 0xc0135761, v17
	v_lshl_add_u64 v[6:7], v[36:37], 0, v[6:7]
	global_store_dwordx2 v[6:7], v[4:5], off
	v_exp_f32_e32 v17, v17
	s_nop 0
	v_add_f32_e32 v9, 1.0, v17
	v_rcp_f32_e32 v18, v9
	v_mul_f32_e32 v6, v10, v11
	v_lshlrev_b32_e32 v10, 16, v61
	v_fma_f32 v10, v2, v10, v26
	v_mul_f32_e32 v11, 0x3d372713, v10
	v_mul_f32_e32 v11, v10, v11
	v_fma_f32 v11, v10, v11, v10
	v_mul_f32_e32 v11, 0xc0135761, v11
	v_exp_f32_e32 v11, v11
	v_mul_f32_e32 v7, v16, v18
	v_and_b32_e32 v9, 0xffff0000, v61
	v_fmac_f32_e32 v27, v3, v9
	v_mul_f32_e32 v9, 0x3d372713, v27
	v_add_f32_e32 v11, 1.0, v11
	v_mul_f32_e32 v9, v27, v9
	v_fma_f32 v9, v27, v9, v27
	v_rcp_f32_e32 v19, v11
	v_mul_f32_e32 v9, 0xc0135761, v9
	v_exp_f32_e32 v9, v9
	v_cvt_pk_bf16_f32 v6, v6, v7
	v_add_f32_e32 v9, 1.0, v9
	v_rcp_f32_e32 v17, v9
	v_mul_f32_e32 v7, v10, v19
	v_add_u32_e32 v4, v21, v84
	v_mul_f32_e32 v8, v27, v17
	s_waitcnt lgkmcnt(0)
	v_lshlrev_b32_e32 v9, 16, v58
	v_fma_f32 v9, v0, v9, v12
	v_mul_f32_e32 v10, 0x3d372713, v9
	v_mul_f32_e32 v10, v9, v10
	v_fma_f32 v10, v9, v10, v9
	v_mul_f32_e32 v10, 0xc0135761, v10
	v_exp_f32_e32 v10, v10
	v_and_b32_e32 v12, 0xffff0000, v58
	v_cvt_pk_bf16_f32 v7, v7, v8
	v_fma_f32 v12, v1, v12, v13
	v_add_f32_e32 v8, 1.0, v10
	v_mul_f32_e32 v13, 0x3d372713, v12
	v_rcp_f32_e32 v11, v8
	v_mul_f32_e32 v13, v12, v13
	v_ashrrev_i32_e32 v5, 31, v4
	v_fma_f32 v13, v12, v13, v12
	v_lshlrev_b64 v[4:5], 10, v[4:5]
	v_mul_f32_e32 v13, 0xc0135761, v13
	v_lshl_add_u64 v[4:5], v[36:37], 0, v[4:5]
	global_store_dwordx2 v[4:5], v[6:7], off
	v_exp_f32_e32 v13, v13
	s_nop 0
	v_add_f32_e32 v10, 1.0, v13
	v_rcp_f32_e32 v16, v10
	v_mul_f32_e32 v6, v9, v11
	v_lshlrev_b32_e32 v9, 16, v59
	v_fma_f32 v9, v2, v9, v14
	v_mul_f32_e32 v11, 0x3d372713, v9
	v_mul_f32_e32 v11, v9, v11
	v_fma_f32 v11, v9, v11, v9
	v_mul_f32_e32 v11, 0xc0135761, v11
	v_exp_f32_e32 v11, v11
	v_mul_f32_e32 v7, v12, v16
	v_and_b32_e32 v10, 0xffff0000, v59
	v_fmac_f32_e32 v15, v3, v10
	v_mul_f32_e32 v10, 0x3d372713, v15
	v_add_f32_e32 v11, 1.0, v11
	v_mul_f32_e32 v10, v15, v10
	v_fma_f32 v10, v15, v10, v15
	v_rcp_f32_e32 v14, v11
	v_mul_f32_e32 v10, 0xc0135761, v10
	v_exp_f32_e32 v10, v10
	v_cvt_pk_bf16_f32 v6, v6, v7
	v_add_f32_e32 v10, 1.0, v10
	v_rcp_f32_e32 v13, v10
	v_mul_f32_e32 v7, v9, v14
	v_add_u32_e32 v4, v21, v85
	v_ashrrev_i32_e32 v5, 31, v4
	v_lshlrev_b64 v[4:5], 10, v[4:5]
	v_lshl_add_u64 v[4:5], v[36:37], 0, v[4:5]
	v_mul_f32_e32 v8, v15, v13
	v_cvt_pk_bf16_f32 v7, v7, v8
	global_store_dwordx2 v[4:5], v[6:7], off
	s_cbranch_scc1 .LBB0_928
	s_barrier
	s_branch .LBB0_918

; __device__ __forceinline__ void phase_conv(PRef p, int layer, int nseg) {
;     ...
;     for (int it = blockIdx.x; it < nseg * 11; it += gridDim.x) {
;         const int seg = it / 11, f = (it % 11) * 512 + fg * 8;
;         const bool isc = seg >= 256;
;         float w[9][8], bias[8];
; #pragma unroll
;         for (int k = 0; k < 9; ++k) { const float4 a = *(const float4*)(CW + (size_t)k * NFF + f), bq = *(const float4*)(CW + (size_t)k * NFF + f + 4);
;             w[k][0] = a.x; w[k][1] = a.y; w[k][2] = a.z; w[k][3] = a.w; w[k][4] = bq.x; w[k][5] = bq.y; w[k][6] = bq.z; w[k][7] = bq.w; }
;         { const float4 a = *(const float4*)(CB + f), bq = *(const float4*)(CB + f + 4); bias[0] = a.x; bias[1] = a.y; bias[2] = a.z; bias[3] = a.w; bias[4] = bq.x; bias[5] = bq.y; bias[6] = bq.z; bias[7] = bq.w; }
;         int W, x0; const bf16_t* lp[3]; bool lv[3];
;         if (!isc) { const int b = seg >> 6, r = seg & 63; W = 64; x0 = 8 * xs;
; #pragma unroll
;             for (int ky = 0; ky < 3; ++ky) { const int yy = r + ky - 1; lv[ky] = (yy >= 0) && (yy < 64); lp[ky] = GV + ((size_t)b * 4096 + (size_t)(lv[ky] ? yy : r) * 64) * NUP + f; } }
.LBB0_1041:
	s_and_b32 s6, s84, 7
	s_lshl_b32 s6, s6, 5
	s_lshr_b32 s8, s84, 3
	s_add_i32 s8, s8, s6
	s_lshr_b32 s6, s52, 8
	v_lshl_or_b32 v80, s6, 9, v224
	v_ashrrev_i32_e32 v81, 31, v80
	v_lshlrev_b64 v[40:41], 2, v[80:81]
	v_lshl_add_u64 v[36:37], s[16:17], 0, v[40:41]
	v_add_co_u32_e32 v2, vcc, s13, v36
	v_lshl_add_u64 v[0:1], v[36:37], 0, s[10:11]
	s_nop 0
	v_addc_co_u32_e32 v3, vcc, 0, v37, vcc
	v_add_co_u32_e32 v16, vcc, s14, v36
	global_load_dwordx4 v[48:51], v[2:3], off offset:2048
	global_load_dwordx4 v[52:55], v[0:1], off offset:16
	v_addc_co_u32_e32 v17, vcc, 0, v37, vcc
	v_add_co_u32_e32 v2, vcc, s28, v36
	v_lshl_add_u64 v[0:1], v[36:37], 0, s[22:23]
	s_nop 0
	v_addc_co_u32_e32 v3, vcc, 0, v37, vcc
	v_add_co_u32_e32 v8, vcc, s29, v36
	global_load_dwordx4 v[56:59], v[2:3], off offset:2048
	global_load_dwordx4 v[60:63], v[0:1], off offset:16
	s_mov_b64 s[6:7], vcc
	v_add_co_u32_e32 v2, vcc, s33, v36
	v_lshl_add_u64 v[0:1], v[36:37], 0, s[26:27]
	s_nop 0
	v_addc_co_u32_e32 v3, vcc, 0, v37, vcc
	v_addc_co_u32_e64 v9, vcc, 0, v37, s[6:7]
	v_add_co_u32_e32 v28, vcc, s48, v36
	global_load_dwordx4 v[64:67], v[2:3], off offset:2048
	global_load_dwordx4 v[68:71], v[0:1], off offset:16
	v_lshl_add_u64 v[0:1], v[36:37], 0, s[34:35]
	v_lshl_add_u64 v[4:5], v[36:37], 0, s[30:31]
	s_mov_b64 s[6:7], vcc
	v_add_co_u32_e32 v24, vcc, s49, v36
	v_lshl_add_u64 v[20:21], v[36:37], 0, s[20:21]
	v_lshl_add_u64 v[12:13], v[36:37], 0, s[24:25]
	global_load_dwordx4 v[72:75], v[0:1], off offset:16
	v_addc_co_u32_e32 v25, vcc, 0, v37, vcc
	global_load_dwordx4 v[4:7], v[4:5], off offset:16
	v_lshl_add_u64 v[0:1], v[36:37], 0, s[36:37]
	global_load_dwordx4 v[0:3], v[0:1], off offset:16
	s_nop 0
	global_load_dwordx4 v[8:11], v[8:9], off
	s_nop 0
	global_load_dwordx4 v[12:15], v[12:13], off offset:16
	s_nop 0
	global_load_dwordx4 v[16:19], v[16:17], off
	s_nop 0
	global_load_dwordx4 v[20:23], v[20:21], off offset:16
	v_lshl_add_u64 v[44:45], s[18:19], 0, v[40:41]
	global_load_dwordx4 v[76:79], v[24:25], off offset:2048
	v_add_co_u32_e32 v24, vcc, s50, v36
	s_and_b32 s12, s8, 63
	s_nop 0
	v_addc_co_u32_e32 v25, vcc, 0, v37, vcc
	global_load_dwordx4 v[24:27], v[24:25], off
	v_addc_co_u32_e64 v29, vcc, 0, v37, s[6:7]
	global_load_dwordx4 v[28:31], v[28:29], off
	s_nop 0
	global_load_dwordx4 v[32:35], v[36:37], off
	s_nop 0
	global_load_dwordx4 v[36:39], v[36:37], off offset:16
	s_nop 0
	global_load_dwordx4 v[40:43], v[44:45], off
	s_nop 0
	global_load_dwordx4 v[44:47], v[44:45], off offset:16
	s_ashr_i32 s6, s8, 6
	s_ashr_i32 s7, s6, 31
	s_add_i32 s42, s12, -1
	s_lshl_b64 s[6:7], s[6:7], 12
	s_cmp_lt_u32 s42, 64
	s_cselect_b64 s[38:39], -1, 0
	s_and_b64 s[8:9], s[38:39], exec
	s_cselect_b32 s8, s42, s12
	s_ashr_i32 s9, s8, 31
	s_lshl_b64 s[8:9], s[8:9], 6
	s_add_u32 s8, s8, s6
	s_addc_u32 s9, s9, s7
	s_mulk_i32 s9, 0x5800
	s_mul_hi_u32 s40, s8, 0x5800
	s_add_i32 s40, s40, s9
	s_mulk_i32 s8, 0x5800
	s_add_u32 s8, s2, s8
	s_addc_u32 s9, s3, s40
	v_lshlrev_b64 v[80:81], 1, v[80:81]
	s_lshl_b32 s40, s12, 6
	v_lshl_add_u64 v[138:139], s[8:9], 0, v[80:81]
	s_or_b32 s8, s6, s40
	s_mul_i32 s9, s7, 0x5800
	s_mul_hi_u32 s41, s8, 0x5800
	s_add_i32 s41, s41, s9
	s_mulk_i32 s8, 0x5800
	s_add_u32 s8, s2, s8
	s_addc_u32 s9, s3, s41
	s_add_i32 s43, s40, 64
	s_cmp_lg_u32 s12, 63
	s_cselect_b64 s[40:41], -1, 0
	v_lshl_add_u64 v[140:141], s[8:9], 0, v[80:81]
	s_and_b64 s[8:9], s[40:41], exec
	s_cselect_b32 s8, s43, 0xfc0
	s_add_u32 s6, s6, s8
	s_addc_u32 s7, s7, 0
	s_mulk_i32 s7, 0x5800
	s_mul_hi_u32 s8, s6, 0x5800
	s_add_i32 s8, s8, s7
	s_mulk_i32 s6, 0x5800
	s_add_u32 s6, s2, s6
	s_addc_u32 s7, s3, s8
	v_lshl_add_u64 v[142:143], s[6:7], 0, v[80:81]
	v_or_b32_e32 v80, s42, v225
	v_cmp_gt_u32_e64 s[6:7], 64, v80
	s_and_b64 s[42:43], s[40:41], s[4:5]
	s_waitcnt vmcnt(16)
	v_mov_b32_e32 v148, v62
	v_mov_b32_e32 v150, v54
	v_mov_b32_e32 v156, v60
	v_mov_b32_e32 v158, v52
	v_mov_b32_e32 v164, v58
	v_mov_b32_e32 v166, v50
	s_waitcnt vmcnt(15)
	v_mov_b32_e32 v162, v66
	s_waitcnt vmcnt(14)
	v_mov_b32_e32 v146, v70
	v_mov_b32_e32 v154, v68
	v_mov_b32_e32 v170, v64
	v_mov_b32_e32 v172, v56
	v_mov_b32_e32 v174, v48
	s_mov_b64 s[44:45], -1
	s_mov_b32 s8, 0
	s_waitcnt vmcnt(13)
	v_mov_b32_e32 v144, v74
	v_mov_b32_e32 v152, v72
	s_waitcnt vmcnt(12)
	v_mov_b32_e32 v147, v6
	v_mov_b32_e32 v6, v71
	s_waitcnt vmcnt(11)
	v_mov_b32_e32 v145, v2
	v_mov_b32_e32 v2, v75
	s_waitcnt vmcnt(9)
	v_mov_b32_e32 v149, v14
	v_mov_b32_e32 v14, v63
	s_waitcnt vmcnt(7)
	v_mov_b32_e32 v151, v22
	v_mov_b32_e32 v22, v55
	v_mov_b32_e32 v153, v0
	v_mov_b32_e32 v0, v73
	v_mov_b32_e32 v155, v4
	v_mov_b32_e32 v4, v69
	v_mov_b32_e32 v157, v12
	v_mov_b32_e32 v12, v61
	v_mov_b32_e32 v159, v20
	v_mov_b32_e32 v20, v53
	s_waitcnt vmcnt(6)
	v_mov_b32_e32 v160, v78
	s_waitcnt vmcnt(5)
	v_mov_b32_e32 v161, v26
	v_mov_b32_e32 v26, v79
	s_waitcnt vmcnt(4)
	v_mov_b32_e32 v163, v30
	v_mov_b32_e32 v30, v67
	v_mov_b32_e32 v165, v10
	v_mov_b32_e32 v10, v59
	v_mov_b32_e32 v167, v18
	v_mov_b32_e32 v18, v51
	v_mov_b32_e32 v168, v76
	v_mov_b32_e32 v169, v24
	v_mov_b32_e32 v24, v77
	v_mov_b32_e32 v171, v28
	v_mov_b32_e32 v28, v65
	v_mov_b32_e32 v173, v8
	v_mov_b32_e32 v8, v57
	v_mov_b32_e32 v175, v16
	v_mov_b32_e32 v16, v49
	s_branch .LBB0_1043
; __device__ __forceinline__ float bflo(unsigned w) { return __uint_as_float(w << 16); }
; __device__ __forceinline__ float bfhi(unsigned w) { return __uint_as_float(w & 0xffff0000u); }
; __device__ __forceinline__ void phase_conv(PRef p, int layer, int nseg) {
;     ...
;         for (int hx = 0; hx < 2; ++hx) { const int xb = x0 + 4 * hx;
;             u32x4 gc[3][6], vv[4];
; #pragma unroll
;             for (int ky = 0; ky < 3; ++ky)
; #pragma unroll
;                 for (int cx = 0; cx < 6; ++cx) { const int xx = xb - 1 + cx;
;                     gc[ky][cx] = (lv[ky] && xx >= 0 && xx < W) ? *(const u32x4*)(lp[ky] + (size_t)xx * NUP) : (u32x4){0u, 0u, 0u, 0u}; }
; #pragma unroll
;             for (int xi = 0; xi < 4; ++xi) vv[xi] = *(const u32x4*)(lp[1] + (size_t)(xb + xi) * NUP + NFF);
; #pragma unroll
;             for (int xi = 0; xi < 4; ++xi) {
;                 float acc[8];
; #pragma unroll
;                 for (int j = 0; j < 8; ++j) acc[j] = bias[j];
; #pragma unroll
;                 for (int ky = 0; ky < 3; ++ky)
; #pragma unroll
;                     for (int kx = 0; kx < 3; ++kx) { const u32x4 gq = gc[ky][xi + kx]; const int k = ky * 3 + kx;
;                         acc[0] += w[k][0] * bflo(gq.x); acc[1] += w[k][1] * bfhi(gq.x); acc[2] += w[k][2] * bflo(gq.y); acc[3] += w[k][3] * bfhi(gq.y);
;                         acc[4] += w[k][4] * bflo(gq.z); acc[5] += w[k][5] * bfhi(gq.z); acc[6] += w[k][6] * bflo(gq.w); acc[7] += w[k][7] * bfhi(gq.w); }
.LBB0_1042:
	s_or_b64 exec, exec, s[8:9]
	s_waitcnt vmcnt(0)
	v_lshlrev_b32_e32 v136, 16, v96
	v_and_b32_e32 v96, 0xffff0000, v96
	v_fma_f32 v182, v33, v96, v41
	v_lshlrev_b32_e32 v96, 16, v97
	v_fma_f32 v183, v34, v96, v42
	v_and_b32_e32 v96, 0xffff0000, v97
	v_fma_f32 v184, v35, v96, v43
	v_lshlrev_b32_e32 v96, 16, v98
	v_fma_f32 v185, v36, v96, v44
	v_and_b32_e32 v96, 0xffff0000, v98
	v_fma_f32 v98, v37, v96, v45
	v_lshlrev_b32_e32 v96, 16, v99
	v_fma_f32 v186, v38, v96, v46
	v_and_b32_e32 v96, 0xffff0000, v99
	v_lshlrev_b32_e32 v203, 16, v100
	v_lshlrev_b32_e32 v202, 16, v92
	v_fma_f32 v136, v32, v136, v40
	v_fma_f32 v99, v39, v96, v47
	v_and_b32_e32 v201, 0xffff0000, v100
	v_fma_f32 v96, v174, v202, v136
	v_and_b32_e32 v200, 0xffff0000, v92
	v_fma_f32 v136, v175, v203, v96
	v_lshlrev_b32_e32 v198, 16, v93
	v_fma_f32 v92, v16, v200, v182
	v_lshlrev_b32_e32 v199, 16, v101
	v_fma_f32 v100, v17, v201, v92
	v_mad_i64_i32 v[48:49], s[8:9], v90, s51, v[140:141]
	v_fma_f32 v92, v166, v198, v183
	v_and_b32_e32 v197, 0xffff0000, v101
	v_and_b32_e32 v196, 0xffff0000, v93
	v_add_co_u32_e32 v204, vcc, 0x2000, v48
	v_fma_f32 v96, v167, v199, v92
	s_nop 0
	v_addc_co_u32_e32 v205, vcc, 0, v49, vcc
	v_mad_i64_i32 v[48:49], s[8:9], v91, s51, v[140:141]
	v_fma_f32 v92, v18, v196, v184
	v_lshlrev_b32_e32 v195, 16, v102
	v_lshlrev_b32_e32 v194, 16, v94
	v_add_co_u32_e32 v180, vcc, 0x2000, v48
	v_fma_f32 v97, v19, v197, v92
	s_nop 0
	v_addc_co_u32_e32 v181, vcc, 0, v49, vcc
	global_load_dwordx4 v[108:111], v[204:205], off offset:3072
	global_load_dwordx4 v[104:107], v[180:181], off offset:3072
	v_fma_f32 v92, v158, v194, v185
	v_and_b32_e32 v193, 0xffff0000, v102
	v_and_b32_e32 v192, 0xffff0000, v94
	v_fma_f32 v101, v159, v195, v92
	v_lshlrev_b32_e32 v190, 16, v95
	v_fma_f32 v92, v20, v192, v98
	v_lshlrev_b32_e32 v191, 16, v103
	v_fma_f32 v94, v21, v193, v92
	v_and_b32_e32 v189, 0xffff0000, v103
	v_fma_f32 v92, v150, v190, v186
	v_and_b32_e32 v188, 0xffff0000, v95
	v_fma_f32 v98, v151, v191, v92
	v_lshlrev_b32_e32 v207, 16, v116
	v_fma_f32 v92, v22, v188, v99
	v_lshlrev_b32_e32 v206, 16, v112
	v_fma_f32 v95, v23, v189, v92
	v_and_b32_e32 v209, 0xffff0000, v116
	v_fma_f32 v92, v172, v206, v136
	v_and_b32_e32 v208, 0xffff0000, v112
	v_fma_f32 v99, v173, v207, v92
	v_lshlrev_b32_e32 v210, 16, v113
	v_fma_f32 v92, v8, v208, v100
	v_lshlrev_b32_e32 v211, 16, v117
	v_fma_f32 v100, v9, v209, v92
	v_and_b32_e32 v213, 0xffff0000, v117
	v_fma_f32 v92, v164, v210, v96
	v_and_b32_e32 v212, 0xffff0000, v113
	v_fma_f32 v96, v165, v211, v92
	v_lshlrev_b32_e32 v215, 16, v118
	v_fma_f32 v92, v10, v212, v97
	v_lshlrev_b32_e32 v214, 16, v114
	v_fma_f32 v97, v11, v213, v92
	v_and_b32_e32 v217, 0xffff0000, v118
	v_fma_f32 v92, v156, v214, v101
	v_and_b32_e32 v216, 0xffff0000, v114
	v_fma_f32 v101, v157, v215, v92
	v_lshlrev_b32_e32 v218, 16, v115
	v_fma_f32 v92, v12, v216, v94
	v_lshlrev_b32_e32 v219, 16, v119
	v_fma_f32 v94, v13, v217, v92
	v_and_b32_e32 v221, 0xffff0000, v119
	v_fma_f32 v92, v148, v218, v98
	v_and_b32_e32 v220, 0xffff0000, v115
	v_fma_f32 v98, v149, v219, v92
	v_lshlrev_b32_e32 v187, 16, v132
	v_fma_f32 v92, v14, v220, v95
	v_lshlrev_b32_e32 v186, 16, v120
	v_fma_f32 v102, v15, v221, v92
	v_and_b32_e32 v185, 0xffff0000, v132
	v_fma_f32 v92, v170, v186, v99
	v_and_b32_e32 v184, 0xffff0000, v120
	v_fma_f32 v99, v171, v187, v92
	v_lshlrev_b32_e32 v182, 16, v121
	v_fma_f32 v92, v28, v184, v100
	v_lshlrev_b32_e32 v183, 16, v133
	v_fma_f32 v103, v29, v185, v92
	v_and_b32_e32 v117, 0xffff0000, v133
	v_fma_f32 v92, v162, v182, v96
	v_and_b32_e32 v116, 0xffff0000, v121
	v_fma_f32 v114, v163, v183, v92
	v_lshlrev_b32_e32 v113, 16, v134
	v_fma_f32 v92, v30, v116, v97
	v_lshlrev_b32_e32 v112, 16, v122
	v_fma_f32 v115, v31, v117, v92
	v_and_b32_e32 v100, 0xffff0000, v122
	v_fma_f32 v92, v154, v112, v101
	v_and_b32_e32 v101, 0xffff0000, v134
	v_fma_f32 v136, v155, v113, v92
	v_lshlrev_b32_e32 v96, 16, v123
	v_fma_f32 v92, v4, v100, v94
	v_lshlrev_b32_e32 v97, 16, v135
	v_fma_f32 v134, v5, v101, v92
	v_lshlrev_b32_e32 v133, 16, v128
	v_fma_f32 v92, v146, v96, v98
	v_fma_f32 v206, v147, v97, v92
	v_and_b32_e32 v93, 0xffff0000, v135
	v_and_b32_e32 v92, 0xffff0000, v123
	v_lshlrev_b32_e32 v132, 16, v124
	v_fma_f32 v94, v6, v92, v102
	v_fma_f32 v135, v7, v93, v94
	v_and_b32_e32 v123, 0xffff0000, v128
	v_fma_f32 v94, v168, v132, v99
	v_and_b32_e32 v122, 0xffff0000, v124
	v_fma_f32 v210, v169, v133, v94
	v_lshlrev_b32_e32 v120, 16, v125
	v_fma_f32 v94, v24, v122, v103
	v_lshlrev_b32_e32 v121, 16, v129
	v_fma_f32 v128, v25, v123, v94
	v_mul_f32_e32 v124, 0x3d372713, v210
	v_fma_f32 v94, v160, v120, v114
	v_and_b32_e32 v119, 0xffff0000, v129
	v_and_b32_e32 v118, 0xffff0000, v125
	v_mul_f32_e32 v124, v210, v124
	v_fma_f32 v214, v161, v121, v94
	v_fma_f32 v124, v210, v124, v210
	v_fma_f32 v94, v26, v118, v115
	v_lshlrev_b32_e32 v115, 16, v130
	v_lshlrev_b32_e32 v114, 16, v126
	v_mul_f32_e32 v124, 0xc0135761, v124
	v_fma_f32 v129, v27, v119, v94
	v_fma_f32 v94, v152, v114, v136
	v_and_b32_e32 v103, 0xffff0000, v130
	v_and_b32_e32 v102, 0xffff0000, v126
	v_fma_f32 v136, v153, v115, v94
	v_exp_f32_e32 v124, v124
	v_fma_f32 v94, v0, v102, v134
	v_lshlrev_b32_e32 v98, 16, v127
	v_lshlrev_b32_e32 v99, 16, v131
	v_fma_f32 v126, v1, v103, v94
	v_mad_i64_i32 v[48:49], s[8:9], v176, s51, v[140:141]
	v_fma_f32 v94, v144, v98, v206
	v_fma_f32 v130, v145, v99, v94
	v_and_b32_e32 v94, 0xffff0000, v127
	v_add_f32_e32 v127, 1.0, v124
	v_and_b32_e32 v95, 0xffff0000, v131
	v_rcp_f32_e32 v134, v127
	v_add_co_u32_e32 v178, vcc, 0x2000, v48
	s_nop 0
	s_nop 0
	v_addc_co_u32_e32 v179, vcc, 0, v49, vcc
	v_mad_i64_i32 v[48:49], s[8:9], v177, s51, v[140:141]
	v_add_co_u32_e32 v176, vcc, 0x2000, v48
	v_fma_f32 v124, v2, v94, v135
	s_nop 0
	v_addc_co_u32_e32 v177, vcc, 0, v49, vcc
	v_fma_f32 v124, v3, v95, v124
	v_mul_f32_e32 v206, 0x3d372713, v128
	v_mul_f32_e32 v206, v128, v206
	v_fma_f32 v206, v128, v206, v128
	v_mul_f32_e32 v206, 0xc0135761, v206
	v_exp_f32_e32 v206, v206
	v_mul_f32_e32 v125, v210, v134
	v_add_f32_e32 v131, 1.0, v206
	v_rcp_f32_e32 v135, v131
	s_waitcnt vmcnt(1)
; __device__ __forceinline__ unsigned cvt_pk_bf16(float lo, float hi) { unsigned r; asm("v_cvt_pk_bf16_f32 %0, %1, %2" : "=v"(r) : "v"(lo), "v"(hi)); return r; }
; __device__ __forceinline__ float bflo(unsigned w) { return __uint_as_float(w << 16); }
; __device__ __forceinline__ float bfhi(unsigned w) { return __uint_as_float(w & 0xffff0000u); }
; __device__ __forceinline__ float gelu_tanh(float x) { const float u = 0.7978845608028654f * (x + 0.044715f * x * x * x); return x / (1.f + __expf(-2.f * u)); }
; __device__ __forceinline__ void phase_conv(PRef p, int layer, int nseg) {
;     ...
;             for (int xi = 0; xi < 4; ++xi) {
;                 float acc[8];
; #pragma unroll
;                 for (int j = 0; j < 8; ++j) acc[j] = bias[j];
; #pragma unroll
;                 for (int ky = 0; ky < 3; ++ky)
; #pragma unroll
;                     for (int kx = 0; kx < 3; ++kx) { const u32x4 gq = gc[ky][xi + kx]; const int k = ky * 3 + kx;
;                         acc[0] += w[k][0] * bflo(gq.x); acc[1] += w[k][1] * bfhi(gq.x); acc[2] += w[k][2] * bflo(gq.y); acc[3] += w[k][3] * bfhi(gq.y);
;                         acc[4] += w[k][4] * bflo(gq.z); acc[5] += w[k][5] * bfhi(gq.z); acc[6] += w[k][6] * bflo(gq.w); acc[7] += w[k][7] * bfhi(gq.w); }
;                 u32x4 o;
;                 o.x = cvt_pk_bf16(gelu_tanh(acc[0]) * bflo(vv[xi].x), gelu_tanh(acc[1]) * bfhi(vv[xi].x));
;                 o.y = cvt_pk_bf16(gelu_tanh(acc[2]) * bflo(vv[xi].y), gelu_tanh(acc[3]) * bfhi(vv[xi].y));
;                 o.z = cvt_pk_bf16(gelu_tanh(acc[4]) * bflo(vv[xi].z), gelu_tanh(acc[5]) * bfhi(vv[xi].z));
;                 o.w = cvt_pk_bf16(gelu_tanh(acc[6]) * bflo(vv[xi].w), gelu_tanh(acc[7]) * bfhi(vv[xi].w));
;                 *(u32x4*)((bf16_t*)lp[1] + (size_t)(xb + xi) * NUP + NFF) = o; } }
	v_lshlrev_b32_e32 v127, 16, v108
	v_mul_f32_e32 v125, v125, v127
	v_and_b32_e32 v108, 0xffff0000, v108
	v_mul_f32_e32 v134, 0x3d372713, v214
	v_mul_f32_e32 v134, v214, v134
	v_fma_f32 v134, v214, v134, v214
	v_mul_f32_e32 v134, 0xc0135761, v134
	v_exp_f32_e32 v134, v134
	v_mul_f32_e32 v127, v128, v135
	v_mul_f32_e32 v108, v127, v108
	v_add_f32_e32 v128, 1.0, v134
	v_rcp_f32_e32 v134, v128
	v_cvt_pk_bf16_f32 v108, v125, v108
	global_load_dwordx4 v[88:91], v[178:179], off offset:3072
	global_load_dwordx4 v[48:51], v[176:177], off offset:3072
	v_fma_f32 v202, v32, v202, v40
	v_mul_f32_e32 v135, 0x3d372713, v129
	v_mul_f32_e32 v135, v129, v135
	v_fma_f32 v135, v129, v135, v129
	v_mul_f32_e32 v135, 0xc0135761, v135
	v_exp_f32_e32 v135, v135
	v_mul_f32_e32 v125, v214, v134
	v_add_f32_e32 v127, 1.0, v135
	v_rcp_f32_e32 v134, v127
	v_lshlrev_b32_e32 v128, 16, v109
	v_mul_f32_e32 v125, v125, v128
	v_and_b32_e32 v109, 0xffff0000, v109
	v_mul_f32_e32 v131, 0x3d372713, v136
	v_mul_f32_e32 v131, v136, v131
	v_fma_f32 v131, v136, v131, v136
	v_mul_f32_e32 v131, 0xc0135761, v131
	v_exp_f32_e32 v131, v131
	v_mul_f32_e32 v127, v129, v134
	v_mul_f32_e32 v109, v127, v109
	v_add_f32_e32 v128, 1.0, v131
	v_rcp_f32_e32 v131, v128
	v_cvt_pk_bf16_f32 v109, v125, v109
	v_fma_f32 v210, v33, v200, v41
	v_fma_f32 v214, v35, v196, v43
	v_mul_f32_e32 v134, 0x3d372713, v126
	v_mul_f32_e32 v134, v126, v134
	v_fma_f32 v134, v126, v134, v126
	v_mul_f32_e32 v134, 0xc0135761, v134
	v_exp_f32_e32 v134, v134
	v_mul_f32_e32 v125, v136, v131
	v_add_f32_e32 v127, 1.0, v134
	v_rcp_f32_e32 v131, v127
	v_lshlrev_b32_e32 v128, 16, v110
	v_mul_f32_e32 v125, v125, v128
	v_and_b32_e32 v110, 0xffff0000, v110
	v_mul_f32_e32 v129, 0x3d372713, v130
	v_mul_f32_e32 v129, v130, v129
	v_fma_f32 v129, v130, v129, v130
	v_mul_f32_e32 v129, 0xc0135761, v129
	v_exp_f32_e32 v129, v129
	v_mul_f32_e32 v126, v126, v131
	v_mul_f32_e32 v110, v126, v110
	v_add_f32_e32 v127, 1.0, v129
	v_rcp_f32_e32 v129, v127
	v_cvt_pk_bf16_f32 v110, v125, v110
	s_waitcnt vmcnt(2)
	v_lshlrev_b32_e32 v234, 16, v105
	v_fma_f32 v218, v37, v192, v45
	v_mul_f32_e32 v131, 0x3d372713, v124
	v_mul_f32_e32 v131, v124, v131
	v_fma_f32 v131, v124, v131, v124
	v_mul_f32_e32 v131, 0xc0135761, v131
	v_exp_f32_e32 v131, v131
	v_mul_f32_e32 v125, v130, v129
	v_add_f32_e32 v126, 1.0, v131
	v_rcp_f32_e32 v129, v126
	v_lshlrev_b32_e32 v127, 16, v111
	v_mul_f32_e32 v125, v125, v127
	v_and_b32_e32 v111, 0xffff0000, v111
	v_mul_f32_e32 v124, v124, v129
	v_mul_f32_e32 v111, v124, v111
	v_cvt_pk_bf16_f32 v111, v125, v111
	global_store_dwordx4 v[204:205], v[108:111], off offset:3072
	v_pk_mov_b32 v[124:125], v[210:211], v[182:183] op_sel:[1,0]
	v_pk_mov_b32 v[126:127], v[212:213], v[116:117] op_sel:[1,0]
	v_pk_mov_b32 v[108:109], v[206:207], v[186:187] op_sel:[1,0]
	v_lshlrev_b32_e32 v207, 16, v76
	v_lshlrev_b32_e32 v206, 16, v72
	v_pk_mov_b32 v[128:129], v[214:215], v[112:113] op_sel:[1,0]
	v_lshlrev_b32_e32 v117, 16, v104
	v_and_b32_e32 v183, 0xffff0000, v104
	v_and_b32_e32 v113, 0xffff0000, v105
	v_pk_mov_b32 v[104:105], v[202:203], v[206:207] op_sel:[1,0]
	v_pk_mov_b32 v[130:131], v[216:217], v[100:101] op_sel:[1,0]
	v_fma_f32 v104, v174, v104, v202
	v_fma_f32 v104, v175, v105, v104
	v_fma_f32 v104, v172, v108, v104
	v_pk_mov_b32 v[134:135], v[218:219], v[96:97] op_sel:[1,0]
	v_lshlrev_b32_e32 v101, 16, v106
	v_and_b32_e32 v97, 0xffff0000, v106
	v_fma_f32 v106, v32, v203, v40
	v_fma_f32 v203, v173, v109, v104
	v_pk_mov_b32 v[110:111], v[208:209], v[184:185] op_sel:[1,0]
	v_fma_f32 v104, v174, v206, v106
	v_and_b32_e32 v209, 0xffff0000, v76
	v_and_b32_e32 v208, 0xffff0000, v72
	v_fma_f32 v235, v175, v207, v104
	v_pk_mov_b32 v[104:105], v[200:201], v[208:209] op_sel:[1,0]
	v_pk_mov_b32 v[204:205], v[220:221], v[92:93] op_sel:[1,0]
	v_fma_f32 v72, v16, v104, v210
	v_fma_f32 v72, v17, v105, v72
	v_lshlrev_b32_e32 v93, 16, v107
	v_and_b32_e32 v136, 0xffff0000, v107
	v_fma_f32 v107, v33, v201, v41
	v_fma_f32 v72, v8, v110, v72
	v_fma_f32 v198, v34, v198, v42
	v_fma_f32 v236, v9, v111, v72
	v_fma_f32 v72, v16, v208, v107
	v_lshlrev_b32_e32 v210, 16, v73
	v_lshlrev_b32_e32 v211, 16, v77
	v_fma_f32 v237, v17, v209, v72
	v_pk_mov_b32 v[104:105], v[198:199], v[210:211] op_sel:[1,0]
	v_fma_f32 v185, v34, v199, v42
	v_fma_f32 v72, v166, v104, v198
	v_fma_f32 v72, v167, v105, v72
	v_fma_f32 v72, v164, v124, v72
	v_fma_f32 v238, v165, v125, v72
	v_fma_f32 v72, v166, v210, v185
	v_and_b32_e32 v213, 0xffff0000, v77
	v_and_b32_e32 v212, 0xffff0000, v73
	v_fma_f32 v239, v167, v211, v72
	v_pk_mov_b32 v[72:73], v[196:197], v[212:213] op_sel:[1,0]
	v_fma_f32 v187, v35, v197, v43
	v_fma_f32 v72, v18, v72, v214
	v_fma_f32 v72, v19, v73, v72
	v_fma_f32 v72, v10, v126, v72
	v_fma_f32 v240, v11, v127, v72
	v_fma_f32 v194, v36, v194, v44
	v_fma_f32 v72, v18, v212, v187
	v_lshlrev_b32_e32 v215, 16, v78
	v_lshlrev_b32_e32 v214, 16, v74
	v_fma_f32 v241, v19, v213, v72
	v_pk_mov_b32 v[72:73], v[194:195], v[214:215] op_sel:[1,0]
	v_fma_f32 v216, v36, v195, v44
	v_fma_f32 v72, v158, v72, v194
	v_fma_f32 v72, v159, v73, v72
	v_fma_f32 v72, v156, v128, v72
	v_fma_f32 v202, v157, v129, v72
	v_and_b32_e32 v217, 0xffff0000, v78
	v_fma_f32 v72, v158, v214, v216
	v_and_b32_e32 v216, 0xffff0000, v74
	v_fma_f32 v201, v159, v215, v72
	v_pk_mov_b32 v[72:73], v[192:193], v[216:217] op_sel:[1,0]
	v_fma_f32 v219, v37, v193, v45
	v_fma_f32 v72, v20, v72, v218
	v_fma_f32 v72, v21, v73, v72
	v_fma_f32 v72, v12, v130, v72
	v_fma_f32 v199, v13, v131, v72
	v_fma_f32 v190, v38, v190, v46
	v_fma_f32 v72, v20, v216, v219
	v_lshlrev_b32_e32 v218, 16, v75
	v_lshlrev_b32_e32 v219, 16, v79
	v_fma_f32 v198, v21, v217, v72
	v_pk_mov_b32 v[72:73], v[190:191], v[218:219] op_sel:[1,0]
	v_fma_f32 v220, v38, v191, v46
	v_fma_f32 v72, v150, v72, v190
	v_fma_f32 v72, v151, v73, v72
	v_fma_f32 v72, v148, v134, v72
	v_fma_f32 v197, v149, v135, v72
	v_and_b32_e32 v221, 0xffff0000, v79
	v_fma_f32 v72, v150, v218, v220
	v_and_b32_e32 v220, 0xffff0000, v75
	v_fma_f32 v196, v151, v219, v72
	v_pk_mov_b32 v[72:73], v[188:189], v[220:221] op_sel:[1,0]
	v_fma_f32 v227, v39, v188, v47
	s_waitcnt vmcnt(2)
; __device__ __forceinline__ unsigned cvt_pk_bf16(float lo, float hi) { unsigned r; asm("v_cvt_pk_bf16_f32 %0, %1, %2" : "=v"(r) : "v"(lo), "v"(hi)); return r; }
; __device__ __forceinline__ float bflo(unsigned w) { return __uint_as_float(w << 16); }
; __device__ __forceinline__ float bfhi(unsigned w) { return __uint_as_float(w & 0xffff0000u); }
; __device__ __forceinline__ float gelu_tanh(float x) { const float u = 0.7978845608028654f * (x + 0.044715f * x * x * x); return x / (1.f + __expf(-2.f * u)); }
; __device__ __forceinline__ void phase_conv(PRef p, int layer, int nseg) {
;     ...
;             for (int xi = 0; xi < 4; ++xi) {
;                 float acc[8];
; #pragma unroll
;                 for (int j = 0; j < 8; ++j) acc[j] = bias[j];
; #pragma unroll
;                 for (int ky = 0; ky < 3; ++ky)
; #pragma unroll
;                     for (int kx = 0; kx < 3; ++kx) { const u32x4 gq = gc[ky][xi + kx]; const int k = ky * 3 + kx;
;                         acc[0] += w[k][0] * bflo(gq.x); acc[1] += w[k][1] * bfhi(gq.x); acc[2] += w[k][2] * bflo(gq.y); acc[3] += w[k][3] * bfhi(gq.y);
;                         acc[4] += w[k][4] * bflo(gq.z); acc[5] += w[k][5] * bfhi(gq.z); acc[6] += w[k][6] * bflo(gq.w); acc[7] += w[k][7] * bfhi(gq.w); }
;                 u32x4 o;
;                 o.x = cvt_pk_bf16(gelu_tanh(acc[0]) * bflo(vv[xi].x), gelu_tanh(acc[1]) * bfhi(vv[xi].x));
;                 o.y = cvt_pk_bf16(gelu_tanh(acc[2]) * bflo(vv[xi].y), gelu_tanh(acc[3]) * bfhi(vv[xi].y));
;                 o.z = cvt_pk_bf16(gelu_tanh(acc[4]) * bflo(vv[xi].z), gelu_tanh(acc[5]) * bfhi(vv[xi].z));
;                 o.w = cvt_pk_bf16(gelu_tanh(acc[6]) * bflo(vv[xi].w), gelu_tanh(acc[7]) * bfhi(vv[xi].w));
;                 *(u32x4*)((bf16_t*)lp[1] + (size_t)(xb + xi) * NUP + NFF) = o; } }
	v_lshlrev_b32_e32 v185, 16, v88
	v_fma_f32 v72, v22, v72, v227
	v_and_b32_e32 v227, 0xffff0000, v88
	v_lshlrev_b32_e32 v242, 16, v89
	v_and_b32_e32 v243, 0xffff0000, v89
	v_lshlrev_b32_e32 v244, 16, v90
	v_and_b32_e32 v200, 0xffff0000, v90
	v_lshlrev_b32_e32 v89, 16, v91
	v_and_b32_e32 v88, 0xffff0000, v91
	v_lshlrev_b32_e32 v91, 16, v68
	v_mov_b32_e32 v90, v207
	v_fma_f32 v72, v23, v73, v72
	v_fma_f32 v187, v32, v206, v40
	v_fma_f32 v72, v14, v204, v72
	v_fma_f32 v90, v174, v90, v187
	v_fma_f32 v195, v15, v205, v72
	v_pk_mul_f32 v[72:73], v[22:23], v[220:221]
	v_fma_f32 v206, v33, v208, v41
	v_fma_f32 v208, v34, v210, v42
	v_fma_f32 v210, v35, v212, v43
	v_fma_f32 v212, v36, v214, v44
	v_fma_f32 v214, v37, v216, v45
	v_fma_f32 v216, v38, v218, v46
	v_fma_f32 v218, v39, v220, v47
	v_fma_f32 v220, v175, v91, v90
	v_and_b32_e32 v91, 0xffff0000, v68
	v_mov_b32_e32 v90, v209
	v_fma_f32 v228, v39, v189, v47
	v_fma_f32 v68, v16, v90, v206
	v_fma_f32 v209, v17, v91, v68
	v_lshlrev_b32_e32 v91, 16, v69
	v_mov_b32_e32 v90, v211
	v_and_b32_e32 v69, 0xffff0000, v69
	v_fma_f32 v68, v166, v90, v208
	v_fma_f32 v208, v167, v91, v68
	v_mov_b32_e32 v68, v213
	v_lshlrev_b32_e32 v206, 16, v56
	v_fma_f32 v68, v18, v68, v210
	v_fma_f32 v210, v19, v69, v68
	v_lshlrev_b32_e32 v69, 16, v70
	v_mov_b32_e32 v68, v215
	v_add_f32_e32 v72, v228, v72
	v_fma_f32 v68, v158, v68, v212
	v_fma_f32 v211, v159, v69, v68
	v_and_b32_e32 v69, 0xffff0000, v70
	v_mov_b32_e32 v68, v217
	v_mov_b32_e32 v70, v206
	v_fma_f32 v68, v20, v68, v214
	v_fma_f32 v91, v21, v69, v68
	v_lshlrev_b32_e32 v69, 16, v71
	v_mov_b32_e32 v68, v219
	v_add_f32_e32 v194, v72, v73
	v_fma_f32 v68, v150, v68, v216
	v_fma_f32 v90, v151, v69, v68
	v_and_b32_e32 v69, 0xffff0000, v71
	v_mov_b32_e32 v68, v221
	v_mov_b32_e32 v71, v132
	v_lshlrev_b32_e32 v73, 16, v84
	v_lshlrev_b32_e32 v72, 16, v80
	v_fma_f32 v68, v22, v68, v218
	v_pk_mov_b32 v[74:75], v[132:133], v[72:73] op_sel:[1,0]
	v_fma_f32 v68, v23, v69, v68
	v_fma_f32 v69, v170, v70, v203
	v_pk_mul_f32 v[204:205], v[168:169], v[74:75]
	v_fma_f32 v69, v171, v71, v69
	v_fma_f32 v69, v168, v74, v69
	v_fma_f32 v69, v169, v75, v69
	v_mul_f32_e32 v132, 0x3d372713, v69
	v_mul_f32_e32 v132, v69, v132
	v_fma_f32 v132, v69, v132, v69
	v_mul_f32_e32 v132, 0xc0135761, v132
	v_mov_b32_e32 v187, v206
	v_lshlrev_b32_e32 v207, 16, v64
	v_pk_mul_f32 v[70:71], v[172:173], v[186:187]
	v_exp_f32_e32 v186, v132
	v_add_f32_e32 v70, v235, v70
	v_mov_b32_e32 v132, v207
	v_add_f32_e32 v187, v70, v71
	v_pk_mul_f32 v[228:229], v[168:169], v[72:73]
	v_fma_f32 v70, v170, v132, v187
	v_fma_f32 v70, v171, v133, v70
	v_fma_f32 v70, v168, v72, v70
	v_fma_f32 v70, v169, v73, v70
	v_mul_f32_e32 v133, 0x3d372713, v70
	v_add_f32_e32 v186, 1.0, v186
	v_mul_f32_e32 v133, v70, v133
	v_fma_f32 v133, v70, v133, v70
	v_rcp_f32_e32 v204, v186
	v_mul_f32_e32 v133, 0xc0135761, v133
	v_exp_f32_e32 v133, v133
	s_nop 0
	v_add_f32_e32 v133, 1.0, v133
	v_rcp_f32_e32 v203, v133
	v_mul_f32_e32 v69, v69, v204
	v_mul_f32_e32 v117, v69, v117
	v_mul_f32_e32 v69, v70, v203
	v_mul_f32_e32 v70, v69, v185
	v_fma_f32 v69, v172, v206, v220
	v_and_b32_e32 v132, 0xffff0000, v56
	v_mov_b32_e32 v186, v132
	v_mov_b32_e32 v187, v122
	v_and_b32_e32 v75, 0xffff0000, v84
	v_and_b32_e32 v74, 0xffff0000, v80
	v_pk_mov_b32 v[76:77], v[122:123], v[74:75] op_sel:[1,0]
	v_fma_f32 v56, v28, v186, v236
	v_pk_mul_f32 v[230:231], v[24:25], v[76:77]
	v_fma_f32 v56, v29, v187, v56
	v_fma_f32 v56, v24, v76, v56
	v_fma_f32 v56, v25, v77, v56
	v_fma_f32 v69, v173, v207, v69
	v_and_b32_e32 v133, 0xffff0000, v64
	v_mul_f32_e32 v64, 0x3d372713, v56
	v_mul_f32_e32 v64, v56, v64
	v_fma_f32 v64, v56, v64, v56
	v_mov_b32_e32 v185, v132
	v_mul_f32_e32 v64, 0xc0135761, v64
	v_fma_f32 v71, v8, v184, v237
	v_mov_b32_e32 v122, v133
	v_exp_f32_e32 v64, v64
	v_fma_f32 v71, v9, v185, v71
	v_pk_mul_f32 v[232:233], v[24:25], v[74:75]
	v_fma_f32 v71, v28, v122, v71
	v_fma_f32 v71, v29, v123, v71
	v_fma_f32 v71, v24, v74, v71
	v_add_f32_e32 v64, 1.0, v64
	v_fma_f32 v71, v25, v75, v71
	v_mul_f32_e32 v186, 0x3d372713, v71
	v_rcp_f32_e32 v185, v64
	v_mul_f32_e32 v186, v71, v186
	v_fma_f32 v186, v71, v186, v71
	v_mul_f32_e32 v186, 0xc0135761, v186
	v_exp_f32_e32 v186, v186
	s_nop 0
	v_add_f32_e32 v184, 1.0, v186
	v_rcp_f32_e32 v187, v184
	v_mul_f32_e32 v56, v56, v185
	v_lshlrev_b32_e32 v76, 16, v81
	v_mul_f32_e32 v64, v71, v187
	v_pk_mul_f32 v[122:123], v[8:9], v[132:133]
	v_mul_f32_e32 v71, v64, v227
	v_add_f32_e32 v64, v209, v122
	v_lshlrev_b32_e32 v122, 16, v57
	v_mov_b32_e32 v132, v122
	v_mov_b32_e32 v133, v120
	v_lshlrev_b32_e32 v77, 16, v85
	v_mul_f32_e32 v56, v56, v183
	v_pk_mov_b32 v[78:79], v[120:121], v[76:77] op_sel:[1,0]
	v_cvt_pk_bf16_f32 v56, v117, v56
	v_fma_f32 v117, v162, v132, v238
	v_pk_mul_f32 v[192:193], v[160:161], v[78:79]
	v_fma_f32 v117, v163, v133, v117
	v_fma_f32 v117, v160, v78, v117
	v_fma_f32 v117, v161, v79, v117
	v_mul_f32_e32 v120, 0x3d372713, v117
	v_mul_f32_e32 v120, v117, v120
	v_fma_f32 v120, v117, v120, v117
	v_mul_f32_e32 v120, 0xc0135761, v120
	v_mov_b32_e32 v183, v122
	v_pk_mul_f32 v[132:133], v[164:165], v[182:183]
	v_add_f32_e32 v64, v64, v123
	v_lshlrev_b32_e32 v123, 16, v65
	v_exp_f32_e32 v182, v120
	v_add_f32_e32 v120, v239, v132
	v_add_f32_e32 v132, v120, v133
	v_mov_b32_e32 v120, v123
	v_pk_mul_f32 v[190:191], v[160:161], v[76:77]
	v_fma_f32 v120, v162, v120, v132
	v_fma_f32 v120, v163, v121, v120
	v_fma_f32 v120, v160, v76, v120
	v_add_f32_e32 v133, 1.0, v182
	v_fma_f32 v120, v161, v77, v120
	v_mul_f32_e32 v184, 0x3d372713, v120
	v_rcp_f32_e32 v183, v133
	v_mul_f32_e32 v184, v120, v184
	v_fma_f32 v184, v120, v184, v120
; __device__ __forceinline__ unsigned cvt_pk_bf16(float lo, float hi) { unsigned r; asm("v_cvt_pk_bf16_f32 %0, %1, %2" : "=v"(r) : "v"(lo), "v"(hi)); return r; }
; __device__ __forceinline__ float bflo(unsigned w) { return __uint_as_float(w << 16); }
; __device__ __forceinline__ float bfhi(unsigned w) { return __uint_as_float(w & 0xffff0000u); }
; __device__ __forceinline__ float gelu_tanh(float x) { const float u = 0.7978845608028654f * (x + 0.044715f * x * x * x); return x / (1.f + __expf(-2.f * u)); }
; __device__ __forceinline__ void phase_conv(PRef p, int layer, int nseg) {
;     ...
;             for (int xi = 0; xi < 4; ++xi) {
;                 float acc[8];
; #pragma unroll
;                 for (int j = 0; j < 8; ++j) acc[j] = bias[j];
; #pragma unroll
;                 for (int ky = 0; ky < 3; ++ky)
; #pragma unroll
;                     for (int kx = 0; kx < 3; ++kx) { const u32x4 gq = gc[ky][xi + kx]; const int k = ky * 3 + kx;
;                         acc[0] += w[k][0] * bflo(gq.x); acc[1] += w[k][1] * bfhi(gq.x); acc[2] += w[k][2] * bflo(gq.y); acc[3] += w[k][3] * bfhi(gq.y);
;                         acc[4] += w[k][4] * bflo(gq.z); acc[5] += w[k][5] * bfhi(gq.z); acc[6] += w[k][6] * bflo(gq.w); acc[7] += w[k][7] * bfhi(gq.w); }
;                 u32x4 o;
;                 o.x = cvt_pk_bf16(gelu_tanh(acc[0]) * bflo(vv[xi].x), gelu_tanh(acc[1]) * bfhi(vv[xi].x));
;                 o.y = cvt_pk_bf16(gelu_tanh(acc[2]) * bflo(vv[xi].y), gelu_tanh(acc[3]) * bfhi(vv[xi].y));
;                 o.z = cvt_pk_bf16(gelu_tanh(acc[4]) * bflo(vv[xi].z), gelu_tanh(acc[5]) * bfhi(vv[xi].z));
;                 o.w = cvt_pk_bf16(gelu_tanh(acc[6]) * bflo(vv[xi].w), gelu_tanh(acc[7]) * bfhi(vv[xi].w));
;                 *(u32x4*)((bf16_t*)lp[1] + (size_t)(xb + xi) * NUP + NFF) = o; } }
	v_mul_f32_e32 v184, 0xc0135761, v184
	v_exp_f32_e32 v184, v184
	s_nop 0
	v_add_f32_e32 v182, 1.0, v184
	v_rcp_f32_e32 v185, v182
	v_mul_f32_e32 v117, v117, v183
	v_mul_f32_e32 v132, v117, v234
	v_mul_f32_e32 v117, v120, v185
	v_pk_mul_f32 v[120:121], v[164:165], v[122:123]
	v_mul_f32_e32 v133, v117, v242
	v_add_f32_e32 v117, v208, v120
	v_and_b32_e32 v120, 0xffff0000, v57
	v_mov_b32_e32 v122, v120
	v_mov_b32_e32 v123, v118
	v_and_b32_e32 v79, 0xffff0000, v85
	v_and_b32_e32 v78, 0xffff0000, v81
	v_pk_mov_b32 v[80:81], v[118:119], v[78:79] op_sel:[1,0]
	v_fma_f32 v57, v30, v122, v240
	v_pk_mul_f32 v[188:189], v[26:27], v[80:81]
	v_fma_f32 v57, v31, v123, v57
	v_fma_f32 v57, v26, v80, v57
	v_fma_f32 v57, v27, v81, v57
	v_add_f32_e32 v182, v117, v121
	v_and_b32_e32 v121, 0xffff0000, v65
	v_mul_f32_e32 v65, 0x3d372713, v57
	v_mov_b32_e32 v117, v120
	v_mul_f32_e32 v65, v57, v65
	v_fma_f32 v65, v57, v65, v57
	v_mul_f32_e32 v65, 0xc0135761, v65
	v_fma_f32 v116, v10, v116, v241
	v_mov_b32_e32 v118, v121
	v_fma_f32 v122, v11, v117, v116
	v_fma_f32 v116, v30, v118, v122
	v_pk_mul_f32 v[134:135], v[26:27], v[78:79]
	v_exp_f32_e32 v65, v65
	v_fma_f32 v116, v31, v119, v116
	v_fma_f32 v116, v26, v78, v116
	v_fma_f32 v116, v27, v79, v116
	v_mul_f32_e32 v119, 0x3d372713, v116
	v_add_f32_e32 v65, 1.0, v65
	v_mul_f32_e32 v119, v116, v119
	v_fma_f32 v119, v116, v119, v116
	v_rcp_f32_e32 v183, v65
	v_mul_f32_e32 v119, 0xc0135761, v119
	v_exp_f32_e32 v119, v119
	s_nop 0
	v_add_f32_e32 v119, 1.0, v119
	v_rcp_f32_e32 v123, v119
	v_mul_f32_e32 v57, v57, v183
	v_mul_f32_e32 v57, v57, v113
	v_mul_f32_e32 v65, v116, v123
	v_mov_b32_e32 v119, v114
	v_fma_f32 v113, v10, v120, v210
	v_lshlrev_b32_e32 v116, 16, v58
	v_mov_b32_e32 v118, v116
	v_lshlrev_b32_e32 v81, 16, v86
	v_lshlrev_b32_e32 v80, 16, v82
	v_pk_mov_b32 v[84:85], v[114:115], v[80:81] op_sel:[1,0]
	v_fma_f32 v120, v11, v121, v113
	v_fma_f32 v113, v154, v118, v202
	v_pk_mul_f32 v[130:131], v[152:153], v[84:85]
	v_fma_f32 v114, v155, v119, v113
	v_fma_f32 v114, v152, v84, v114
	v_fma_f32 v118, v153, v85, v114
	v_mul_f32_e32 v114, 0x3d372713, v118
	v_mul_f32_e32 v114, v118, v114
	v_fma_f32 v114, v118, v114, v118
	v_mul_f32_e32 v114, 0xc0135761, v114
	v_mov_b32_e32 v113, v116
	v_lshlrev_b32_e32 v117, 16, v66
	v_exp_f32_e32 v119, v114
	v_fma_f32 v112, v156, v112, v201
	v_mov_b32_e32 v114, v117
	v_fma_f32 v121, v157, v113, v112
	v_pk_mul_f32 v[128:129], v[152:153], v[80:81]
	v_fma_f32 v112, v154, v114, v121
	v_fma_f32 v112, v155, v115, v112
	v_fma_f32 v112, v152, v80, v112
	v_fma_f32 v112, v153, v81, v112
	v_mul_f32_e32 v115, 0x3d372713, v112
	v_add_f32_e32 v119, 1.0, v119
	v_mul_f32_e32 v115, v112, v115
	v_fma_f32 v115, v112, v115, v112
	v_rcp_f32_e32 v123, v119
	v_mul_f32_e32 v115, 0xc0135761, v115
	v_exp_f32_e32 v115, v115
	s_nop 0
	v_add_f32_e32 v115, 1.0, v115
	v_rcp_f32_e32 v122, v115
	v_mul_f32_e32 v113, v118, v123
	v_mul_f32_e32 v118, v113, v101
	v_mul_f32_e32 v101, v112, v122
	v_mul_f32_e32 v119, v101, v244
	v_fma_f32 v101, v156, v116, v211
	v_and_b32_e32 v112, 0xffff0000, v58
	v_mov_b32_e32 v114, v112
	v_mov_b32_e32 v115, v102
	v_and_b32_e32 v85, 0xffff0000, v86
	v_and_b32_e32 v84, 0xffff0000, v82
	v_pk_mov_b32 v[104:105], v[102:103], v[84:85] op_sel:[1,0]
	v_fma_f32 v58, v4, v114, v199
	v_pk_mul_f32 v[126:127], v[0:1], v[104:105]
	v_fma_f32 v58, v5, v115, v58
	v_fma_f32 v58, v0, v104, v58
	v_fma_f32 v58, v1, v105, v58
	v_fma_f32 v116, v157, v117, v101
	v_and_b32_e32 v113, 0xffff0000, v66
	v_mul_f32_e32 v66, 0x3d372713, v58
	v_mov_b32_e32 v101, v112
	v_mul_f32_e32 v66, v58, v66
	v_fma_f32 v66, v58, v66, v58
	v_mul_f32_e32 v66, 0xc0135761, v66
	v_fma_f32 v100, v12, v100, v198
	v_mov_b32_e32 v102, v113
	v_fma_f32 v114, v13, v101, v100
	v_fma_f32 v100, v4, v102, v114
	v_pk_mul_f32 v[124:125], v[0:1], v[84:85]
	v_exp_f32_e32 v66, v66
	v_fma_f32 v100, v5, v103, v100
	v_fma_f32 v100, v0, v84, v100
	v_fma_f32 v100, v1, v85, v100
	v_mul_f32_e32 v103, 0x3d372713, v100
	v_add_f32_e32 v66, 1.0, v66
	v_mul_f32_e32 v103, v100, v103
	v_fma_f32 v103, v100, v103, v100
	v_rcp_f32_e32 v117, v66
	v_mul_f32_e32 v103, 0xc0135761, v103
	v_exp_f32_e32 v103, v103
	s_nop 0
	v_add_f32_e32 v103, 1.0, v103
	v_rcp_f32_e32 v115, v103
	v_mul_f32_e32 v58, v58, v117
	v_mul_f32_e32 v58, v58, v97
	v_mul_f32_e32 v66, v100, v115
	v_mul_f32_e32 v114, v66, v200
	v_fma_f32 v66, v12, v112, v91
	v_lshlrev_b32_e32 v100, 16, v59
	v_mov_b32_e32 v102, v100
	v_mov_b32_e32 v103, v98
	v_lshlrev_b32_e32 v104, 16, v83
	v_lshlrev_b32_e32 v105, 16, v87
	v_pk_mov_b32 v[106:107], v[98:99], v[104:105] op_sel:[1,0]
	v_fma_f32 v112, v13, v113, v66
	v_fma_f32 v66, v146, v102, v197
	v_pk_mul_f32 v[110:111], v[144:145], v[106:107]
	v_fma_f32 v66, v147, v103, v66
	v_fma_f32 v66, v144, v106, v66
	v_fma_f32 v66, v145, v107, v66
	v_mul_f32_e32 v91, 0x3d372713, v66
	v_mov_b32_e32 v97, v100
	v_mul_f32_e32 v91, v66, v91
	v_lshlrev_b32_e32 v101, 16, v67
	v_fma_f32 v91, v66, v91, v66
	v_mul_f32_e32 v91, 0xc0135761, v91
	v_fma_f32 v96, v148, v96, v196
	v_mov_b32_e32 v98, v101
	v_fma_f32 v102, v149, v97, v96
	v_fma_f32 v96, v146, v98, v102
	v_pk_mul_f32 v[108:109], v[144:145], v[104:105]
	v_exp_f32_e32 v91, v91
	v_fma_f32 v96, v147, v99, v96
	v_fma_f32 v96, v144, v104, v96
	v_fma_f32 v96, v145, v105, v96
	v_mul_f32_e32 v99, 0x3d372713, v96
	v_add_f32_e32 v91, 1.0, v91
	v_mul_f32_e32 v99, v96, v99
	v_fma_f32 v99, v96, v99, v96
	v_rcp_f32_e32 v110, v91
	v_mul_f32_e32 v99, 0xc0135761, v99
	v_exp_f32_e32 v99, v99
	s_nop 0
	v_add_f32_e32 v99, 1.0, v99
	v_rcp_f32_e32 v103, v99
	v_mul_f32_e32 v66, v66, v110
	v_mul_f32_e32 v98, v66, v93
	v_mul_f32_e32 v66, v96, v103
; __device__ __forceinline__ unsigned cvt_pk_bf16(float lo, float hi) { unsigned r; asm("v_cvt_pk_bf16_f32 %0, %1, %2" : "=v"(r) : "v"(lo), "v"(hi)); return r; }
; __device__ __forceinline__ float bflo(unsigned w) { return __uint_as_float(w << 16); }
; __device__ __forceinline__ float bfhi(unsigned w) { return __uint_as_float(w & 0xffff0000u); }
; __device__ __forceinline__ float gelu_tanh(float x) { const float u = 0.7978845608028654f * (x + 0.044715f * x * x * x); return x / (1.f + __expf(-2.f * u)); }
; __device__ __forceinline__ void phase_conv(PRef p, int layer, int nseg) {
;     ...
;             for (int xi = 0; xi < 4; ++xi) {
;                 float acc[8];
; #pragma unroll
;                 for (int j = 0; j < 8; ++j) acc[j] = bias[j];
; #pragma unroll
;                 for (int ky = 0; ky < 3; ++ky)
; #pragma unroll
;                     for (int kx = 0; kx < 3; ++kx) { const u32x4 gq = gc[ky][xi + kx]; const int k = ky * 3 + kx;
;                         acc[0] += w[k][0] * bflo(gq.x); acc[1] += w[k][1] * bfhi(gq.x); acc[2] += w[k][2] * bflo(gq.y); acc[3] += w[k][3] * bfhi(gq.y);
;                         acc[4] += w[k][4] * bflo(gq.z); acc[5] += w[k][5] * bfhi(gq.z); acc[6] += w[k][6] * bflo(gq.w); acc[7] += w[k][7] * bfhi(gq.w); }
;                 u32x4 o;
;                 o.x = cvt_pk_bf16(gelu_tanh(acc[0]) * bflo(vv[xi].x), gelu_tanh(acc[1]) * bfhi(vv[xi].x));
;                 o.y = cvt_pk_bf16(gelu_tanh(acc[2]) * bflo(vv[xi].y), gelu_tanh(acc[3]) * bfhi(vv[xi].y));
;                 o.z = cvt_pk_bf16(gelu_tanh(acc[4]) * bflo(vv[xi].z), gelu_tanh(acc[5]) * bfhi(vv[xi].z));
;                 o.w = cvt_pk_bf16(gelu_tanh(acc[6]) * bflo(vv[xi].w), gelu_tanh(acc[7]) * bfhi(vv[xi].w));
;                 *(u32x4*)((bf16_t*)lp[1] + (size_t)(xb + xi) * NUP + NFF) = o; } }
	v_pk_mul_f32 v[96:97], v[148:149], v[100:101]
	v_mul_f32_e32 v89, v66, v89
	v_fma_f32 v66, v148, v100, v90
	v_fma_f32 v96, v149, v101, v66
	v_and_b32_e32 v66, 0xffff0000, v59
	v_mov_b32_e32 v90, v66
	v_mov_b32_e32 v91, v94
	v_and_b32_e32 v87, 0xffff0000, v87
	v_and_b32_e32 v86, 0xffff0000, v83
	v_pk_mov_b32 v[82:83], v[94:95], v[86:87] op_sel:[1,0]
	v_fma_f32 v59, v6, v90, v195
	v_pk_mul_f32 v[106:107], v[2:3], v[82:83]
	v_fma_f32 v59, v7, v91, v59
	v_fma_f32 v59, v2, v82, v59
	v_mov_b32_e32 v93, v66
	v_fma_f32 v59, v3, v83, v59
	v_pk_mul_f32 v[90:91], v[14:15], v[92:93]
	v_mul_f32_e32 v92, 0x3d372713, v59
	v_mul_f32_e32 v92, v59, v92
	v_fma_f32 v92, v59, v92, v59
	v_and_b32_e32 v67, 0xffff0000, v67
	v_mul_f32_e32 v92, 0xc0135761, v92
	v_add_f32_e32 v90, v194, v90
	v_mov_b32_e32 v94, v67
	v_add_f32_e32 v93, v90, v91
	v_pk_mul_f32 v[90:91], v[6:7], v[94:95]
	v_exp_f32_e32 v92, v92
	v_fma_f32 v90, v6, v94, v93
	v_fma_f32 v90, v7, v95, v90
	v_fma_f32 v82, v2, v86, v90
	v_fma_f32 v82, v3, v87, v82
	v_add_f32_e32 v92, 1.0, v92
	v_mul_f32_e32 v83, 0x3d372713, v82
	v_mul_f32_e32 v83, v82, v83
	v_rcp_f32_e32 v99, v92
	v_fma_f32 v83, v82, v83, v82
	v_mul_f32_e32 v83, 0xc0135761, v83
	v_exp_f32_e32 v83, v83
	s_nop 0
	v_add_f32_e32 v83, 1.0, v83
	v_rcp_f32_e32 v94, v83
	v_mul_f32_e32 v59, v59, v99
	v_cvt_pk_bf16_f32 v57, v132, v57
	v_mul_f32_e32 v59, v59, v136
	v_mul_f32_e32 v65, v65, v243
	v_cvt_pk_bf16_f32 v58, v118, v58
	v_mul_f32_e32 v82, v82, v94
	v_cvt_pk_bf16_f32 v59, v98, v59
	global_store_dwordx4 v[180:181], v[56:59], off offset:3072
	v_pk_mov_b32 v[72:73], v[72:73], v[72:73] op_sel:[1,0]
	v_mul_f32_e32 v82, v82, v88
	v_cvt_pk_bf16_f32 v56, v70, v71
	v_cvt_pk_bf16_f32 v57, v133, v65
	v_cvt_pk_bf16_f32 v58, v119, v114
	v_cvt_pk_bf16_f32 v59, v89, v82
	global_store_dwordx4 v[178:179], v[56:59], off offset:3072
	v_fma_f32 v66, v14, v66, v68
	v_fma_f32 v88, v15, v67, v66
	v_lshlrev_b32_e32 v56, 16, v52
	v_mov_b32_e32 v57, v73
	v_lshlrev_b32_e32 v58, 16, v53
	v_and_b32_e32 v66, 0xffff0000, v53
	v_fma_f32 v53, v170, v56, v69
	v_fma_f32 v89, v171, v57, v53
	v_pk_mov_b32 v[56:57], v[74:75], v[74:75] op_sel:[1,0]
	v_and_b32_e32 v52, 0xffff0000, v52
	v_mov_b32_e32 v53, v57
	v_lshlrev_b32_e32 v68, 16, v54
	v_fma_f32 v52, v28, v52, v64
	v_fma_f32 v74, v29, v53, v52
	v_pk_mov_b32 v[52:53], v[76:77], v[76:77] op_sel:[1,0]
	v_and_b32_e32 v54, 0xffff0000, v54
	v_mov_b32_e32 v59, v53
	v_lshlrev_b32_e32 v70, 16, v55
	v_fma_f32 v53, v162, v58, v182
	v_fma_f32 v75, v163, v59, v53
	v_pk_mov_b32 v[58:59], v[78:79], v[78:79] op_sel:[1,0]
	v_and_b32_e32 v82, 0xffff0000, v55
	v_mov_b32_e32 v67, v59
	v_lshlrev_b32_e32 v73, 16, v60
	v_fma_f32 v53, v30, v66, v120
	v_fma_f32 v76, v31, v67, v53
	v_pk_mov_b32 v[64:65], v[80:81], v[80:81] op_sel:[1,0]
	v_and_b32_e32 v57, 0xffff0000, v60
	v_mov_b32_e32 v69, v65
	v_fma_f32 v53, v154, v68, v116
	v_fma_f32 v77, v155, v69, v53
	v_pk_mov_b32 v[66:67], v[84:85], v[84:85] op_sel:[1,0]
	v_and_b32_e32 v59, 0xffff0000, v61
	v_mov_b32_e32 v55, v67
	v_lshlrev_b32_e32 v65, 16, v62
	v_fma_f32 v53, v4, v54, v112
	v_fma_f32 v78, v5, v55, v53
	v_pk_mov_b32 v[54:55], v[104:105], v[104:105] op_sel:[1,0]
	v_and_b32_e32 v67, 0xffff0000, v62
	v_mov_b32_e32 v71, v55
	v_lshlrev_b32_e32 v55, 16, v63
	v_fma_f32 v53, v146, v70, v96
	v_fma_f32 v79, v147, v71, v53
	v_pk_mov_b32 v[68:69], v[86:87], v[86:87] op_sel:[1,0]
	s_xor_b64 s[44:45], s[44:45], -1
	v_mov_b32_e32 v83, v69
	v_and_b32_e32 v69, 0xffff0000, v63
	v_fma_f32 v53, v6, v82, v88
	v_fma_f32 v80, v7, v83, v53
	v_pk_mul_f32 v[70:71], v[168:169], v[72:73]
	s_nop 0
	v_fma_f32 v53, v168, v72, v89
	v_fma_f32 v70, v169, v73, v53
	v_fma_f32 v53, v24, v56, v74
	v_fma_f32 v56, v25, v57, v53
	v_lshlrev_b32_e32 v53, 16, v61
	s_nop 0
	v_fma_f32 v52, v160, v52, v75
	v_fma_f32 v57, v161, v53, v52
	s_nop 0
	v_fma_f32 v52, v26, v58, v76
	v_fma_f32 v58, v27, v59, v52
	s_nop 0
	v_fma_f32 v52, v152, v64, v77
	v_fma_f32 v59, v153, v65, v52
	s_nop 0
	v_fma_f32 v52, v0, v66, v78
	v_fma_f32 v60, v1, v67, v52
	v_pk_mul_f32 v[52:53], v[144:145], v[54:55]
	v_mul_f32_e32 v54, 0x3d372713, v70
	v_mul_f32_e32 v54, v70, v54
	v_fma_f32 v54, v70, v54, v70
	v_mul_f32_e32 v54, 0xc0135761, v54
	v_exp_f32_e32 v54, v54
	v_add_f32_e32 v52, v79, v52
	v_add_f32_e32 v55, v52, v53
	v_add_f32_e32 v54, 1.0, v54
	v_rcp_f32_e32 v62, v54
	v_fma_f32 v52, v2, v68, v80
	v_fma_f32 v52, v3, v69, v52
	v_mul_f32_e32 v64, 0x3d372713, v56
	v_mul_f32_e32 v64, v56, v64
	v_fma_f32 v64, v56, v64, v56
	v_mul_f32_e32 v64, 0xc0135761, v64
	v_exp_f32_e32 v64, v64
	v_mul_f32_e32 v53, v70, v62
	v_add_f32_e32 v61, 1.0, v64
	v_rcp_f32_e32 v63, v61
	s_waitcnt vmcnt(3)
	v_lshlrev_b32_e32 v54, 16, v48
	v_mul_f32_e32 v53, v53, v54
	v_and_b32_e32 v48, 0xffff0000, v48
	v_mul_f32_e32 v62, 0x3d372713, v57
	v_mul_f32_e32 v62, v57, v62
	v_fma_f32 v62, v57, v62, v57
	v_mul_f32_e32 v62, 0xc0135761, v62
	v_exp_f32_e32 v62, v62
	v_mul_f32_e32 v54, v56, v63
	v_mul_f32_e32 v48, v54, v48
	v_add_f32_e32 v56, 1.0, v62
	v_rcp_f32_e32 v62, v56
	v_cvt_pk_bf16_f32 v48, v53, v48
	s_nop 0
	v_mul_f32_e32 v63, 0x3d372713, v58
	v_mul_f32_e32 v63, v58, v63
	v_fma_f32 v63, v58, v63, v58
	v_mul_f32_e32 v63, 0xc0135761, v63
	v_exp_f32_e32 v63, v63
	v_mul_f32_e32 v53, v57, v62
	v_add_f32_e32 v54, 1.0, v63
	v_rcp_f32_e32 v62, v54
	v_lshlrev_b32_e32 v56, 16, v49
	v_mul_f32_e32 v53, v53, v56
	v_and_b32_e32 v49, 0xffff0000, v49
	v_mul_f32_e32 v61, 0x3d372713, v59
	v_mul_f32_e32 v61, v59, v61
	v_fma_f32 v61, v59, v61, v59
	v_mul_f32_e32 v61, 0xc0135761, v61
	v_exp_f32_e32 v61, v61
	v_mul_f32_e32 v54, v58, v62
	v_mul_f32_e32 v49, v54, v49
	v_add_f32_e32 v56, 1.0, v61
	v_rcp_f32_e32 v58, v56
	v_cvt_pk_bf16_f32 v49, v53, v49
	s_nop 0
	v_mul_f32_e32 v61, 0x3d372713, v60
	v_mul_f32_e32 v61, v60, v61
	v_fma_f32 v61, v60, v61, v60
	v_mul_f32_e32 v61, 0xc0135761, v61
	v_exp_f32_e32 v61, v61
	v_mul_f32_e32 v53, v59, v58
	v_add_f32_e32 v54, 1.0, v61
	v_rcp_f32_e32 v58, v54
	v_lshlrev_b32_e32 v56, 16, v50
	v_mul_f32_e32 v53, v53, v56
	v_and_b32_e32 v50, 0xffff0000, v50
	v_mul_f32_e32 v57, 0x3d372713, v55
	v_mul_f32_e32 v57, v55, v57
	v_fma_f32 v57, v55, v57, v55
	v_mul_f32_e32 v57, 0xc0135761, v57
	v_exp_f32_e32 v57, v57
	v_mul_f32_e32 v54, v60, v58
	v_mul_f32_e32 v50, v54, v50
	v_add_f32_e32 v56, 1.0, v57
	v_rcp_f32_e32 v58, v56
	v_cvt_pk_bf16_f32 v50, v53, v50
	s_nop 0
	v_mul_f32_e32 v59, 0x3d372713, v52
	v_mul_f32_e32 v59, v52, v59
	v_fma_f32 v59, v52, v59, v52
	v_mul_f32_e32 v59, 0xc0135761, v59
	v_exp_f32_e32 v59, v59
	v_mul_f32_e32 v53, v55, v58
	v_add_f32_e32 v54, 1.0, v59
	v_rcp_f32_e32 v58, v54
	v_lshlrev_b32_e32 v55, 16, v51
	v_mul_f32_e32 v53, v53, v55
	v_and_b32_e32 v51, 0xffff0000, v51
	v_mul_f32_e32 v52, v52, v58
	v_mul_f32_e32 v51, v52, v51
	s_mov_b32 s8, 4
	s_andn2_b64 vcc, exec, s[44:45]
	s_mov_b64 s[44:45], 0
	v_cvt_pk_bf16_f32 v51, v53, v51
	global_store_dwordx4 v[176:177], v[48:51], off offset:3072
	s_cbranch_vccz .LBB0_1040
